# attention fast path: decide of softmax block 1 starts one MFMA gap earlier, its first half spread over six PV0 gaps instead of five
# baseline (speedup 1.0000x reference)
.Latt_nr0_0:
	s_waitcnt lgkmcnt(3)
	v_mfma_f32_32x32x16_bf16 v[222:237], v[214:217], v[152:155], v[222:237]
	v_add_u32_e32 v214, s98, v200
	ds_read_b128 v[214:217], v214 offset:8192
	v_sub_f32_e32 v128, v128, v190
	v_exp_f32_e32 v128, v128
	v_sub_f32_e32 v129, v129, v190
	v_exp_f32_e32 v129, v129
	v_sub_f32_e32 v130, v130, v190
	s_waitcnt lgkmcnt(3)
	v_mfma_f32_32x32x16_bf16 v[222:237], v[238:241], v[156:159], v[222:237]
	v_add_u32_e32 v238, s98, v201
	ds_read_b128 v[238:241], v238 offset:8192
	v_add_f32_e32 v254, 0, v128
	v_exp_f32_e32 v130, v130
	v_sub_f32_e32 v131, v131, v190
	v_add_f32_e32 v254, v129, v254
	v_exp_f32_e32 v131, v131
	s_waitcnt lgkmcnt(3)
	v_mfma_f32_32x32x16_bf16 v[222:237], v[206:209], v[160:163], v[222:237]
	ds_read_b64_tr_b16 v[206:207], v205
	ds_read_b64_tr_b16 v[208:209], v205 offset:4096
	v_sub_f32_e32 v132, v132, v190
	v_add_f32_e32 v254, v130, v254
	v_exp_f32_e32 v132, v132
	v_sub_f32_e32 v133, v133, v190
	v_add_f32_e32 v254, v131, v254
	s_waitcnt lgkmcnt(4)
	v_mfma_f32_32x32x16_bf16 v[222:237], v[210:213], v[164:167], v[222:237]
	ds_read_b64_tr_b16 v[210:211], v218
	ds_read_b64_tr_b16 v[212:213], v218 offset:4096
	v_exp_f32_e32 v133, v133
	v_sub_f32_e32 v134, v134, v190
	v_add_f32_e32 v254, v132, v254
	v_exp_f32_e32 v134, v134
	s_waitcnt lgkmcnt(5)
	v_mfma_f32_32x32x16_bf16 v[222:237], v[214:217], v[168:171], v[222:237]
	ds_read_b64_tr_b16 v[214:215], v219
	ds_read_b64_tr_b16 v[216:217], v219 offset:4096
	v_sub_f32_e32 v135, v135, v190
	v_add_f32_e32 v254, v133, v254
	v_exp_f32_e32 v135, v135
	s_nop 0
	s_waitcnt lgkmcnt(6)
	v_mfma_f32_32x32x16_bf16 v[222:237], v[238:241], v[172:175], v[222:237]
	ds_read_b64_tr_b16 v[238:239], v221
	ds_read_b64_tr_b16 v[240:241], v221 offset:4096
	v_cvt_pk_bf16_f32 v242, v128, v129
	v_cvt_pk_bf16_f32 v243, v130, v131
	v_cvt_pk_bf16_f32 v244, v132, v133
	v_cvt_pk_bf16_f32 v245, v134, v135
	s_nop 1
	s_waitcnt lgkmcnt(6)
	v_mfma_f32_32x32x16_bf16 v[112:127], v[206:209], v[242:245], v[112:127]
	ds_read_b64_tr_b16 v[206:207], v205 offset:256
	ds_read_b64_tr_b16 v[208:209], v205 offset:4352
	v_sub_f32_e32 v136, v136, v190
	v_add_f32_e32 v254, v134, v254
	v_exp_f32_e32 v136, v136
	v_sub_f32_e32 v137, v137, v190
	v_add_f32_e32 v254, v135, v254
	s_waitcnt lgkmcnt(6)
	v_mfma_f32_32x32x16_bf16 v[96:111], v[210:213], v[242:245], v[96:111]
	ds_read_b64_tr_b16 v[210:211], v218 offset:256
	ds_read_b64_tr_b16 v[212:213], v218 offset:4352
	v_exp_f32_e32 v137, v137
	v_sub_f32_e32 v138, v138, v190
	v_add_f32_e32 v254, v136, v254
	v_exp_f32_e32 v138, v138
	v_sub_f32_e32 v139, v139, v190
	s_waitcnt lgkmcnt(6)
	v_mfma_f32_32x32x16_bf16 v[80:95], v[214:217], v[242:245], v[80:95]
	ds_read_b64_tr_b16 v[214:215], v219 offset:256
	ds_read_b64_tr_b16 v[216:217], v219 offset:4352
	v_add_f32_e32 v254, v137, v254
	v_exp_f32_e32 v139, v139
	v_sub_f32_e32 v140, v140, v190
	v_add_f32_e32 v254, v138, v254
	s_waitcnt lgkmcnt(6)
	v_mfma_f32_32x32x16_bf16 v[64:79], v[238:241], v[242:245], v[64:79]
	ds_read_b64_tr_b16 v[238:239], v221 offset:256
	ds_read_b64_tr_b16 v[240:241], v221 offset:4352
	v_exp_f32_e32 v140, v140
	v_sub_f32_e32 v141, v141, v190
	v_add_f32_e32 v254, v139, v254
	v_exp_f32_e32 v141, v141
	s_waitcnt lgkmcnt(6)
	v_mfma_f32_32x32x16_bf16 v[48:63], v[206:209], v[242:245], v[48:63]
	ds_read_b64_tr_b16 v[206:207], v205 offset:8192
	ds_read_b64_tr_b16 v[208:209], v205 offset:12288
	v_sub_f32_e32 v142, v142, v190
	v_add_f32_e32 v254, v140, v254
	v_exp_f32_e32 v142, v142
	v_sub_f32_e32 v143, v143, v190
	s_waitcnt lgkmcnt(6)
	v_mfma_f32_32x32x16_bf16 v[32:47], v[210:213], v[242:245], v[32:47]
	ds_read_b64_tr_b16 v[210:211], v218 offset:8192
	ds_read_b64_tr_b16 v[212:213], v218 offset:12288
	v_add_f32_e32 v254, v141, v254
	v_exp_f32_e32 v143, v143
	v_add_f32_e32 v254, v142, v254
	v_add_f32_e32 v254, v143, v254
	s_waitcnt lgkmcnt(6)
	v_mfma_f32_32x32x16_bf16 v[16:31], v[214:217], v[242:245], v[16:31]
	ds_read_b64_tr_b16 v[214:215], v219 offset:8192
	ds_read_b64_tr_b16 v[216:217], v219 offset:12288
	v_cvt_pk_bf16_f32 v250, v136, v137
	v_cvt_pk_bf16_f32 v251, v138, v139
	v_cvt_pk_bf16_f32 v252, v140, v141
	v_cvt_pk_bf16_f32 v253, v142, v143
	v_add_f32_e32 v202, v202, v254
	s_waitcnt lgkmcnt(6)
	v_mfma_f32_32x32x16_bf16 v[0:15], v[238:241], v[242:245], v[0:15]
	ds_read_b64_tr_b16 v[238:239], v221 offset:8192
	ds_read_b64_tr_b16 v[240:241], v221 offset:12288
	ds_read_b64_tr_b16 v[128:129], v205 offset:8448
	ds_read_b64_tr_b16 v[130:131], v205 offset:12544
	v_max3_f32 v246, v222, v223, v224
	v_max3_f32 v247, v225, v226, v227
	v_max3_f32 v246, v246, v228, v229
	v_max3_f32 v247, v247, v230, v231
	v_max3_f32 v246, v246, v232, v233
	s_waitcnt lgkmcnt(8)
	v_mfma_f32_32x32x16_bf16 v[112:127], v[206:209], v[250:253], v[112:127]
	ds_read_b64_tr_b16 v[206:207], v218 offset:8448
	ds_read_b64_tr_b16 v[208:209], v218 offset:12544
	v_max3_f32 v247, v247, v234, v235
	v_max3_f32 v246, v246, v236, v237
	v_max_f32_e32 v246, v246, v247
	v_mov_b32_e32 v247, v246
	v_add_f32_e32 v249, 0x41000000, v190
	s_waitcnt lgkmcnt(8)
	v_mfma_f32_32x32x16_bf16 v[96:111], v[210:213], v[250:253], v[96:111]
	ds_read_b64_tr_b16 v[210:211], v219 offset:8448
	ds_read_b64_tr_b16 v[212:213], v219 offset:12544
	s_nop 1
	v_permlane32_swap_b32_e32 v246, v247
	v_max_f32_e32 v246, v246, v247
	v_cmp_gt_f32_e32 vcc, v246, v249
	s_cbranch_vccnz .Latt_rs1_0
	s_waitcnt lgkmcnt(8)
	v_mfma_f32_32x32x16_bf16 v[80:95], v[214:217], v[250:253], v[80:95]
	ds_read_b64_tr_b16 v[214:215], v221 offset:8448
	ds_read_b64_tr_b16 v[216:217], v221 offset:12544
	v_sub_f32_e32 v222, v222, v190
	v_exp_f32_e32 v222, v222
	v_sub_f32_e32 v223, v223, v190
	v_exp_f32_e32 v223, v223
	v_sub_f32_e32 v224, v224, v190
	s_waitcnt lgkmcnt(8)
	v_mfma_f32_32x32x16_bf16 v[64:79], v[238:241], v[250:253], v[64:79]
	ds_read_b64_tr_b16 v[238:239], v205 offset:16384
	ds_read_b64_tr_b16 v[240:241], v205 offset:20480
	v_add_f32_e32 v254, 0, v222
	v_exp_f32_e32 v224, v224
	v_sub_f32_e32 v225, v225, v190
	v_add_f32_e32 v254, v223, v254
	v_exp_f32_e32 v225, v225
	s_waitcnt lgkmcnt(8)
	v_mfma_f32_32x32x16_bf16 v[48:63], v[128:131], v[250:253], v[48:63]
	ds_read_b64_tr_b16 v[128:129], v218 offset:16384
	ds_read_b64_tr_b16 v[130:131], v218 offset:20480
	v_sub_f32_e32 v226, v226, v190
	v_add_f32_e32 v254, v224, v254
	v_exp_f32_e32 v226, v226
	v_sub_f32_e32 v227, v227, v190
	v_add_f32_e32 v254, v225, v254
	s_waitcnt lgkmcnt(8)
	v_mfma_f32_32x32x16_bf16 v[32:47], v[206:209], v[250:253], v[32:47]
	ds_read_b64_tr_b16 v[206:207], v219 offset:16384
	ds_read_b64_tr_b16 v[208:209], v219 offset:20480
	v_exp_f32_e32 v227, v227
	v_sub_f32_e32 v228, v228, v190
	v_add_f32_e32 v254, v226, v254
	v_exp_f32_e32 v228, v228
	s_waitcnt lgkmcnt(8)
	v_mfma_f32_32x32x16_bf16 v[16:31], v[210:213], v[250:253], v[16:31]
	ds_read_b64_tr_b16 v[210:211], v221 offset:16384
	ds_read_b64_tr_b16 v[212:213], v221 offset:20480
	v_sub_f32_e32 v229, v229, v190
	v_add_f32_e32 v254, v227, v254
	v_exp_f32_e32 v229, v229
	s_nop 0
	s_waitcnt lgkmcnt(8)
	v_mfma_f32_32x32x16_bf16 v[0:15], v[214:217], v[250:253], v[0:15]
	ds_read_b64_tr_b16 v[214:215], v205 offset:16640
	ds_read_b64_tr_b16 v[216:217], v205 offset:20736
	v_cvt_pk_bf16_f32 v242, v222, v223
	v_cvt_pk_bf16_f32 v243, v224, v225
	v_cvt_pk_bf16_f32 v244, v226, v227
	v_cvt_pk_bf16_f32 v245, v228, v229
	s_nop 1
	s_waitcnt lgkmcnt(8)
	v_mfma_f32_32x32x16_bf16 v[112:127], v[238:241], v[242:245], v[112:127]
	ds_read_b64_tr_b16 v[238:239], v218 offset:16640
	ds_read_b64_tr_b16 v[240:241], v218 offset:20736
	v_sub_f32_e32 v230, v230, v190
	v_add_f32_e32 v254, v228, v254
	v_exp_f32_e32 v230, v230
	v_sub_f32_e32 v231, v231, v190
	v_add_f32_e32 v254, v229, v254
	s_waitcnt lgkmcnt(8)
	v_mfma_f32_32x32x16_bf16 v[96:111], v[128:131], v[242:245], v[96:111]
	ds_read_b64_tr_b16 v[128:129], v219 offset:16640
	ds_read_b64_tr_b16 v[130:131], v219 offset:20736
	v_exp_f32_e32 v231, v231
	v_sub_f32_e32 v232, v232, v190
	v_add_f32_e32 v254, v230, v254
	v_exp_f32_e32 v232, v232
	v_sub_f32_e32 v233, v233, v190
	s_cmp_lg_u64 s[18:19], 0
	s_cbranch_scc1 .Latt_nd0_0
	s_sub_i32 s100, s88, 1
	s_cmp_eq_u32 s88, 0
	s_cselect_b32 s100, 2, s100
	s_lshl_b32 s101, s100, 14
	s_add_i32 m0, s85, s101
	s_nop 0
	global_load_lds_dwordx4 v178, s[14:15]

.Latt_rs1_0:
	s_waitcnt lgkmcnt(8)
	v_mfma_f32_32x32x16_bf16 v[80:95], v[214:217], v[250:253], v[80:95]
	ds_read_b64_tr_b16 v[214:215], v221 offset:8448
	ds_read_b64_tr_b16 v[216:217], v221 offset:12544
	s_waitcnt lgkmcnt(8)
	v_mfma_f32_32x32x16_bf16 v[64:79], v[238:241], v[250:253], v[64:79]
	ds_read_b64_tr_b16 v[238:239], v205 offset:16384
	ds_read_b64_tr_b16 v[240:241], v205 offset:20480
	s_waitcnt lgkmcnt(8)
	v_mfma_f32_32x32x16_bf16 v[48:63], v[128:131], v[250:253], v[48:63]
	ds_read_b64_tr_b16 v[128:129], v218 offset:16384
	ds_read_b64_tr_b16 v[130:131], v218 offset:20480
	s_waitcnt lgkmcnt(8)
	v_mfma_f32_32x32x16_bf16 v[32:47], v[206:209], v[250:253], v[32:47]
	ds_read_b64_tr_b16 v[206:207], v219 offset:16384
	ds_read_b64_tr_b16 v[208:209], v219 offset:20480
	s_waitcnt lgkmcnt(8)
	v_mfma_f32_32x32x16_bf16 v[16:31], v[210:213], v[250:253], v[16:31]
	ds_read_b64_tr_b16 v[210:211], v221 offset:16384
	ds_read_b64_tr_b16 v[212:213], v221 offset:20480
	s_waitcnt lgkmcnt(8)
	v_mfma_f32_32x32x16_bf16 v[0:15], v[214:217], v[250:253], v[0:15]
	ds_read_b64_tr_b16 v[214:215], v205 offset:16640
	ds_read_b64_tr_b16 v[216:217], v205 offset:20736
	s_nop 11
	v_max_f32_e32 v246, v190, v246
	v_sub_f32_e32 v190, v190, v246
	v_exp_f32_e32 v190, v190
	s_nop 0
	v_pk_mul_f32 v[126:127], v[126:127], v[190:191] op_sel_hi:[1,0]
	v_pk_mul_f32 v[124:125], v[124:125], v[190:191] op_sel_hi:[1,0]
	v_pk_mul_f32 v[122:123], v[122:123], v[190:191] op_sel_hi:[1,0]
	v_pk_mul_f32 v[120:121], v[120:121], v[190:191] op_sel_hi:[1,0]
	v_pk_mul_f32 v[118:119], v[118:119], v[190:191] op_sel_hi:[1,0]
	v_pk_mul_f32 v[116:117], v[116:117], v[190:191] op_sel_hi:[1,0]
	v_pk_mul_f32 v[114:115], v[114:115], v[190:191] op_sel_hi:[1,0]
	v_pk_mul_f32 v[112:113], v[112:113], v[190:191] op_sel_hi:[1,0]
	v_pk_mul_f32 v[110:111], v[110:111], v[190:191] op_sel_hi:[1,0]
	v_pk_mul_f32 v[108:109], v[108:109], v[190:191] op_sel_hi:[1,0]
	v_pk_mul_f32 v[106:107], v[106:107], v[190:191] op_sel_hi:[1,0]
	v_pk_mul_f32 v[104:105], v[104:105], v[190:191] op_sel_hi:[1,0]
	v_pk_mul_f32 v[102:103], v[102:103], v[190:191] op_sel_hi:[1,0]
	v_pk_mul_f32 v[100:101], v[100:101], v[190:191] op_sel_hi:[1,0]
	v_pk_mul_f32 v[98:99], v[98:99], v[190:191] op_sel_hi:[1,0]
	v_pk_mul_f32 v[96:97], v[96:97], v[190:191] op_sel_hi:[1,0]
	v_pk_mul_f32 v[94:95], v[94:95], v[190:191] op_sel_hi:[1,0]
	v_pk_mul_f32 v[92:93], v[92:93], v[190:191] op_sel_hi:[1,0]
	v_pk_mul_f32 v[90:91], v[90:91], v[190:191] op_sel_hi:[1,0]
	v_pk_mul_f32 v[88:89], v[88:89], v[190:191] op_sel_hi:[1,0]
	v_pk_mul_f32 v[86:87], v[86:87], v[190:191] op_sel_hi:[1,0]
	v_pk_mul_f32 v[84:85], v[84:85], v[190:191] op_sel_hi:[1,0]
	v_pk_mul_f32 v[82:83], v[82:83], v[190:191] op_sel_hi:[1,0]
	v_pk_mul_f32 v[80:81], v[80:81], v[190:191] op_sel_hi:[1,0]
	v_pk_mul_f32 v[78:79], v[78:79], v[190:191] op_sel_hi:[1,0]
	v_pk_mul_f32 v[76:77], v[76:77], v[190:191] op_sel_hi:[1,0]
	v_pk_mul_f32 v[74:75], v[74:75], v[190:191] op_sel_hi:[1,0]
	v_pk_mul_f32 v[72:73], v[72:73], v[190:191] op_sel_hi:[1,0]
	v_pk_mul_f32 v[70:71], v[70:71], v[190:191] op_sel_hi:[1,0]
	v_pk_mul_f32 v[68:69], v[68:69], v[190:191] op_sel_hi:[1,0]
	v_pk_mul_f32 v[66:67], v[66:67], v[190:191] op_sel_hi:[1,0]
	v_pk_mul_f32 v[64:65], v[64:65], v[190:191] op_sel_hi:[1,0]
	v_pk_mul_f32 v[62:63], v[62:63], v[190:191] op_sel_hi:[1,0]
	v_pk_mul_f32 v[60:61], v[60:61], v[190:191] op_sel_hi:[1,0]
	v_pk_mul_f32 v[58:59], v[58:59], v[190:191] op_sel_hi:[1,0]
	v_pk_mul_f32 v[56:57], v[56:57], v[190:191] op_sel_hi:[1,0]
	v_pk_mul_f32 v[54:55], v[54:55], v[190:191] op_sel_hi:[1,0]
	v_pk_mul_f32 v[52:53], v[52:53], v[190:191] op_sel_hi:[1,0]
	v_pk_mul_f32 v[50:51], v[50:51], v[190:191] op_sel_hi:[1,0]
	v_pk_mul_f32 v[48:49], v[48:49], v[190:191] op_sel_hi:[1,0]
	v_pk_mul_f32 v[46:47], v[46:47], v[190:191] op_sel_hi:[1,0]
	v_pk_mul_f32 v[44:45], v[44:45], v[190:191] op_sel_hi:[1,0]
	v_pk_mul_f32 v[42:43], v[42:43], v[190:191] op_sel_hi:[1,0]
	v_pk_mul_f32 v[40:41], v[40:41], v[190:191] op_sel_hi:[1,0]
	v_pk_mul_f32 v[38:39], v[38:39], v[190:191] op_sel_hi:[1,0]
	v_pk_mul_f32 v[36:37], v[36:37], v[190:191] op_sel_hi:[1,0]
	v_pk_mul_f32 v[34:35], v[34:35], v[190:191] op_sel_hi:[1,0]
	v_pk_mul_f32 v[32:33], v[32:33], v[190:191] op_sel_hi:[1,0]
	v_pk_mul_f32 v[30:31], v[30:31], v[190:191] op_sel_hi:[1,0]
	v_pk_mul_f32 v[28:29], v[28:29], v[190:191] op_sel_hi:[1,0]
	v_pk_mul_f32 v[26:27], v[26:27], v[190:191] op_sel_hi:[1,0]
	v_pk_mul_f32 v[24:25], v[24:25], v[190:191] op_sel_hi:[1,0]
	v_pk_mul_f32 v[22:23], v[22:23], v[190:191] op_sel_hi:[1,0]
	v_pk_mul_f32 v[20:21], v[20:21], v[190:191] op_sel_hi:[1,0]
	v_pk_mul_f32 v[18:19], v[18:19], v[190:191] op_sel_hi:[1,0]
	v_pk_mul_f32 v[16:17], v[16:17], v[190:191] op_sel_hi:[1,0]
	v_pk_mul_f32 v[14:15], v[14:15], v[190:191] op_sel_hi:[1,0]
	v_pk_mul_f32 v[12:13], v[12:13], v[190:191] op_sel_hi:[1,0]
	v_pk_mul_f32 v[10:11], v[10:11], v[190:191] op_sel_hi:[1,0]
	v_pk_mul_f32 v[8:9], v[8:9], v[190:191] op_sel_hi:[1,0]
	v_pk_mul_f32 v[6:7], v[6:7], v[190:191] op_sel_hi:[1,0]
	v_pk_mul_f32 v[4:5], v[4:5], v[190:191] op_sel_hi:[1,0]
	v_pk_mul_f32 v[2:3], v[2:3], v[190:191] op_sel_hi:[1,0]
	v_pk_mul_f32 v[0:1], v[0:1], v[190:191] op_sel_hi:[1,0]
	v_mul_f32_e32 v202, v202, v190
	v_mov_b32_e32 v190, v246
	v_sub_f32_e32 v222, v222, v190
	v_exp_f32_e32 v222, v222
	v_sub_f32_e32 v223, v223, v190
	v_exp_f32_e32 v223, v223
	v_sub_f32_e32 v224, v224, v190
	v_add_f32_e32 v254, 0, v222
	v_exp_f32_e32 v224, v224
	v_sub_f32_e32 v225, v225, v190
	v_add_f32_e32 v254, v223, v254
	v_exp_f32_e32 v225, v225
	v_sub_f32_e32 v226, v226, v190
	v_add_f32_e32 v254, v224, v254
	v_exp_f32_e32 v226, v226
	v_sub_f32_e32 v227, v227, v190
	v_add_f32_e32 v254, v225, v254
	v_exp_f32_e32 v227, v227
	v_sub_f32_e32 v228, v228, v190
	v_add_f32_e32 v254, v226, v254
	v_exp_f32_e32 v228, v228
	v_sub_f32_e32 v229, v229, v190
	v_add_f32_e32 v254, v227, v254
	v_exp_f32_e32 v229, v229
	v_sub_f32_e32 v230, v230, v190
	v_add_f32_e32 v254, v228, v254
	v_exp_f32_e32 v230, v230
	v_sub_f32_e32 v231, v231, v190
	v_add_f32_e32 v254, v229, v254
	v_exp_f32_e32 v231, v231
	v_sub_f32_e32 v232, v232, v190
	v_add_f32_e32 v254, v230, v254
	v_exp_f32_e32 v232, v232
	v_sub_f32_e32 v233, v233, v190
	v_add_f32_e32 v254, v231, v254
	v_exp_f32_e32 v233, v233
	v_sub_f32_e32 v234, v234, v190
	v_add_f32_e32 v254, v232, v254
	v_exp_f32_e32 v234, v234
	v_sub_f32_e32 v235, v235, v190
	v_add_f32_e32 v254, v233, v254
	v_exp_f32_e32 v235, v235
	v_sub_f32_e32 v236, v236, v190
	v_add_f32_e32 v254, v234, v254
	v_exp_f32_e32 v236, v236
	v_sub_f32_e32 v237, v237, v190
	v_add_f32_e32 v254, v235, v254
	v_exp_f32_e32 v237, v237
	v_add_f32_e32 v254, v236, v254
	v_add_f32_e32 v254, v237, v254
	v_cvt_pk_bf16_f32 v242, v222, v223
	v_cvt_pk_bf16_f32 v243, v224, v225
	v_cvt_pk_bf16_f32 v244, v226, v227
	v_cvt_pk_bf16_f32 v245, v228, v229
	v_cvt_pk_bf16_f32 v250, v230, v231
	v_cvt_pk_bf16_f32 v251, v232, v233
	v_cvt_pk_bf16_f32 v252, v234, v235
	v_cvt_pk_bf16_f32 v253, v236, v237
	v_add_f32_e32 v202, v202, v254
	s_nop 1
	s_waitcnt lgkmcnt(8)
	v_mfma_f32_32x32x16_bf16 v[112:127], v[238:241], v[242:245], v[112:127]
	ds_read_b64_tr_b16 v[238:239], v218 offset:16640
	ds_read_b64_tr_b16 v[240:241], v218 offset:20736
	s_waitcnt lgkmcnt(8)
	v_mfma_f32_32x32x16_bf16 v[96:111], v[128:131], v[242:245], v[96:111]
	ds_read_b64_tr_b16 v[222:223], v219 offset:16640
	ds_read_b64_tr_b16 v[224:225], v219 offset:20736
	s_cmp_lg_u64 s[18:19], 0
	s_cbranch_scc1 .Latt_ndr0_0
	s_sub_i32 s100, s88, 1
	s_cmp_eq_u32 s88, 0
	s_cselect_b32 s100, 2, s100
	s_lshl_b32 s101, s100, 14
	s_add_i32 m0, s85, s101
	s_nop 0
	global_load_lds_dwordx4 v178, s[14:15]

.Latt_nr0_1:
	s_waitcnt lgkmcnt(3)
	v_mfma_f32_32x32x16_bf16 v[222:237], v[214:217], v[152:155], v[222:237]
	v_add_u32_e32 v214, s98, v202
	ds_read_b128 v[214:217], v214 offset:8192
	v_sub_f32_e32 v128, v128, v190
	v_exp_f32_e32 v128, v128
	v_sub_f32_e32 v129, v129, v190
	v_exp_f32_e32 v129, v129
	v_sub_f32_e32 v130, v130, v190
	s_waitcnt lgkmcnt(3)
	v_mfma_f32_32x32x16_bf16 v[222:237], v[238:241], v[156:159], v[222:237]
	v_add_u32_e32 v238, s98, v203
	ds_read_b128 v[238:241], v238 offset:8192
	v_add_f32_e32 v254, 0, v128
	v_exp_f32_e32 v130, v130
	v_sub_f32_e32 v131, v131, v190
	v_add_f32_e32 v254, v129, v254
	v_exp_f32_e32 v131, v131
	s_waitcnt lgkmcnt(3)
	v_mfma_f32_32x32x16_bf16 v[222:237], v[206:209], v[160:163], v[222:237]
	ds_read_b64_tr_b16 v[206:207], v205
	ds_read_b64_tr_b16 v[208:209], v205 offset:4096
	v_sub_f32_e32 v132, v132, v190
	v_add_f32_e32 v254, v130, v254
	v_exp_f32_e32 v132, v132
	v_sub_f32_e32 v133, v133, v190
	v_add_f32_e32 v254, v131, v254
	s_waitcnt lgkmcnt(4)
	v_mfma_f32_32x32x16_bf16 v[222:237], v[210:213], v[164:167], v[222:237]
	ds_read_b64_tr_b16 v[210:211], v218
	ds_read_b64_tr_b16 v[212:213], v218 offset:4096
	v_exp_f32_e32 v133, v133
	v_sub_f32_e32 v134, v134, v190
	v_add_f32_e32 v254, v132, v254
	v_exp_f32_e32 v134, v134
	s_waitcnt lgkmcnt(5)
	v_mfma_f32_32x32x16_bf16 v[222:237], v[214:217], v[168:171], v[222:237]
	ds_read_b64_tr_b16 v[214:215], v219
	ds_read_b64_tr_b16 v[216:217], v219 offset:4096
	v_sub_f32_e32 v135, v135, v190
	v_add_f32_e32 v254, v133, v254
	v_exp_f32_e32 v135, v135
	s_nop 0
	s_waitcnt lgkmcnt(6)
	v_mfma_f32_32x32x16_bf16 v[222:237], v[238:241], v[172:175], v[222:237]
	ds_read_b64_tr_b16 v[238:239], v221
	ds_read_b64_tr_b16 v[240:241], v221 offset:4096
	v_cvt_pk_bf16_f32 v242, v128, v129
	v_cvt_pk_bf16_f32 v243, v130, v131
	v_cvt_pk_bf16_f32 v244, v132, v133
	v_cvt_pk_bf16_f32 v245, v134, v135
	s_nop 1
	s_waitcnt lgkmcnt(6)
	v_mfma_f32_32x32x16_bf16 v[112:127], v[206:209], v[242:245], v[112:127]
	ds_read_b64_tr_b16 v[206:207], v205 offset:256
	ds_read_b64_tr_b16 v[208:209], v205 offset:4352
	v_sub_f32_e32 v136, v136, v190
	v_add_f32_e32 v254, v134, v254
	v_exp_f32_e32 v136, v136
	v_sub_f32_e32 v137, v137, v190
	v_add_f32_e32 v254, v135, v254
	s_waitcnt lgkmcnt(6)
	v_mfma_f32_32x32x16_bf16 v[96:111], v[210:213], v[242:245], v[96:111]
	ds_read_b64_tr_b16 v[210:211], v218 offset:256
	ds_read_b64_tr_b16 v[212:213], v218 offset:4352
	v_exp_f32_e32 v137, v137
	v_sub_f32_e32 v138, v138, v190
	v_add_f32_e32 v254, v136, v254
	v_exp_f32_e32 v138, v138
	v_sub_f32_e32 v139, v139, v190
	s_waitcnt lgkmcnt(6)
	v_mfma_f32_32x32x16_bf16 v[80:95], v[214:217], v[242:245], v[80:95]
	ds_read_b64_tr_b16 v[214:215], v219 offset:256
	ds_read_b64_tr_b16 v[216:217], v219 offset:4352
	v_add_f32_e32 v254, v137, v254
	v_exp_f32_e32 v139, v139
	v_sub_f32_e32 v140, v140, v190
	v_add_f32_e32 v254, v138, v254
	s_waitcnt lgkmcnt(6)
	v_mfma_f32_32x32x16_bf16 v[64:79], v[238:241], v[242:245], v[64:79]
	ds_read_b64_tr_b16 v[238:239], v221 offset:256
	ds_read_b64_tr_b16 v[240:241], v221 offset:4352
	v_exp_f32_e32 v140, v140
	v_sub_f32_e32 v141, v141, v190
	v_add_f32_e32 v254, v139, v254
	v_exp_f32_e32 v141, v141
	s_waitcnt lgkmcnt(6)
	v_mfma_f32_32x32x16_bf16 v[48:63], v[206:209], v[242:245], v[48:63]
	ds_read_b64_tr_b16 v[206:207], v205 offset:8192
	ds_read_b64_tr_b16 v[208:209], v205 offset:12288
	v_sub_f32_e32 v142, v142, v190
	v_add_f32_e32 v254, v140, v254
	v_exp_f32_e32 v142, v142
	v_sub_f32_e32 v143, v143, v190
	s_waitcnt lgkmcnt(6)
	v_mfma_f32_32x32x16_bf16 v[32:47], v[210:213], v[242:245], v[32:47]
	ds_read_b64_tr_b16 v[210:211], v218 offset:8192
	ds_read_b64_tr_b16 v[212:213], v218 offset:12288
	v_add_f32_e32 v254, v141, v254
	v_exp_f32_e32 v143, v143
	v_add_f32_e32 v254, v142, v254
	v_add_f32_e32 v254, v143, v254
	s_waitcnt lgkmcnt(6)
	v_mfma_f32_32x32x16_bf16 v[16:31], v[214:217], v[242:245], v[16:31]
	ds_read_b64_tr_b16 v[214:215], v219 offset:8192
	ds_read_b64_tr_b16 v[216:217], v219 offset:12288
	v_cvt_pk_bf16_f32 v250, v136, v137
	v_cvt_pk_bf16_f32 v251, v138, v139
	v_cvt_pk_bf16_f32 v252, v140, v141
	v_cvt_pk_bf16_f32 v253, v142, v143
	v_add_f32_e32 v195, v195, v254
	s_waitcnt lgkmcnt(6)
	v_mfma_f32_32x32x16_bf16 v[0:15], v[238:241], v[242:245], v[0:15]
	ds_read_b64_tr_b16 v[238:239], v221 offset:8192
	ds_read_b64_tr_b16 v[240:241], v221 offset:12288
	ds_read_b64_tr_b16 v[128:129], v205 offset:8448
	ds_read_b64_tr_b16 v[130:131], v205 offset:12544
	v_max3_f32 v246, v222, v223, v224
	v_max3_f32 v247, v225, v226, v227
	v_max3_f32 v246, v246, v228, v229
	v_max3_f32 v247, v247, v230, v231
	v_max3_f32 v246, v246, v232, v233
	s_waitcnt lgkmcnt(8)
	v_mfma_f32_32x32x16_bf16 v[112:127], v[206:209], v[250:253], v[112:127]
	ds_read_b64_tr_b16 v[206:207], v218 offset:8448
	ds_read_b64_tr_b16 v[208:209], v218 offset:12544
	v_max3_f32 v247, v247, v234, v235
	v_max3_f32 v246, v246, v236, v237
	v_max_f32_e32 v246, v246, v247
	v_mov_b32_e32 v247, v246
	v_add_f32_e32 v249, 0x41000000, v190
	s_waitcnt lgkmcnt(8)
	v_mfma_f32_32x32x16_bf16 v[96:111], v[210:213], v[250:253], v[96:111]
	ds_read_b64_tr_b16 v[210:211], v219 offset:8448
	ds_read_b64_tr_b16 v[212:213], v219 offset:12544
	s_nop 1
	v_permlane32_swap_b32_e32 v246, v247
	v_max_f32_e32 v246, v246, v247
	v_cmp_gt_f32_e32 vcc, v246, v249
	s_cbranch_vccnz .Latt_rs1_1
	s_waitcnt lgkmcnt(8)
	v_mfma_f32_32x32x16_bf16 v[80:95], v[214:217], v[250:253], v[80:95]
	ds_read_b64_tr_b16 v[214:215], v221 offset:8448
	ds_read_b64_tr_b16 v[216:217], v221 offset:12544
	v_sub_f32_e32 v222, v222, v190
	v_exp_f32_e32 v222, v222
	v_sub_f32_e32 v223, v223, v190
	v_exp_f32_e32 v223, v223
	v_sub_f32_e32 v224, v224, v190
	s_waitcnt lgkmcnt(8)
	v_mfma_f32_32x32x16_bf16 v[64:79], v[238:241], v[250:253], v[64:79]
	ds_read_b64_tr_b16 v[238:239], v205 offset:16384
	ds_read_b64_tr_b16 v[240:241], v205 offset:20480
	v_add_f32_e32 v254, 0, v222
	v_exp_f32_e32 v224, v224
	v_sub_f32_e32 v225, v225, v190
	v_add_f32_e32 v254, v223, v254
	v_exp_f32_e32 v225, v225
	s_waitcnt lgkmcnt(8)
	v_mfma_f32_32x32x16_bf16 v[48:63], v[128:131], v[250:253], v[48:63]
	ds_read_b64_tr_b16 v[128:129], v218 offset:16384
	ds_read_b64_tr_b16 v[130:131], v218 offset:20480
	v_sub_f32_e32 v226, v226, v190
	v_add_f32_e32 v254, v224, v254
	v_exp_f32_e32 v226, v226
	v_sub_f32_e32 v227, v227, v190
	v_add_f32_e32 v254, v225, v254
	s_waitcnt lgkmcnt(8)
	v_mfma_f32_32x32x16_bf16 v[32:47], v[206:209], v[250:253], v[32:47]
	ds_read_b64_tr_b16 v[206:207], v219 offset:16384
	ds_read_b64_tr_b16 v[208:209], v219 offset:20480
	v_exp_f32_e32 v227, v227
	v_sub_f32_e32 v228, v228, v190
	v_add_f32_e32 v254, v226, v254
	v_exp_f32_e32 v228, v228
	s_waitcnt lgkmcnt(8)
	v_mfma_f32_32x32x16_bf16 v[16:31], v[210:213], v[250:253], v[16:31]
	ds_read_b64_tr_b16 v[210:211], v221 offset:16384
	ds_read_b64_tr_b16 v[212:213], v221 offset:20480
	v_sub_f32_e32 v229, v229, v190
	v_add_f32_e32 v254, v227, v254
	v_exp_f32_e32 v229, v229
	s_nop 0
	s_waitcnt lgkmcnt(8)
	v_mfma_f32_32x32x16_bf16 v[0:15], v[214:217], v[250:253], v[0:15]
	ds_read_b64_tr_b16 v[214:215], v205 offset:16640
	ds_read_b64_tr_b16 v[216:217], v205 offset:20736
	v_cvt_pk_bf16_f32 v242, v222, v223
	v_cvt_pk_bf16_f32 v243, v224, v225
	v_cvt_pk_bf16_f32 v244, v226, v227
	v_cvt_pk_bf16_f32 v245, v228, v229
	s_nop 1
	s_waitcnt lgkmcnt(8)
	v_mfma_f32_32x32x16_bf16 v[112:127], v[238:241], v[242:245], v[112:127]
	ds_read_b64_tr_b16 v[238:239], v218 offset:16640
	ds_read_b64_tr_b16 v[240:241], v218 offset:20736
	v_sub_f32_e32 v230, v230, v190
	v_add_f32_e32 v254, v228, v254
	v_exp_f32_e32 v230, v230
	v_sub_f32_e32 v231, v231, v190
	v_add_f32_e32 v254, v229, v254
	s_waitcnt lgkmcnt(8)
	v_mfma_f32_32x32x16_bf16 v[96:111], v[128:131], v[242:245], v[96:111]
	ds_read_b64_tr_b16 v[128:129], v219 offset:16640
	ds_read_b64_tr_b16 v[130:131], v219 offset:20736
	v_exp_f32_e32 v231, v231
	v_sub_f32_e32 v232, v232, v190
	v_add_f32_e32 v254, v230, v254
	v_exp_f32_e32 v232, v232
	v_sub_f32_e32 v233, v233, v190
	s_cmp_lg_u64 s[18:19], 0
	s_cbranch_scc1 .Latt_nd0_1
	s_sub_i32 s100, s33, 1
	s_cmp_eq_u32 s33, 0
	s_cselect_b32 s100, 2, s100
	s_lshl_b32 s101, s100, 14
	s_add_i32 m0, s85, s101
	s_nop 0
	global_load_lds_dwordx4 v178, s[12:13]

.Latt_rs1_1:
	s_waitcnt lgkmcnt(8)
	v_mfma_f32_32x32x16_bf16 v[80:95], v[214:217], v[250:253], v[80:95]
	ds_read_b64_tr_b16 v[214:215], v221 offset:8448
	ds_read_b64_tr_b16 v[216:217], v221 offset:12544
	s_waitcnt lgkmcnt(8)
	v_mfma_f32_32x32x16_bf16 v[64:79], v[238:241], v[250:253], v[64:79]
	ds_read_b64_tr_b16 v[238:239], v205 offset:16384
	ds_read_b64_tr_b16 v[240:241], v205 offset:20480
	s_waitcnt lgkmcnt(8)
	v_mfma_f32_32x32x16_bf16 v[48:63], v[128:131], v[250:253], v[48:63]
	ds_read_b64_tr_b16 v[128:129], v218 offset:16384
	ds_read_b64_tr_b16 v[130:131], v218 offset:20480
	s_waitcnt lgkmcnt(8)
	v_mfma_f32_32x32x16_bf16 v[32:47], v[206:209], v[250:253], v[32:47]
	ds_read_b64_tr_b16 v[206:207], v219 offset:16384
	ds_read_b64_tr_b16 v[208:209], v219 offset:20480
	s_waitcnt lgkmcnt(8)
	v_mfma_f32_32x32x16_bf16 v[16:31], v[210:213], v[250:253], v[16:31]
	ds_read_b64_tr_b16 v[210:211], v221 offset:16384
	ds_read_b64_tr_b16 v[212:213], v221 offset:20480
	s_waitcnt lgkmcnt(8)
	v_mfma_f32_32x32x16_bf16 v[0:15], v[214:217], v[250:253], v[0:15]
	ds_read_b64_tr_b16 v[214:215], v205 offset:16640
	ds_read_b64_tr_b16 v[216:217], v205 offset:20736
	s_nop 11
	v_max_f32_e32 v246, v190, v246
	v_sub_f32_e32 v190, v190, v246
	v_exp_f32_e32 v190, v190
	s_nop 0
	v_pk_mul_f32 v[126:127], v[126:127], v[190:191] op_sel_hi:[1,0]
	v_pk_mul_f32 v[124:125], v[124:125], v[190:191] op_sel_hi:[1,0]
	v_pk_mul_f32 v[122:123], v[122:123], v[190:191] op_sel_hi:[1,0]
	v_pk_mul_f32 v[120:121], v[120:121], v[190:191] op_sel_hi:[1,0]
	v_pk_mul_f32 v[118:119], v[118:119], v[190:191] op_sel_hi:[1,0]
	v_pk_mul_f32 v[116:117], v[116:117], v[190:191] op_sel_hi:[1,0]
	v_pk_mul_f32 v[114:115], v[114:115], v[190:191] op_sel_hi:[1,0]
	v_pk_mul_f32 v[112:113], v[112:113], v[190:191] op_sel_hi:[1,0]
	v_pk_mul_f32 v[110:111], v[110:111], v[190:191] op_sel_hi:[1,0]
	v_pk_mul_f32 v[108:109], v[108:109], v[190:191] op_sel_hi:[1,0]
	v_pk_mul_f32 v[106:107], v[106:107], v[190:191] op_sel_hi:[1,0]
	v_pk_mul_f32 v[104:105], v[104:105], v[190:191] op_sel_hi:[1,0]
	v_pk_mul_f32 v[102:103], v[102:103], v[190:191] op_sel_hi:[1,0]
	v_pk_mul_f32 v[100:101], v[100:101], v[190:191] op_sel_hi:[1,0]
	v_pk_mul_f32 v[98:99], v[98:99], v[190:191] op_sel_hi:[1,0]
	v_pk_mul_f32 v[96:97], v[96:97], v[190:191] op_sel_hi:[1,0]
	v_pk_mul_f32 v[94:95], v[94:95], v[190:191] op_sel_hi:[1,0]
	v_pk_mul_f32 v[92:93], v[92:93], v[190:191] op_sel_hi:[1,0]
	v_pk_mul_f32 v[90:91], v[90:91], v[190:191] op_sel_hi:[1,0]
	v_pk_mul_f32 v[88:89], v[88:89], v[190:191] op_sel_hi:[1,0]
	v_pk_mul_f32 v[86:87], v[86:87], v[190:191] op_sel_hi:[1,0]
	v_pk_mul_f32 v[84:85], v[84:85], v[190:191] op_sel_hi:[1,0]
	v_pk_mul_f32 v[82:83], v[82:83], v[190:191] op_sel_hi:[1,0]
	v_pk_mul_f32 v[80:81], v[80:81], v[190:191] op_sel_hi:[1,0]
	v_pk_mul_f32 v[78:79], v[78:79], v[190:191] op_sel_hi:[1,0]
	v_pk_mul_f32 v[76:77], v[76:77], v[190:191] op_sel_hi:[1,0]
	v_pk_mul_f32 v[74:75], v[74:75], v[190:191] op_sel_hi:[1,0]
	v_pk_mul_f32 v[72:73], v[72:73], v[190:191] op_sel_hi:[1,0]
	v_pk_mul_f32 v[70:71], v[70:71], v[190:191] op_sel_hi:[1,0]
	v_pk_mul_f32 v[68:69], v[68:69], v[190:191] op_sel_hi:[1,0]
	v_pk_mul_f32 v[66:67], v[66:67], v[190:191] op_sel_hi:[1,0]
	v_pk_mul_f32 v[64:65], v[64:65], v[190:191] op_sel_hi:[1,0]
	v_pk_mul_f32 v[62:63], v[62:63], v[190:191] op_sel_hi:[1,0]
	v_pk_mul_f32 v[60:61], v[60:61], v[190:191] op_sel_hi:[1,0]
	v_pk_mul_f32 v[58:59], v[58:59], v[190:191] op_sel_hi:[1,0]
	v_pk_mul_f32 v[56:57], v[56:57], v[190:191] op_sel_hi:[1,0]
	v_pk_mul_f32 v[54:55], v[54:55], v[190:191] op_sel_hi:[1,0]
	v_pk_mul_f32 v[52:53], v[52:53], v[190:191] op_sel_hi:[1,0]
	v_pk_mul_f32 v[50:51], v[50:51], v[190:191] op_sel_hi:[1,0]
	v_pk_mul_f32 v[48:49], v[48:49], v[190:191] op_sel_hi:[1,0]
	v_pk_mul_f32 v[46:47], v[46:47], v[190:191] op_sel_hi:[1,0]
	v_pk_mul_f32 v[44:45], v[44:45], v[190:191] op_sel_hi:[1,0]
	v_pk_mul_f32 v[42:43], v[42:43], v[190:191] op_sel_hi:[1,0]
	v_pk_mul_f32 v[40:41], v[40:41], v[190:191] op_sel_hi:[1,0]
	v_pk_mul_f32 v[38:39], v[38:39], v[190:191] op_sel_hi:[1,0]
	v_pk_mul_f32 v[36:37], v[36:37], v[190:191] op_sel_hi:[1,0]
	v_pk_mul_f32 v[34:35], v[34:35], v[190:191] op_sel_hi:[1,0]
	v_pk_mul_f32 v[32:33], v[32:33], v[190:191] op_sel_hi:[1,0]
	v_pk_mul_f32 v[30:31], v[30:31], v[190:191] op_sel_hi:[1,0]
	v_pk_mul_f32 v[28:29], v[28:29], v[190:191] op_sel_hi:[1,0]
	v_pk_mul_f32 v[26:27], v[26:27], v[190:191] op_sel_hi:[1,0]
	v_pk_mul_f32 v[24:25], v[24:25], v[190:191] op_sel_hi:[1,0]
	v_pk_mul_f32 v[22:23], v[22:23], v[190:191] op_sel_hi:[1,0]
	v_pk_mul_f32 v[20:21], v[20:21], v[190:191] op_sel_hi:[1,0]
	v_pk_mul_f32 v[18:19], v[18:19], v[190:191] op_sel_hi:[1,0]
	v_pk_mul_f32 v[16:17], v[16:17], v[190:191] op_sel_hi:[1,0]
	v_pk_mul_f32 v[14:15], v[14:15], v[190:191] op_sel_hi:[1,0]
	v_pk_mul_f32 v[12:13], v[12:13], v[190:191] op_sel_hi:[1,0]
	v_pk_mul_f32 v[10:11], v[10:11], v[190:191] op_sel_hi:[1,0]
	v_pk_mul_f32 v[8:9], v[8:9], v[190:191] op_sel_hi:[1,0]
	v_pk_mul_f32 v[6:7], v[6:7], v[190:191] op_sel_hi:[1,0]
	v_pk_mul_f32 v[4:5], v[4:5], v[190:191] op_sel_hi:[1,0]
	v_pk_mul_f32 v[2:3], v[2:3], v[190:191] op_sel_hi:[1,0]
	v_pk_mul_f32 v[0:1], v[0:1], v[190:191] op_sel_hi:[1,0]
	v_mul_f32_e32 v195, v195, v190
	v_mov_b32_e32 v190, v246
	v_sub_f32_e32 v222, v222, v190
	v_exp_f32_e32 v222, v222
	v_sub_f32_e32 v223, v223, v190
	v_exp_f32_e32 v223, v223
	v_sub_f32_e32 v224, v224, v190
	v_add_f32_e32 v254, 0, v222
	v_exp_f32_e32 v224, v224
	v_sub_f32_e32 v225, v225, v190
	v_add_f32_e32 v254, v223, v254
	v_exp_f32_e32 v225, v225
	v_sub_f32_e32 v226, v226, v190
	v_add_f32_e32 v254, v224, v254
	v_exp_f32_e32 v226, v226
	v_sub_f32_e32 v227, v227, v190
	v_add_f32_e32 v254, v225, v254
	v_exp_f32_e32 v227, v227
	v_sub_f32_e32 v228, v228, v190
	v_add_f32_e32 v254, v226, v254
	v_exp_f32_e32 v228, v228
	v_sub_f32_e32 v229, v229, v190
	v_add_f32_e32 v254, v227, v254
	v_exp_f32_e32 v229, v229
	v_sub_f32_e32 v230, v230, v190
	v_add_f32_e32 v254, v228, v254
	v_exp_f32_e32 v230, v230
	v_sub_f32_e32 v231, v231, v190
	v_add_f32_e32 v254, v229, v254
	v_exp_f32_e32 v231, v231
	v_sub_f32_e32 v232, v232, v190
	v_add_f32_e32 v254, v230, v254
	v_exp_f32_e32 v232, v232
	v_sub_f32_e32 v233, v233, v190
	v_add_f32_e32 v254, v231, v254
	v_exp_f32_e32 v233, v233
	v_sub_f32_e32 v234, v234, v190
	v_add_f32_e32 v254, v232, v254
	v_exp_f32_e32 v234, v234
	v_sub_f32_e32 v235, v235, v190
	v_add_f32_e32 v254, v233, v254
	v_exp_f32_e32 v235, v235
	v_sub_f32_e32 v236, v236, v190
	v_add_f32_e32 v254, v234, v254
	v_exp_f32_e32 v236, v236
	v_sub_f32_e32 v237, v237, v190
	v_add_f32_e32 v254, v235, v254
	v_exp_f32_e32 v237, v237
	v_add_f32_e32 v254, v236, v254
	v_add_f32_e32 v254, v237, v254
	v_cvt_pk_bf16_f32 v242, v222, v223
	v_cvt_pk_bf16_f32 v243, v224, v225
	v_cvt_pk_bf16_f32 v244, v226, v227
	v_cvt_pk_bf16_f32 v245, v228, v229
	v_cvt_pk_bf16_f32 v250, v230, v231
	v_cvt_pk_bf16_f32 v251, v232, v233
	v_cvt_pk_bf16_f32 v252, v234, v235
	v_cvt_pk_bf16_f32 v253, v236, v237
	v_add_f32_e32 v195, v195, v254
	s_nop 1
	s_waitcnt lgkmcnt(8)
	v_mfma_f32_32x32x16_bf16 v[112:127], v[238:241], v[242:245], v[112:127]
	ds_read_b64_tr_b16 v[238:239], v218 offset:16640
	ds_read_b64_tr_b16 v[240:241], v218 offset:20736
	s_waitcnt lgkmcnt(8)
	v_mfma_f32_32x32x16_bf16 v[96:111], v[128:131], v[242:245], v[96:111]
	ds_read_b64_tr_b16 v[222:223], v219 offset:16640
	ds_read_b64_tr_b16 v[224:225], v219 offset:20736
	s_cmp_lg_u64 s[18:19], 0
	s_cbranch_scc1 .Latt_ndr0_1
	s_sub_i32 s100, s33, 1
	s_cmp_eq_u32 s33, 0
	s_cselect_b32 s100, 2, s100
	s_lshl_b32 s101, s100, 14
	s_add_i32 m0, s85, s101
	s_nop 0
	global_load_lds_dwordx4 v178, s[12:13]

.Latt_nr0_2:
	s_waitcnt lgkmcnt(3)
	v_mfma_f32_32x32x16_bf16 v[222:237], v[214:217], v[152:155], v[222:237]
	v_add_u32_e32 v214, s98, v201
	ds_read_b128 v[214:217], v214 offset:8192
	v_sub_f32_e32 v128, v128, v190
	v_exp_f32_e32 v128, v128
	v_sub_f32_e32 v129, v129, v190
	v_exp_f32_e32 v129, v129
	v_sub_f32_e32 v130, v130, v190
	s_waitcnt lgkmcnt(3)
	v_mfma_f32_32x32x16_bf16 v[222:237], v[238:241], v[156:159], v[222:237]
	v_add_u32_e32 v238, s98, v202
	ds_read_b128 v[238:241], v238 offset:8192
	v_add_f32_e32 v254, 0, v128
	v_exp_f32_e32 v130, v130
	v_sub_f32_e32 v131, v131, v190
	v_add_f32_e32 v254, v129, v254
	v_exp_f32_e32 v131, v131
	s_waitcnt lgkmcnt(3)
	v_mfma_f32_32x32x16_bf16 v[222:237], v[206:209], v[160:163], v[222:237]
	ds_read_b64_tr_b16 v[206:207], v205
	ds_read_b64_tr_b16 v[208:209], v205 offset:4096
	v_sub_f32_e32 v132, v132, v190
	v_add_f32_e32 v254, v130, v254
	v_exp_f32_e32 v132, v132
	v_sub_f32_e32 v133, v133, v190
	v_add_f32_e32 v254, v131, v254
	s_waitcnt lgkmcnt(4)
	v_mfma_f32_32x32x16_bf16 v[222:237], v[210:213], v[164:167], v[222:237]
	ds_read_b64_tr_b16 v[210:211], v218
	ds_read_b64_tr_b16 v[212:213], v218 offset:4096
	v_exp_f32_e32 v133, v133
	v_sub_f32_e32 v134, v134, v190
	v_add_f32_e32 v254, v132, v254
	v_exp_f32_e32 v134, v134
	s_waitcnt lgkmcnt(5)
	v_mfma_f32_32x32x16_bf16 v[222:237], v[214:217], v[168:171], v[222:237]
	ds_read_b64_tr_b16 v[214:215], v219
	ds_read_b64_tr_b16 v[216:217], v219 offset:4096
	v_sub_f32_e32 v135, v135, v190
	v_add_f32_e32 v254, v133, v254
	v_exp_f32_e32 v135, v135
	s_nop 0
	s_waitcnt lgkmcnt(6)
	v_mfma_f32_32x32x16_bf16 v[222:237], v[238:241], v[172:175], v[222:237]
	ds_read_b64_tr_b16 v[238:239], v221
	ds_read_b64_tr_b16 v[240:241], v221 offset:4096
	v_cvt_pk_bf16_f32 v242, v128, v129
	v_cvt_pk_bf16_f32 v243, v130, v131
	v_cvt_pk_bf16_f32 v244, v132, v133
	v_cvt_pk_bf16_f32 v245, v134, v135
	s_nop 1
	s_waitcnt lgkmcnt(6)
	v_mfma_f32_32x32x16_bf16 v[112:127], v[206:209], v[242:245], v[112:127]
	ds_read_b64_tr_b16 v[206:207], v205 offset:256
	ds_read_b64_tr_b16 v[208:209], v205 offset:4352
	v_sub_f32_e32 v136, v136, v190
	v_add_f32_e32 v254, v134, v254
	v_exp_f32_e32 v136, v136
	v_sub_f32_e32 v137, v137, v190
	v_add_f32_e32 v254, v135, v254
	s_waitcnt lgkmcnt(6)
	v_mfma_f32_32x32x16_bf16 v[96:111], v[210:213], v[242:245], v[96:111]
	ds_read_b64_tr_b16 v[210:211], v218 offset:256
	ds_read_b64_tr_b16 v[212:213], v218 offset:4352
	v_exp_f32_e32 v137, v137
	v_sub_f32_e32 v138, v138, v190
	v_add_f32_e32 v254, v136, v254
	v_exp_f32_e32 v138, v138
	v_sub_f32_e32 v139, v139, v190
	s_waitcnt lgkmcnt(6)
	v_mfma_f32_32x32x16_bf16 v[80:95], v[214:217], v[242:245], v[80:95]
	ds_read_b64_tr_b16 v[214:215], v219 offset:256
	ds_read_b64_tr_b16 v[216:217], v219 offset:4352
	v_add_f32_e32 v254, v137, v254
	v_exp_f32_e32 v139, v139
	v_sub_f32_e32 v140, v140, v190
	v_add_f32_e32 v254, v138, v254
	s_waitcnt lgkmcnt(6)
	v_mfma_f32_32x32x16_bf16 v[64:79], v[238:241], v[242:245], v[64:79]
	ds_read_b64_tr_b16 v[238:239], v221 offset:256
	ds_read_b64_tr_b16 v[240:241], v221 offset:4352
	v_exp_f32_e32 v140, v140
	v_sub_f32_e32 v141, v141, v190
	v_add_f32_e32 v254, v139, v254
	v_exp_f32_e32 v141, v141
	s_waitcnt lgkmcnt(6)
	v_mfma_f32_32x32x16_bf16 v[48:63], v[206:209], v[242:245], v[48:63]
	ds_read_b64_tr_b16 v[206:207], v205 offset:8192
	ds_read_b64_tr_b16 v[208:209], v205 offset:12288
	v_sub_f32_e32 v142, v142, v190
	v_add_f32_e32 v254, v140, v254
	v_exp_f32_e32 v142, v142
	v_sub_f32_e32 v143, v143, v190
	s_waitcnt lgkmcnt(6)
	v_mfma_f32_32x32x16_bf16 v[32:47], v[210:213], v[242:245], v[32:47]
	ds_read_b64_tr_b16 v[210:211], v218 offset:8192
	ds_read_b64_tr_b16 v[212:213], v218 offset:12288
	v_add_f32_e32 v254, v141, v254
	v_exp_f32_e32 v143, v143
	v_add_f32_e32 v254, v142, v254
	v_add_f32_e32 v254, v143, v254
	s_waitcnt lgkmcnt(6)
	v_mfma_f32_32x32x16_bf16 v[16:31], v[214:217], v[242:245], v[16:31]
	ds_read_b64_tr_b16 v[214:215], v219 offset:8192
	ds_read_b64_tr_b16 v[216:217], v219 offset:12288
	v_cvt_pk_bf16_f32 v250, v136, v137
	v_cvt_pk_bf16_f32 v251, v138, v139
	v_cvt_pk_bf16_f32 v252, v140, v141
	v_cvt_pk_bf16_f32 v253, v142, v143
	v_add_f32_e32 v203, v203, v254
	s_waitcnt lgkmcnt(6)
	v_mfma_f32_32x32x16_bf16 v[0:15], v[238:241], v[242:245], v[0:15]
	ds_read_b64_tr_b16 v[238:239], v221 offset:8192
	ds_read_b64_tr_b16 v[240:241], v221 offset:12288
	ds_read_b64_tr_b16 v[128:129], v205 offset:8448
	ds_read_b64_tr_b16 v[130:131], v205 offset:12544
	v_max3_f32 v246, v222, v223, v224
	v_max3_f32 v247, v225, v226, v227
	v_max3_f32 v246, v246, v228, v229
	v_max3_f32 v247, v247, v230, v231
	v_max3_f32 v246, v246, v232, v233
	s_waitcnt lgkmcnt(8)
	v_mfma_f32_32x32x16_bf16 v[112:127], v[206:209], v[250:253], v[112:127]
	ds_read_b64_tr_b16 v[206:207], v218 offset:8448
	ds_read_b64_tr_b16 v[208:209], v218 offset:12544
	v_max3_f32 v247, v247, v234, v235
	v_max3_f32 v246, v246, v236, v237
	v_max_f32_e32 v246, v246, v247
	v_mov_b32_e32 v247, v246
	v_add_f32_e32 v249, 0x41000000, v190
	s_waitcnt lgkmcnt(8)
	v_mfma_f32_32x32x16_bf16 v[96:111], v[210:213], v[250:253], v[96:111]
	ds_read_b64_tr_b16 v[210:211], v219 offset:8448
	ds_read_b64_tr_b16 v[212:213], v219 offset:12544
	s_nop 1
	v_permlane32_swap_b32_e32 v246, v247
	v_max_f32_e32 v246, v246, v247
	v_cmp_gt_f32_e32 vcc, v246, v249
	s_cbranch_vccnz .Latt_rs1_2
	s_waitcnt lgkmcnt(8)
	v_mfma_f32_32x32x16_bf16 v[80:95], v[214:217], v[250:253], v[80:95]
	ds_read_b64_tr_b16 v[214:215], v221 offset:8448
	ds_read_b64_tr_b16 v[216:217], v221 offset:12544
	v_sub_f32_e32 v222, v222, v190
	v_exp_f32_e32 v222, v222
	v_sub_f32_e32 v223, v223, v190
	v_exp_f32_e32 v223, v223
	v_sub_f32_e32 v224, v224, v190
	s_waitcnt lgkmcnt(8)
	v_mfma_f32_32x32x16_bf16 v[64:79], v[238:241], v[250:253], v[64:79]
	ds_read_b64_tr_b16 v[238:239], v205 offset:16384
	ds_read_b64_tr_b16 v[240:241], v205 offset:20480
	v_add_f32_e32 v254, 0, v222
	v_exp_f32_e32 v224, v224
	v_sub_f32_e32 v225, v225, v190
	v_add_f32_e32 v254, v223, v254
	v_exp_f32_e32 v225, v225
	s_waitcnt lgkmcnt(8)
	v_mfma_f32_32x32x16_bf16 v[48:63], v[128:131], v[250:253], v[48:63]
	ds_read_b64_tr_b16 v[128:129], v218 offset:16384
	ds_read_b64_tr_b16 v[130:131], v218 offset:20480
	v_sub_f32_e32 v226, v226, v190
	v_add_f32_e32 v254, v224, v254
	v_exp_f32_e32 v226, v226
	v_sub_f32_e32 v227, v227, v190
	v_add_f32_e32 v254, v225, v254
	s_waitcnt lgkmcnt(8)
	v_mfma_f32_32x32x16_bf16 v[32:47], v[206:209], v[250:253], v[32:47]
	ds_read_b64_tr_b16 v[206:207], v219 offset:16384
	ds_read_b64_tr_b16 v[208:209], v219 offset:20480
	v_exp_f32_e32 v227, v227
	v_sub_f32_e32 v228, v228, v190
	v_add_f32_e32 v254, v226, v254
	v_exp_f32_e32 v228, v228
	s_waitcnt lgkmcnt(8)
	v_mfma_f32_32x32x16_bf16 v[16:31], v[210:213], v[250:253], v[16:31]
	ds_read_b64_tr_b16 v[210:211], v221 offset:16384
	ds_read_b64_tr_b16 v[212:213], v221 offset:20480
	v_sub_f32_e32 v229, v229, v190
	v_add_f32_e32 v254, v227, v254
	v_exp_f32_e32 v229, v229
	s_nop 0
	s_waitcnt lgkmcnt(8)
	v_mfma_f32_32x32x16_bf16 v[0:15], v[214:217], v[250:253], v[0:15]
	ds_read_b64_tr_b16 v[214:215], v205 offset:16640
	ds_read_b64_tr_b16 v[216:217], v205 offset:20736
	v_cvt_pk_bf16_f32 v242, v222, v223
	v_cvt_pk_bf16_f32 v243, v224, v225
	v_cvt_pk_bf16_f32 v244, v226, v227
	v_cvt_pk_bf16_f32 v245, v228, v229
	s_nop 1
	s_waitcnt lgkmcnt(8)
	v_mfma_f32_32x32x16_bf16 v[112:127], v[238:241], v[242:245], v[112:127]
	ds_read_b64_tr_b16 v[238:239], v218 offset:16640
	ds_read_b64_tr_b16 v[240:241], v218 offset:20736
	v_sub_f32_e32 v230, v230, v190
	v_add_f32_e32 v254, v228, v254
	v_exp_f32_e32 v230, v230
	v_sub_f32_e32 v231, v231, v190
	v_add_f32_e32 v254, v229, v254
	s_waitcnt lgkmcnt(8)
	v_mfma_f32_32x32x16_bf16 v[96:111], v[128:131], v[242:245], v[96:111]
	ds_read_b64_tr_b16 v[128:129], v219 offset:16640
	ds_read_b64_tr_b16 v[130:131], v219 offset:20736
	v_exp_f32_e32 v231, v231
	v_sub_f32_e32 v232, v232, v190
	v_add_f32_e32 v254, v230, v254
	v_exp_f32_e32 v232, v232
	v_sub_f32_e32 v233, v233, v190
	s_cmp_lg_u64 s[12:13], 0
	s_cbranch_scc1 .Latt_nd0_2
	s_sub_i32 s100, s38, 1
	s_cmp_eq_u32 s38, 0
	s_cselect_b32 s100, 2, s100
	s_lshl_b32 s101, s100, 14
	s_add_i32 m0, s40, s101
	s_nop 0
	global_load_lds_dwordx4 v178, s[22:23]

.Latt_rs1_2:
	s_waitcnt lgkmcnt(8)
	v_mfma_f32_32x32x16_bf16 v[80:95], v[214:217], v[250:253], v[80:95]
	ds_read_b64_tr_b16 v[214:215], v221 offset:8448
	ds_read_b64_tr_b16 v[216:217], v221 offset:12544
	s_waitcnt lgkmcnt(8)
	v_mfma_f32_32x32x16_bf16 v[64:79], v[238:241], v[250:253], v[64:79]
	ds_read_b64_tr_b16 v[238:239], v205 offset:16384
	ds_read_b64_tr_b16 v[240:241], v205 offset:20480
	s_waitcnt lgkmcnt(8)
	v_mfma_f32_32x32x16_bf16 v[48:63], v[128:131], v[250:253], v[48:63]
	ds_read_b64_tr_b16 v[128:129], v218 offset:16384
	ds_read_b64_tr_b16 v[130:131], v218 offset:20480
	s_waitcnt lgkmcnt(8)
	v_mfma_f32_32x32x16_bf16 v[32:47], v[206:209], v[250:253], v[32:47]
	ds_read_b64_tr_b16 v[206:207], v219 offset:16384
	ds_read_b64_tr_b16 v[208:209], v219 offset:20480
	s_waitcnt lgkmcnt(8)
	v_mfma_f32_32x32x16_bf16 v[16:31], v[210:213], v[250:253], v[16:31]
	ds_read_b64_tr_b16 v[210:211], v221 offset:16384
	ds_read_b64_tr_b16 v[212:213], v221 offset:20480
	s_waitcnt lgkmcnt(8)
	v_mfma_f32_32x32x16_bf16 v[0:15], v[214:217], v[250:253], v[0:15]
	ds_read_b64_tr_b16 v[214:215], v205 offset:16640
	ds_read_b64_tr_b16 v[216:217], v205 offset:20736
	s_nop 11
	v_max_f32_e32 v246, v190, v246
	v_sub_f32_e32 v190, v190, v246
	v_exp_f32_e32 v190, v190
	s_nop 0
	v_pk_mul_f32 v[126:127], v[126:127], v[190:191] op_sel_hi:[1,0]
	v_pk_mul_f32 v[124:125], v[124:125], v[190:191] op_sel_hi:[1,0]
	v_pk_mul_f32 v[122:123], v[122:123], v[190:191] op_sel_hi:[1,0]
	v_pk_mul_f32 v[120:121], v[120:121], v[190:191] op_sel_hi:[1,0]
	v_pk_mul_f32 v[118:119], v[118:119], v[190:191] op_sel_hi:[1,0]
	v_pk_mul_f32 v[116:117], v[116:117], v[190:191] op_sel_hi:[1,0]
	v_pk_mul_f32 v[114:115], v[114:115], v[190:191] op_sel_hi:[1,0]
	v_pk_mul_f32 v[112:113], v[112:113], v[190:191] op_sel_hi:[1,0]
	v_pk_mul_f32 v[110:111], v[110:111], v[190:191] op_sel_hi:[1,0]
	v_pk_mul_f32 v[108:109], v[108:109], v[190:191] op_sel_hi:[1,0]
	v_pk_mul_f32 v[106:107], v[106:107], v[190:191] op_sel_hi:[1,0]
	v_pk_mul_f32 v[104:105], v[104:105], v[190:191] op_sel_hi:[1,0]
	v_pk_mul_f32 v[102:103], v[102:103], v[190:191] op_sel_hi:[1,0]
	v_pk_mul_f32 v[100:101], v[100:101], v[190:191] op_sel_hi:[1,0]
	v_pk_mul_f32 v[98:99], v[98:99], v[190:191] op_sel_hi:[1,0]
	v_pk_mul_f32 v[96:97], v[96:97], v[190:191] op_sel_hi:[1,0]
	v_pk_mul_f32 v[94:95], v[94:95], v[190:191] op_sel_hi:[1,0]
	v_pk_mul_f32 v[92:93], v[92:93], v[190:191] op_sel_hi:[1,0]
	v_pk_mul_f32 v[90:91], v[90:91], v[190:191] op_sel_hi:[1,0]
	v_pk_mul_f32 v[88:89], v[88:89], v[190:191] op_sel_hi:[1,0]
	v_pk_mul_f32 v[86:87], v[86:87], v[190:191] op_sel_hi:[1,0]
	v_pk_mul_f32 v[84:85], v[84:85], v[190:191] op_sel_hi:[1,0]
	v_pk_mul_f32 v[82:83], v[82:83], v[190:191] op_sel_hi:[1,0]
	v_pk_mul_f32 v[80:81], v[80:81], v[190:191] op_sel_hi:[1,0]
	v_pk_mul_f32 v[78:79], v[78:79], v[190:191] op_sel_hi:[1,0]
	v_pk_mul_f32 v[76:77], v[76:77], v[190:191] op_sel_hi:[1,0]
	v_pk_mul_f32 v[74:75], v[74:75], v[190:191] op_sel_hi:[1,0]
	v_pk_mul_f32 v[72:73], v[72:73], v[190:191] op_sel_hi:[1,0]
	v_pk_mul_f32 v[70:71], v[70:71], v[190:191] op_sel_hi:[1,0]
	v_pk_mul_f32 v[68:69], v[68:69], v[190:191] op_sel_hi:[1,0]
	v_pk_mul_f32 v[66:67], v[66:67], v[190:191] op_sel_hi:[1,0]
	v_pk_mul_f32 v[64:65], v[64:65], v[190:191] op_sel_hi:[1,0]
	v_pk_mul_f32 v[62:63], v[62:63], v[190:191] op_sel_hi:[1,0]
	v_pk_mul_f32 v[60:61], v[60:61], v[190:191] op_sel_hi:[1,0]
	v_pk_mul_f32 v[58:59], v[58:59], v[190:191] op_sel_hi:[1,0]
	v_pk_mul_f32 v[56:57], v[56:57], v[190:191] op_sel_hi:[1,0]
	v_pk_mul_f32 v[54:55], v[54:55], v[190:191] op_sel_hi:[1,0]
	v_pk_mul_f32 v[52:53], v[52:53], v[190:191] op_sel_hi:[1,0]
	v_pk_mul_f32 v[50:51], v[50:51], v[190:191] op_sel_hi:[1,0]
	v_pk_mul_f32 v[48:49], v[48:49], v[190:191] op_sel_hi:[1,0]
	v_pk_mul_f32 v[46:47], v[46:47], v[190:191] op_sel_hi:[1,0]
	v_pk_mul_f32 v[44:45], v[44:45], v[190:191] op_sel_hi:[1,0]
	v_pk_mul_f32 v[42:43], v[42:43], v[190:191] op_sel_hi:[1,0]
	v_pk_mul_f32 v[40:41], v[40:41], v[190:191] op_sel_hi:[1,0]
	v_pk_mul_f32 v[38:39], v[38:39], v[190:191] op_sel_hi:[1,0]
	v_pk_mul_f32 v[36:37], v[36:37], v[190:191] op_sel_hi:[1,0]
	v_pk_mul_f32 v[34:35], v[34:35], v[190:191] op_sel_hi:[1,0]
	v_pk_mul_f32 v[32:33], v[32:33], v[190:191] op_sel_hi:[1,0]
	v_pk_mul_f32 v[30:31], v[30:31], v[190:191] op_sel_hi:[1,0]
	v_pk_mul_f32 v[28:29], v[28:29], v[190:191] op_sel_hi:[1,0]
	v_pk_mul_f32 v[26:27], v[26:27], v[190:191] op_sel_hi:[1,0]
	v_pk_mul_f32 v[24:25], v[24:25], v[190:191] op_sel_hi:[1,0]
	v_pk_mul_f32 v[22:23], v[22:23], v[190:191] op_sel_hi:[1,0]
	v_pk_mul_f32 v[20:21], v[20:21], v[190:191] op_sel_hi:[1,0]
	v_pk_mul_f32 v[18:19], v[18:19], v[190:191] op_sel_hi:[1,0]
	v_pk_mul_f32 v[16:17], v[16:17], v[190:191] op_sel_hi:[1,0]
	v_pk_mul_f32 v[14:15], v[14:15], v[190:191] op_sel_hi:[1,0]
	v_pk_mul_f32 v[12:13], v[12:13], v[190:191] op_sel_hi:[1,0]
	v_pk_mul_f32 v[10:11], v[10:11], v[190:191] op_sel_hi:[1,0]
	v_pk_mul_f32 v[8:9], v[8:9], v[190:191] op_sel_hi:[1,0]
	v_pk_mul_f32 v[6:7], v[6:7], v[190:191] op_sel_hi:[1,0]
	v_pk_mul_f32 v[4:5], v[4:5], v[190:191] op_sel_hi:[1,0]
	v_pk_mul_f32 v[2:3], v[2:3], v[190:191] op_sel_hi:[1,0]
	v_pk_mul_f32 v[0:1], v[0:1], v[190:191] op_sel_hi:[1,0]
	v_mul_f32_e32 v203, v203, v190
	v_mov_b32_e32 v190, v246
	v_sub_f32_e32 v222, v222, v190
	v_exp_f32_e32 v222, v222
	v_sub_f32_e32 v223, v223, v190
	v_exp_f32_e32 v223, v223
	v_sub_f32_e32 v224, v224, v190
	v_add_f32_e32 v254, 0, v222
	v_exp_f32_e32 v224, v224
	v_sub_f32_e32 v225, v225, v190
	v_add_f32_e32 v254, v223, v254
	v_exp_f32_e32 v225, v225
	v_sub_f32_e32 v226, v226, v190
	v_add_f32_e32 v254, v224, v254
	v_exp_f32_e32 v226, v226
	v_sub_f32_e32 v227, v227, v190
	v_add_f32_e32 v254, v225, v254
	v_exp_f32_e32 v227, v227
	v_sub_f32_e32 v228, v228, v190
	v_add_f32_e32 v254, v226, v254
	v_exp_f32_e32 v228, v228
	v_sub_f32_e32 v229, v229, v190
	v_add_f32_e32 v254, v227, v254
	v_exp_f32_e32 v229, v229
	v_sub_f32_e32 v230, v230, v190
	v_add_f32_e32 v254, v228, v254
	v_exp_f32_e32 v230, v230
	v_sub_f32_e32 v231, v231, v190
	v_add_f32_e32 v254, v229, v254
	v_exp_f32_e32 v231, v231
	v_sub_f32_e32 v232, v232, v190
	v_add_f32_e32 v254, v230, v254
	v_exp_f32_e32 v232, v232
	v_sub_f32_e32 v233, v233, v190
	v_add_f32_e32 v254, v231, v254
	v_exp_f32_e32 v233, v233
	v_sub_f32_e32 v234, v234, v190
	v_add_f32_e32 v254, v232, v254
	v_exp_f32_e32 v234, v234
	v_sub_f32_e32 v235, v235, v190
	v_add_f32_e32 v254, v233, v254
	v_exp_f32_e32 v235, v235
	v_sub_f32_e32 v236, v236, v190
	v_add_f32_e32 v254, v234, v254
	v_exp_f32_e32 v236, v236
	v_sub_f32_e32 v237, v237, v190
	v_add_f32_e32 v254, v235, v254
	v_exp_f32_e32 v237, v237
	v_add_f32_e32 v254, v236, v254
	v_add_f32_e32 v254, v237, v254
	v_cvt_pk_bf16_f32 v242, v222, v223
	v_cvt_pk_bf16_f32 v243, v224, v225
	v_cvt_pk_bf16_f32 v244, v226, v227
	v_cvt_pk_bf16_f32 v245, v228, v229
	v_cvt_pk_bf16_f32 v250, v230, v231
	v_cvt_pk_bf16_f32 v251, v232, v233
	v_cvt_pk_bf16_f32 v252, v234, v235
	v_cvt_pk_bf16_f32 v253, v236, v237
	v_add_f32_e32 v203, v203, v254
	s_nop 1
	s_waitcnt lgkmcnt(8)
	v_mfma_f32_32x32x16_bf16 v[112:127], v[238:241], v[242:245], v[112:127]
	ds_read_b64_tr_b16 v[238:239], v218 offset:16640
	ds_read_b64_tr_b16 v[240:241], v218 offset:20736
	s_waitcnt lgkmcnt(8)
	v_mfma_f32_32x32x16_bf16 v[96:111], v[128:131], v[242:245], v[96:111]
	ds_read_b64_tr_b16 v[222:223], v219 offset:16640
	ds_read_b64_tr_b16 v[224:225], v219 offset:20736
	s_cmp_lg_u64 s[12:13], 0
	s_cbranch_scc1 .Latt_ndr0_2
	s_sub_i32 s100, s38, 1
	s_cmp_eq_u32 s38, 0
	s_cselect_b32 s100, 2, s100
	s_lshl_b32 s101, s100, 14
	s_add_i32 m0, s40, s101
	s_nop 0
	global_load_lds_dwordx4 v178, s[22:23]

.Latt_nr0_3:
	s_waitcnt lgkmcnt(3)
	v_mfma_f32_32x32x16_bf16 v[222:237], v[214:217], v[152:155], v[222:237]
	v_add_u32_e32 v214, s98, v202
	ds_read_b128 v[214:217], v214 offset:8192
	v_sub_f32_e32 v128, v128, v190
	v_exp_f32_e32 v128, v128
	v_sub_f32_e32 v129, v129, v190
	v_exp_f32_e32 v129, v129
	v_sub_f32_e32 v130, v130, v190
	s_waitcnt lgkmcnt(3)
	v_mfma_f32_32x32x16_bf16 v[222:237], v[238:241], v[156:159], v[222:237]
	v_add_u32_e32 v238, s98, v203
	ds_read_b128 v[238:241], v238 offset:8192
	v_add_f32_e32 v254, 0, v128
	v_exp_f32_e32 v130, v130
	v_sub_f32_e32 v131, v131, v190
	v_add_f32_e32 v254, v129, v254
	v_exp_f32_e32 v131, v131
	s_waitcnt lgkmcnt(3)
	v_mfma_f32_32x32x16_bf16 v[222:237], v[206:209], v[160:163], v[222:237]
	ds_read_b64_tr_b16 v[206:207], v205
	ds_read_b64_tr_b16 v[208:209], v205 offset:4096
	v_sub_f32_e32 v132, v132, v190
	v_add_f32_e32 v254, v130, v254
	v_exp_f32_e32 v132, v132
	v_sub_f32_e32 v133, v133, v190
	v_add_f32_e32 v254, v131, v254
	s_waitcnt lgkmcnt(4)
	v_mfma_f32_32x32x16_bf16 v[222:237], v[210:213], v[164:167], v[222:237]
	ds_read_b64_tr_b16 v[210:211], v218
	ds_read_b64_tr_b16 v[212:213], v218 offset:4096
	v_exp_f32_e32 v133, v133
	v_sub_f32_e32 v134, v134, v190
	v_add_f32_e32 v254, v132, v254
	v_exp_f32_e32 v134, v134
	s_waitcnt lgkmcnt(5)
	v_mfma_f32_32x32x16_bf16 v[222:237], v[214:217], v[168:171], v[222:237]
	ds_read_b64_tr_b16 v[214:215], v219
	ds_read_b64_tr_b16 v[216:217], v219 offset:4096
	v_sub_f32_e32 v135, v135, v190
	v_add_f32_e32 v254, v133, v254
	v_exp_f32_e32 v135, v135
	s_nop 0
	s_waitcnt lgkmcnt(6)
	v_mfma_f32_32x32x16_bf16 v[222:237], v[238:241], v[172:175], v[222:237]
	ds_read_b64_tr_b16 v[238:239], v221
	ds_read_b64_tr_b16 v[240:241], v221 offset:4096
	v_cvt_pk_bf16_f32 v242, v128, v129
	v_cvt_pk_bf16_f32 v243, v130, v131
	v_cvt_pk_bf16_f32 v244, v132, v133
	v_cvt_pk_bf16_f32 v245, v134, v135
	s_nop 1
	s_waitcnt lgkmcnt(6)
	v_mfma_f32_32x32x16_bf16 v[112:127], v[206:209], v[242:245], v[112:127]
	ds_read_b64_tr_b16 v[206:207], v205 offset:256
	ds_read_b64_tr_b16 v[208:209], v205 offset:4352
	v_sub_f32_e32 v136, v136, v190
	v_add_f32_e32 v254, v134, v254
	v_exp_f32_e32 v136, v136
	v_sub_f32_e32 v137, v137, v190
	v_add_f32_e32 v254, v135, v254
	s_waitcnt lgkmcnt(6)
	v_mfma_f32_32x32x16_bf16 v[96:111], v[210:213], v[242:245], v[96:111]
	ds_read_b64_tr_b16 v[210:211], v218 offset:256
	ds_read_b64_tr_b16 v[212:213], v218 offset:4352
	v_exp_f32_e32 v137, v137
	v_sub_f32_e32 v138, v138, v190
	v_add_f32_e32 v254, v136, v254
	v_exp_f32_e32 v138, v138
	v_sub_f32_e32 v139, v139, v190
	s_waitcnt lgkmcnt(6)
	v_mfma_f32_32x32x16_bf16 v[80:95], v[214:217], v[242:245], v[80:95]
	ds_read_b64_tr_b16 v[214:215], v219 offset:256
	ds_read_b64_tr_b16 v[216:217], v219 offset:4352
	v_add_f32_e32 v254, v137, v254
	v_exp_f32_e32 v139, v139
	v_sub_f32_e32 v140, v140, v190
	v_add_f32_e32 v254, v138, v254
	s_waitcnt lgkmcnt(6)
	v_mfma_f32_32x32x16_bf16 v[64:79], v[238:241], v[242:245], v[64:79]
	ds_read_b64_tr_b16 v[238:239], v221 offset:256
	ds_read_b64_tr_b16 v[240:241], v221 offset:4352
	v_exp_f32_e32 v140, v140
	v_sub_f32_e32 v141, v141, v190
	v_add_f32_e32 v254, v139, v254
	v_exp_f32_e32 v141, v141
	s_waitcnt lgkmcnt(6)
	v_mfma_f32_32x32x16_bf16 v[48:63], v[206:209], v[242:245], v[48:63]
	ds_read_b64_tr_b16 v[206:207], v205 offset:8192
	ds_read_b64_tr_b16 v[208:209], v205 offset:12288
	v_sub_f32_e32 v142, v142, v190
	v_add_f32_e32 v254, v140, v254
	v_exp_f32_e32 v142, v142
	v_sub_f32_e32 v143, v143, v190
	s_waitcnt lgkmcnt(6)
	v_mfma_f32_32x32x16_bf16 v[32:47], v[210:213], v[242:245], v[32:47]
	ds_read_b64_tr_b16 v[210:211], v218 offset:8192
	ds_read_b64_tr_b16 v[212:213], v218 offset:12288
	v_add_f32_e32 v254, v141, v254
	v_exp_f32_e32 v143, v143
	v_add_f32_e32 v254, v142, v254
	v_add_f32_e32 v254, v143, v254
	s_waitcnt lgkmcnt(6)
	v_mfma_f32_32x32x16_bf16 v[16:31], v[214:217], v[242:245], v[16:31]
	ds_read_b64_tr_b16 v[214:215], v219 offset:8192
	ds_read_b64_tr_b16 v[216:217], v219 offset:12288
	v_cvt_pk_bf16_f32 v250, v136, v137
	v_cvt_pk_bf16_f32 v251, v138, v139
	v_cvt_pk_bf16_f32 v252, v140, v141
	v_cvt_pk_bf16_f32 v253, v142, v143
	v_add_f32_e32 v195, v195, v254
	s_waitcnt lgkmcnt(6)
	v_mfma_f32_32x32x16_bf16 v[0:15], v[238:241], v[242:245], v[0:15]
	ds_read_b64_tr_b16 v[238:239], v221 offset:8192
	ds_read_b64_tr_b16 v[240:241], v221 offset:12288
	ds_read_b64_tr_b16 v[128:129], v205 offset:8448
	ds_read_b64_tr_b16 v[130:131], v205 offset:12544
	v_max3_f32 v246, v222, v223, v224
	v_max3_f32 v247, v225, v226, v227
	v_max3_f32 v246, v246, v228, v229
	v_max3_f32 v247, v247, v230, v231
	v_max3_f32 v246, v246, v232, v233
	s_waitcnt lgkmcnt(8)
	v_mfma_f32_32x32x16_bf16 v[112:127], v[206:209], v[250:253], v[112:127]
	ds_read_b64_tr_b16 v[206:207], v218 offset:8448
	ds_read_b64_tr_b16 v[208:209], v218 offset:12544
	v_max3_f32 v247, v247, v234, v235
	v_max3_f32 v246, v246, v236, v237
	v_max_f32_e32 v246, v246, v247
	v_mov_b32_e32 v247, v246
	v_add_f32_e32 v249, 0x41000000, v190
	s_waitcnt lgkmcnt(8)
	v_mfma_f32_32x32x16_bf16 v[96:111], v[210:213], v[250:253], v[96:111]
	ds_read_b64_tr_b16 v[210:211], v219 offset:8448
	ds_read_b64_tr_b16 v[212:213], v219 offset:12544
	s_nop 1
	v_permlane32_swap_b32_e32 v246, v247
	v_max_f32_e32 v246, v246, v247
	v_cmp_gt_f32_e32 vcc, v246, v249
	s_cbranch_vccnz .Latt_rs1_3
	s_waitcnt lgkmcnt(8)
	v_mfma_f32_32x32x16_bf16 v[80:95], v[214:217], v[250:253], v[80:95]
	ds_read_b64_tr_b16 v[214:215], v221 offset:8448
	ds_read_b64_tr_b16 v[216:217], v221 offset:12544
	v_sub_f32_e32 v222, v222, v190
	v_exp_f32_e32 v222, v222
	v_sub_f32_e32 v223, v223, v190
	v_exp_f32_e32 v223, v223
	v_sub_f32_e32 v224, v224, v190
	s_waitcnt lgkmcnt(8)
	v_mfma_f32_32x32x16_bf16 v[64:79], v[238:241], v[250:253], v[64:79]
	ds_read_b64_tr_b16 v[238:239], v205 offset:16384
	ds_read_b64_tr_b16 v[240:241], v205 offset:20480
	v_add_f32_e32 v254, 0, v222
	v_exp_f32_e32 v224, v224
	v_sub_f32_e32 v225, v225, v190
	v_add_f32_e32 v254, v223, v254
	v_exp_f32_e32 v225, v225
	s_waitcnt lgkmcnt(8)
	v_mfma_f32_32x32x16_bf16 v[48:63], v[128:131], v[250:253], v[48:63]
	ds_read_b64_tr_b16 v[128:129], v218 offset:16384
	ds_read_b64_tr_b16 v[130:131], v218 offset:20480
	v_sub_f32_e32 v226, v226, v190
	v_add_f32_e32 v254, v224, v254
	v_exp_f32_e32 v226, v226
	v_sub_f32_e32 v227, v227, v190
	v_add_f32_e32 v254, v225, v254
	s_waitcnt lgkmcnt(8)
	v_mfma_f32_32x32x16_bf16 v[32:47], v[206:209], v[250:253], v[32:47]
	ds_read_b64_tr_b16 v[206:207], v219 offset:16384
	ds_read_b64_tr_b16 v[208:209], v219 offset:20480
	v_exp_f32_e32 v227, v227
	v_sub_f32_e32 v228, v228, v190
	v_add_f32_e32 v254, v226, v254
	v_exp_f32_e32 v228, v228
	s_waitcnt lgkmcnt(8)
	v_mfma_f32_32x32x16_bf16 v[16:31], v[210:213], v[250:253], v[16:31]
	ds_read_b64_tr_b16 v[210:211], v221 offset:16384
	ds_read_b64_tr_b16 v[212:213], v221 offset:20480
	v_sub_f32_e32 v229, v229, v190
	v_add_f32_e32 v254, v227, v254
	v_exp_f32_e32 v229, v229
	s_nop 0
	s_waitcnt lgkmcnt(8)
	v_mfma_f32_32x32x16_bf16 v[0:15], v[214:217], v[250:253], v[0:15]
	ds_read_b64_tr_b16 v[214:215], v205 offset:16640
	ds_read_b64_tr_b16 v[216:217], v205 offset:20736
	v_cvt_pk_bf16_f32 v242, v222, v223
	v_cvt_pk_bf16_f32 v243, v224, v225
	v_cvt_pk_bf16_f32 v244, v226, v227
	v_cvt_pk_bf16_f32 v245, v228, v229
	s_nop 1
	s_waitcnt lgkmcnt(8)
	v_mfma_f32_32x32x16_bf16 v[112:127], v[238:241], v[242:245], v[112:127]
	ds_read_b64_tr_b16 v[238:239], v218 offset:16640
	ds_read_b64_tr_b16 v[240:241], v218 offset:20736
	v_sub_f32_e32 v230, v230, v190
	v_add_f32_e32 v254, v228, v254
	v_exp_f32_e32 v230, v230
	v_sub_f32_e32 v231, v231, v190
	v_add_f32_e32 v254, v229, v254
	s_waitcnt lgkmcnt(8)
	v_mfma_f32_32x32x16_bf16 v[96:111], v[128:131], v[242:245], v[96:111]
	ds_read_b64_tr_b16 v[128:129], v219 offset:16640
	ds_read_b64_tr_b16 v[130:131], v219 offset:20736
	v_exp_f32_e32 v231, v231
	v_sub_f32_e32 v232, v232, v190
	v_add_f32_e32 v254, v230, v254
	v_exp_f32_e32 v232, v232
	v_sub_f32_e32 v233, v233, v190
	s_cmp_lg_u64 s[8:9], 0
	s_cbranch_scc1 .Latt_nd0_3
	s_sub_i32 s100, s11, 1
	s_cmp_eq_u32 s11, 0
	s_cselect_b32 s100, 2, s100
	s_lshl_b32 s101, s100, 14
	s_add_i32 m0, s40, s101
	s_nop 0
	global_load_lds_dwordx4 v178, s[34:35]

.Latt_rs1_3:
	s_waitcnt lgkmcnt(8)
	v_mfma_f32_32x32x16_bf16 v[80:95], v[214:217], v[250:253], v[80:95]
	ds_read_b64_tr_b16 v[214:215], v221 offset:8448
	ds_read_b64_tr_b16 v[216:217], v221 offset:12544
	s_waitcnt lgkmcnt(8)
	v_mfma_f32_32x32x16_bf16 v[64:79], v[238:241], v[250:253], v[64:79]
	ds_read_b64_tr_b16 v[238:239], v205 offset:16384
	ds_read_b64_tr_b16 v[240:241], v205 offset:20480
	s_waitcnt lgkmcnt(8)
	v_mfma_f32_32x32x16_bf16 v[48:63], v[128:131], v[250:253], v[48:63]
	ds_read_b64_tr_b16 v[128:129], v218 offset:16384
	ds_read_b64_tr_b16 v[130:131], v218 offset:20480
	s_waitcnt lgkmcnt(8)
	v_mfma_f32_32x32x16_bf16 v[32:47], v[206:209], v[250:253], v[32:47]
	ds_read_b64_tr_b16 v[206:207], v219 offset:16384
	ds_read_b64_tr_b16 v[208:209], v219 offset:20480
	s_waitcnt lgkmcnt(8)
	v_mfma_f32_32x32x16_bf16 v[16:31], v[210:213], v[250:253], v[16:31]
	ds_read_b64_tr_b16 v[210:211], v221 offset:16384
	ds_read_b64_tr_b16 v[212:213], v221 offset:20480
	s_waitcnt lgkmcnt(8)
	v_mfma_f32_32x32x16_bf16 v[0:15], v[214:217], v[250:253], v[0:15]
	ds_read_b64_tr_b16 v[214:215], v205 offset:16640
	ds_read_b64_tr_b16 v[216:217], v205 offset:20736
	s_nop 11
	v_max_f32_e32 v246, v190, v246
	v_sub_f32_e32 v190, v190, v246
	v_exp_f32_e32 v190, v190
	s_nop 0
	v_pk_mul_f32 v[126:127], v[126:127], v[190:191] op_sel_hi:[1,0]
	v_pk_mul_f32 v[124:125], v[124:125], v[190:191] op_sel_hi:[1,0]
	v_pk_mul_f32 v[122:123], v[122:123], v[190:191] op_sel_hi:[1,0]
	v_pk_mul_f32 v[120:121], v[120:121], v[190:191] op_sel_hi:[1,0]
	v_pk_mul_f32 v[118:119], v[118:119], v[190:191] op_sel_hi:[1,0]
	v_pk_mul_f32 v[116:117], v[116:117], v[190:191] op_sel_hi:[1,0]
	v_pk_mul_f32 v[114:115], v[114:115], v[190:191] op_sel_hi:[1,0]
	v_pk_mul_f32 v[112:113], v[112:113], v[190:191] op_sel_hi:[1,0]
	v_pk_mul_f32 v[110:111], v[110:111], v[190:191] op_sel_hi:[1,0]
	v_pk_mul_f32 v[108:109], v[108:109], v[190:191] op_sel_hi:[1,0]
	v_pk_mul_f32 v[106:107], v[106:107], v[190:191] op_sel_hi:[1,0]
	v_pk_mul_f32 v[104:105], v[104:105], v[190:191] op_sel_hi:[1,0]
	v_pk_mul_f32 v[102:103], v[102:103], v[190:191] op_sel_hi:[1,0]
	v_pk_mul_f32 v[100:101], v[100:101], v[190:191] op_sel_hi:[1,0]
	v_pk_mul_f32 v[98:99], v[98:99], v[190:191] op_sel_hi:[1,0]
	v_pk_mul_f32 v[96:97], v[96:97], v[190:191] op_sel_hi:[1,0]
	v_pk_mul_f32 v[94:95], v[94:95], v[190:191] op_sel_hi:[1,0]
	v_pk_mul_f32 v[92:93], v[92:93], v[190:191] op_sel_hi:[1,0]
	v_pk_mul_f32 v[90:91], v[90:91], v[190:191] op_sel_hi:[1,0]
	v_pk_mul_f32 v[88:89], v[88:89], v[190:191] op_sel_hi:[1,0]
	v_pk_mul_f32 v[86:87], v[86:87], v[190:191] op_sel_hi:[1,0]
	v_pk_mul_f32 v[84:85], v[84:85], v[190:191] op_sel_hi:[1,0]
	v_pk_mul_f32 v[82:83], v[82:83], v[190:191] op_sel_hi:[1,0]
	v_pk_mul_f32 v[80:81], v[80:81], v[190:191] op_sel_hi:[1,0]
	v_pk_mul_f32 v[78:79], v[78:79], v[190:191] op_sel_hi:[1,0]
	v_pk_mul_f32 v[76:77], v[76:77], v[190:191] op_sel_hi:[1,0]
	v_pk_mul_f32 v[74:75], v[74:75], v[190:191] op_sel_hi:[1,0]
	v_pk_mul_f32 v[72:73], v[72:73], v[190:191] op_sel_hi:[1,0]
	v_pk_mul_f32 v[70:71], v[70:71], v[190:191] op_sel_hi:[1,0]
	v_pk_mul_f32 v[68:69], v[68:69], v[190:191] op_sel_hi:[1,0]
	v_pk_mul_f32 v[66:67], v[66:67], v[190:191] op_sel_hi:[1,0]
	v_pk_mul_f32 v[64:65], v[64:65], v[190:191] op_sel_hi:[1,0]
	v_pk_mul_f32 v[62:63], v[62:63], v[190:191] op_sel_hi:[1,0]
	v_pk_mul_f32 v[60:61], v[60:61], v[190:191] op_sel_hi:[1,0]
	v_pk_mul_f32 v[58:59], v[58:59], v[190:191] op_sel_hi:[1,0]
	v_pk_mul_f32 v[56:57], v[56:57], v[190:191] op_sel_hi:[1,0]
	v_pk_mul_f32 v[54:55], v[54:55], v[190:191] op_sel_hi:[1,0]
	v_pk_mul_f32 v[52:53], v[52:53], v[190:191] op_sel_hi:[1,0]
	v_pk_mul_f32 v[50:51], v[50:51], v[190:191] op_sel_hi:[1,0]
	v_pk_mul_f32 v[48:49], v[48:49], v[190:191] op_sel_hi:[1,0]
	v_pk_mul_f32 v[46:47], v[46:47], v[190:191] op_sel_hi:[1,0]
	v_pk_mul_f32 v[44:45], v[44:45], v[190:191] op_sel_hi:[1,0]
	v_pk_mul_f32 v[42:43], v[42:43], v[190:191] op_sel_hi:[1,0]
	v_pk_mul_f32 v[40:41], v[40:41], v[190:191] op_sel_hi:[1,0]
	v_pk_mul_f32 v[38:39], v[38:39], v[190:191] op_sel_hi:[1,0]
	v_pk_mul_f32 v[36:37], v[36:37], v[190:191] op_sel_hi:[1,0]
	v_pk_mul_f32 v[34:35], v[34:35], v[190:191] op_sel_hi:[1,0]
	v_pk_mul_f32 v[32:33], v[32:33], v[190:191] op_sel_hi:[1,0]
	v_pk_mul_f32 v[30:31], v[30:31], v[190:191] op_sel_hi:[1,0]
	v_pk_mul_f32 v[28:29], v[28:29], v[190:191] op_sel_hi:[1,0]
	v_pk_mul_f32 v[26:27], v[26:27], v[190:191] op_sel_hi:[1,0]
	v_pk_mul_f32 v[24:25], v[24:25], v[190:191] op_sel_hi:[1,0]
	v_pk_mul_f32 v[22:23], v[22:23], v[190:191] op_sel_hi:[1,0]
	v_pk_mul_f32 v[20:21], v[20:21], v[190:191] op_sel_hi:[1,0]
	v_pk_mul_f32 v[18:19], v[18:19], v[190:191] op_sel_hi:[1,0]
	v_pk_mul_f32 v[16:17], v[16:17], v[190:191] op_sel_hi:[1,0]
	v_pk_mul_f32 v[14:15], v[14:15], v[190:191] op_sel_hi:[1,0]
	v_pk_mul_f32 v[12:13], v[12:13], v[190:191] op_sel_hi:[1,0]
	v_pk_mul_f32 v[10:11], v[10:11], v[190:191] op_sel_hi:[1,0]
	v_pk_mul_f32 v[8:9], v[8:9], v[190:191] op_sel_hi:[1,0]
	v_pk_mul_f32 v[6:7], v[6:7], v[190:191] op_sel_hi:[1,0]
	v_pk_mul_f32 v[4:5], v[4:5], v[190:191] op_sel_hi:[1,0]
	v_pk_mul_f32 v[2:3], v[2:3], v[190:191] op_sel_hi:[1,0]
	v_pk_mul_f32 v[0:1], v[0:1], v[190:191] op_sel_hi:[1,0]
	v_mul_f32_e32 v195, v195, v190
	v_mov_b32_e32 v190, v246
	v_sub_f32_e32 v222, v222, v190
	v_exp_f32_e32 v222, v222
	v_sub_f32_e32 v223, v223, v190
	v_exp_f32_e32 v223, v223
	v_sub_f32_e32 v224, v224, v190
	v_add_f32_e32 v254, 0, v222
	v_exp_f32_e32 v224, v224
	v_sub_f32_e32 v225, v225, v190
	v_add_f32_e32 v254, v223, v254
	v_exp_f32_e32 v225, v225
	v_sub_f32_e32 v226, v226, v190
	v_add_f32_e32 v254, v224, v254
	v_exp_f32_e32 v226, v226
	v_sub_f32_e32 v227, v227, v190
	v_add_f32_e32 v254, v225, v254
	v_exp_f32_e32 v227, v227
	v_sub_f32_e32 v228, v228, v190
	v_add_f32_e32 v254, v226, v254
	v_exp_f32_e32 v228, v228
	v_sub_f32_e32 v229, v229, v190
	v_add_f32_e32 v254, v227, v254
	v_exp_f32_e32 v229, v229
	v_sub_f32_e32 v230, v230, v190
	v_add_f32_e32 v254, v228, v254
	v_exp_f32_e32 v230, v230
	v_sub_f32_e32 v231, v231, v190
	v_add_f32_e32 v254, v229, v254
	v_exp_f32_e32 v231, v231
	v_sub_f32_e32 v232, v232, v190
	v_add_f32_e32 v254, v230, v254
	v_exp_f32_e32 v232, v232
	v_sub_f32_e32 v233, v233, v190
	v_add_f32_e32 v254, v231, v254
	v_exp_f32_e32 v233, v233
	v_sub_f32_e32 v234, v234, v190
	v_add_f32_e32 v254, v232, v254
	v_exp_f32_e32 v234, v234
	v_sub_f32_e32 v235, v235, v190
	v_add_f32_e32 v254, v233, v254
	v_exp_f32_e32 v235, v235
	v_sub_f32_e32 v236, v236, v190
	v_add_f32_e32 v254, v234, v254
	v_exp_f32_e32 v236, v236
	v_sub_f32_e32 v237, v237, v190
	v_add_f32_e32 v254, v235, v254
	v_exp_f32_e32 v237, v237
	v_add_f32_e32 v254, v236, v254
	v_add_f32_e32 v254, v237, v254
	v_cvt_pk_bf16_f32 v242, v222, v223
	v_cvt_pk_bf16_f32 v243, v224, v225
	v_cvt_pk_bf16_f32 v244, v226, v227
	v_cvt_pk_bf16_f32 v245, v228, v229
	v_cvt_pk_bf16_f32 v250, v230, v231
	v_cvt_pk_bf16_f32 v251, v232, v233
	v_cvt_pk_bf16_f32 v252, v234, v235
	v_cvt_pk_bf16_f32 v253, v236, v237
	v_add_f32_e32 v195, v195, v254
	s_nop 1
	s_waitcnt lgkmcnt(8)
	v_mfma_f32_32x32x16_bf16 v[112:127], v[238:241], v[242:245], v[112:127]
	ds_read_b64_tr_b16 v[238:239], v218 offset:16640
	ds_read_b64_tr_b16 v[240:241], v218 offset:20736
	s_waitcnt lgkmcnt(8)
	v_mfma_f32_32x32x16_bf16 v[96:111], v[128:131], v[242:245], v[96:111]
	ds_read_b64_tr_b16 v[222:223], v219 offset:16640
	ds_read_b64_tr_b16 v[224:225], v219 offset:20736
	s_cmp_lg_u64 s[8:9], 0
	s_cbranch_scc1 .Latt_ndr0_3
	s_sub_i32 s100, s11, 1
	s_cmp_eq_u32 s11, 0
	s_cselect_b32 s100, 2, s100
	s_lshl_b32 s101, s100, 14
	s_add_i32 m0, s40, s101
	s_nop 0
	global_load_lds_dwordx4 v178, s[34:35]

.Latt_nr0_4:
	s_waitcnt lgkmcnt(3)
	v_mfma_f32_32x32x16_bf16 v[222:237], v[214:217], v[152:155], v[222:237]
	v_add_u32_e32 v214, s98, v200
	ds_read_b128 v[214:217], v214 offset:8192
	v_sub_f32_e32 v128, v128, v190
	v_exp_f32_e32 v128, v128
	v_sub_f32_e32 v129, v129, v190
	v_exp_f32_e32 v129, v129
	v_sub_f32_e32 v130, v130, v190
	s_waitcnt lgkmcnt(3)
	v_mfma_f32_32x32x16_bf16 v[222:237], v[238:241], v[156:159], v[222:237]
	v_add_u32_e32 v238, s98, v201
	ds_read_b128 v[238:241], v238 offset:8192
	v_add_f32_e32 v254, 0, v128
	v_exp_f32_e32 v130, v130
	v_sub_f32_e32 v131, v131, v190
	v_add_f32_e32 v254, v129, v254
	v_exp_f32_e32 v131, v131
	s_waitcnt lgkmcnt(3)
	v_mfma_f32_32x32x16_bf16 v[222:237], v[206:209], v[160:163], v[222:237]
	ds_read_b64_tr_b16 v[206:207], v205
	ds_read_b64_tr_b16 v[208:209], v205 offset:4096
	v_sub_f32_e32 v132, v132, v190
	v_add_f32_e32 v254, v130, v254
	v_exp_f32_e32 v132, v132
	v_sub_f32_e32 v133, v133, v190
	v_add_f32_e32 v254, v131, v254
	s_waitcnt lgkmcnt(4)
	v_mfma_f32_32x32x16_bf16 v[222:237], v[210:213], v[164:167], v[222:237]
	ds_read_b64_tr_b16 v[210:211], v218
	ds_read_b64_tr_b16 v[212:213], v218 offset:4096
	v_exp_f32_e32 v133, v133
	v_sub_f32_e32 v134, v134, v190
	v_add_f32_e32 v254, v132, v254
	v_exp_f32_e32 v134, v134
	s_waitcnt lgkmcnt(5)
	v_mfma_f32_32x32x16_bf16 v[222:237], v[214:217], v[168:171], v[222:237]
	ds_read_b64_tr_b16 v[214:215], v219
	ds_read_b64_tr_b16 v[216:217], v219 offset:4096
	v_sub_f32_e32 v135, v135, v190
	v_add_f32_e32 v254, v133, v254
	v_exp_f32_e32 v135, v135
	s_nop 0
	s_waitcnt lgkmcnt(6)
	v_mfma_f32_32x32x16_bf16 v[222:237], v[238:241], v[172:175], v[222:237]
	ds_read_b64_tr_b16 v[238:239], v221
	ds_read_b64_tr_b16 v[240:241], v221 offset:4096
	v_cvt_pk_bf16_f32 v242, v128, v129
	v_cvt_pk_bf16_f32 v243, v130, v131
	v_cvt_pk_bf16_f32 v244, v132, v133
	v_cvt_pk_bf16_f32 v245, v134, v135
	s_nop 1
	s_waitcnt lgkmcnt(6)
	v_mfma_f32_32x32x16_bf16 v[112:127], v[206:209], v[242:245], v[112:127]
	ds_read_b64_tr_b16 v[206:207], v205 offset:256
	ds_read_b64_tr_b16 v[208:209], v205 offset:4352
	v_sub_f32_e32 v136, v136, v190
	v_add_f32_e32 v254, v134, v254
	v_exp_f32_e32 v136, v136
	v_sub_f32_e32 v137, v137, v190
	v_add_f32_e32 v254, v135, v254
	s_waitcnt lgkmcnt(6)
	v_mfma_f32_32x32x16_bf16 v[96:111], v[210:213], v[242:245], v[96:111]
	ds_read_b64_tr_b16 v[210:211], v218 offset:256
	ds_read_b64_tr_b16 v[212:213], v218 offset:4352
	v_exp_f32_e32 v137, v137
	v_sub_f32_e32 v138, v138, v190
	v_add_f32_e32 v254, v136, v254
	v_exp_f32_e32 v138, v138
	v_sub_f32_e32 v139, v139, v190
	s_waitcnt lgkmcnt(6)
	v_mfma_f32_32x32x16_bf16 v[80:95], v[214:217], v[242:245], v[80:95]
	ds_read_b64_tr_b16 v[214:215], v219 offset:256
	ds_read_b64_tr_b16 v[216:217], v219 offset:4352
	v_add_f32_e32 v254, v137, v254
	v_exp_f32_e32 v139, v139
	v_sub_f32_e32 v140, v140, v190
	v_add_f32_e32 v254, v138, v254
	s_waitcnt lgkmcnt(6)
	v_mfma_f32_32x32x16_bf16 v[64:79], v[238:241], v[242:245], v[64:79]
	ds_read_b64_tr_b16 v[238:239], v221 offset:256
	ds_read_b64_tr_b16 v[240:241], v221 offset:4352
	v_exp_f32_e32 v140, v140
	v_sub_f32_e32 v141, v141, v190
	v_add_f32_e32 v254, v139, v254
	v_exp_f32_e32 v141, v141
	s_waitcnt lgkmcnt(6)
	v_mfma_f32_32x32x16_bf16 v[48:63], v[206:209], v[242:245], v[48:63]
	ds_read_b64_tr_b16 v[206:207], v205 offset:8192
	ds_read_b64_tr_b16 v[208:209], v205 offset:12288
	v_sub_f32_e32 v142, v142, v190
	v_add_f32_e32 v254, v140, v254
	v_exp_f32_e32 v142, v142
	v_sub_f32_e32 v143, v143, v190
	s_waitcnt lgkmcnt(6)
	v_mfma_f32_32x32x16_bf16 v[32:47], v[210:213], v[242:245], v[32:47]
	ds_read_b64_tr_b16 v[210:211], v218 offset:8192
	ds_read_b64_tr_b16 v[212:213], v218 offset:12288
	v_add_f32_e32 v254, v141, v254
	v_exp_f32_e32 v143, v143
	v_add_f32_e32 v254, v142, v254
	v_add_f32_e32 v254, v143, v254
	s_waitcnt lgkmcnt(6)
	v_mfma_f32_32x32x16_bf16 v[16:31], v[214:217], v[242:245], v[16:31]
	ds_read_b64_tr_b16 v[214:215], v219 offset:8192
	ds_read_b64_tr_b16 v[216:217], v219 offset:12288
	v_cvt_pk_bf16_f32 v250, v136, v137
	v_cvt_pk_bf16_f32 v251, v138, v139
	v_cvt_pk_bf16_f32 v252, v140, v141
	v_cvt_pk_bf16_f32 v253, v142, v143
	v_add_f32_e32 v202, v202, v254
	s_waitcnt lgkmcnt(6)
	v_mfma_f32_32x32x16_bf16 v[0:15], v[238:241], v[242:245], v[0:15]
	ds_read_b64_tr_b16 v[238:239], v221 offset:8192
	ds_read_b64_tr_b16 v[240:241], v221 offset:12288
	ds_read_b64_tr_b16 v[128:129], v205 offset:8448
	ds_read_b64_tr_b16 v[130:131], v205 offset:12544
	v_max3_f32 v246, v222, v223, v224
	v_max3_f32 v247, v225, v226, v227
	v_max3_f32 v246, v246, v228, v229
	v_max3_f32 v247, v247, v230, v231
	v_max3_f32 v246, v246, v232, v233
	s_waitcnt lgkmcnt(8)
	v_mfma_f32_32x32x16_bf16 v[112:127], v[206:209], v[250:253], v[112:127]
	ds_read_b64_tr_b16 v[206:207], v218 offset:8448
	ds_read_b64_tr_b16 v[208:209], v218 offset:12544
	v_max3_f32 v247, v247, v234, v235
	v_max3_f32 v246, v246, v236, v237
	v_max_f32_e32 v246, v246, v247
	v_mov_b32_e32 v247, v246
	v_add_f32_e32 v249, 0x41000000, v190
	s_waitcnt lgkmcnt(8)
	v_mfma_f32_32x32x16_bf16 v[96:111], v[210:213], v[250:253], v[96:111]
	ds_read_b64_tr_b16 v[210:211], v219 offset:8448
	ds_read_b64_tr_b16 v[212:213], v219 offset:12544
	s_nop 1
	v_permlane32_swap_b32_e32 v246, v247
	v_max_f32_e32 v246, v246, v247
	v_cmp_gt_f32_e32 vcc, v246, v249
	s_cbranch_vccnz .Latt_rs1_4
	s_waitcnt lgkmcnt(8)
	v_mfma_f32_32x32x16_bf16 v[80:95], v[214:217], v[250:253], v[80:95]
	ds_read_b64_tr_b16 v[214:215], v221 offset:8448
	ds_read_b64_tr_b16 v[216:217], v221 offset:12544
	v_sub_f32_e32 v222, v222, v190
	v_exp_f32_e32 v222, v222
	v_sub_f32_e32 v223, v223, v190
	v_exp_f32_e32 v223, v223
	v_sub_f32_e32 v224, v224, v190
	s_waitcnt lgkmcnt(8)
	v_mfma_f32_32x32x16_bf16 v[64:79], v[238:241], v[250:253], v[64:79]
	ds_read_b64_tr_b16 v[238:239], v205 offset:16384
	ds_read_b64_tr_b16 v[240:241], v205 offset:20480
	v_add_f32_e32 v254, 0, v222
	v_exp_f32_e32 v224, v224
	v_sub_f32_e32 v225, v225, v190
	v_add_f32_e32 v254, v223, v254
	v_exp_f32_e32 v225, v225
	s_waitcnt lgkmcnt(8)
	v_mfma_f32_32x32x16_bf16 v[48:63], v[128:131], v[250:253], v[48:63]
	ds_read_b64_tr_b16 v[128:129], v218 offset:16384
	ds_read_b64_tr_b16 v[130:131], v218 offset:20480
	v_sub_f32_e32 v226, v226, v190
	v_add_f32_e32 v254, v224, v254
	v_exp_f32_e32 v226, v226
	v_sub_f32_e32 v227, v227, v190
	v_add_f32_e32 v254, v225, v254
	s_waitcnt lgkmcnt(8)
	v_mfma_f32_32x32x16_bf16 v[32:47], v[206:209], v[250:253], v[32:47]
	ds_read_b64_tr_b16 v[206:207], v219 offset:16384
	ds_read_b64_tr_b16 v[208:209], v219 offset:20480
	v_exp_f32_e32 v227, v227
	v_sub_f32_e32 v228, v228, v190
	v_add_f32_e32 v254, v226, v254
	v_exp_f32_e32 v228, v228
	s_waitcnt lgkmcnt(8)
	v_mfma_f32_32x32x16_bf16 v[16:31], v[210:213], v[250:253], v[16:31]
	ds_read_b64_tr_b16 v[210:211], v221 offset:16384
	ds_read_b64_tr_b16 v[212:213], v221 offset:20480
	v_sub_f32_e32 v229, v229, v190
	v_add_f32_e32 v254, v227, v254
	v_exp_f32_e32 v229, v229
	s_nop 0
	s_waitcnt lgkmcnt(8)
	v_mfma_f32_32x32x16_bf16 v[0:15], v[214:217], v[250:253], v[0:15]
	ds_read_b64_tr_b16 v[214:215], v205 offset:16640
	ds_read_b64_tr_b16 v[216:217], v205 offset:20736
	v_cvt_pk_bf16_f32 v242, v222, v223
	v_cvt_pk_bf16_f32 v243, v224, v225
	v_cvt_pk_bf16_f32 v244, v226, v227
	v_cvt_pk_bf16_f32 v245, v228, v229
	s_nop 1
	s_waitcnt lgkmcnt(8)
	v_mfma_f32_32x32x16_bf16 v[112:127], v[238:241], v[242:245], v[112:127]
	ds_read_b64_tr_b16 v[238:239], v218 offset:16640
	ds_read_b64_tr_b16 v[240:241], v218 offset:20736
	v_sub_f32_e32 v230, v230, v190
	v_add_f32_e32 v254, v228, v254
	v_exp_f32_e32 v230, v230
	v_sub_f32_e32 v231, v231, v190
	v_add_f32_e32 v254, v229, v254
	s_waitcnt lgkmcnt(8)
	v_mfma_f32_32x32x16_bf16 v[96:111], v[128:131], v[242:245], v[96:111]
	ds_read_b64_tr_b16 v[128:129], v219 offset:16640
	ds_read_b64_tr_b16 v[130:131], v219 offset:20736
	v_exp_f32_e32 v231, v231
	v_sub_f32_e32 v232, v232, v190
	v_add_f32_e32 v254, v230, v254
	v_exp_f32_e32 v232, v232
	v_sub_f32_e32 v233, v233, v190
	s_cmp_lg_u64 s[18:19], 0
	s_cbranch_scc1 .Latt_nd0_4
	s_sub_i32 s100, s76, 1
	s_cmp_eq_u32 s76, 0
	s_cselect_b32 s100, 2, s100
	s_lshl_b32 s101, s100, 14
	s_add_i32 m0, s73, s101
	s_nop 0
	global_load_lds_dwordx4 v178, s[14:15]

.Latt_rs1_4:
	s_waitcnt lgkmcnt(8)
	v_mfma_f32_32x32x16_bf16 v[80:95], v[214:217], v[250:253], v[80:95]
	ds_read_b64_tr_b16 v[214:215], v221 offset:8448
	ds_read_b64_tr_b16 v[216:217], v221 offset:12544
	s_waitcnt lgkmcnt(8)
	v_mfma_f32_32x32x16_bf16 v[64:79], v[238:241], v[250:253], v[64:79]
	ds_read_b64_tr_b16 v[238:239], v205 offset:16384
	ds_read_b64_tr_b16 v[240:241], v205 offset:20480
	s_waitcnt lgkmcnt(8)
	v_mfma_f32_32x32x16_bf16 v[48:63], v[128:131], v[250:253], v[48:63]
	ds_read_b64_tr_b16 v[128:129], v218 offset:16384
	ds_read_b64_tr_b16 v[130:131], v218 offset:20480
	s_waitcnt lgkmcnt(8)
	v_mfma_f32_32x32x16_bf16 v[32:47], v[206:209], v[250:253], v[32:47]
	ds_read_b64_tr_b16 v[206:207], v219 offset:16384
	ds_read_b64_tr_b16 v[208:209], v219 offset:20480
	s_waitcnt lgkmcnt(8)
	v_mfma_f32_32x32x16_bf16 v[16:31], v[210:213], v[250:253], v[16:31]
	ds_read_b64_tr_b16 v[210:211], v221 offset:16384
	ds_read_b64_tr_b16 v[212:213], v221 offset:20480
	s_waitcnt lgkmcnt(8)
	v_mfma_f32_32x32x16_bf16 v[0:15], v[214:217], v[250:253], v[0:15]
	ds_read_b64_tr_b16 v[214:215], v205 offset:16640
	ds_read_b64_tr_b16 v[216:217], v205 offset:20736
	s_nop 11
	v_max_f32_e32 v246, v190, v246
	v_sub_f32_e32 v190, v190, v246
	v_exp_f32_e32 v190, v190
	s_nop 0
	v_pk_mul_f32 v[126:127], v[126:127], v[190:191] op_sel_hi:[1,0]
	v_pk_mul_f32 v[124:125], v[124:125], v[190:191] op_sel_hi:[1,0]
	v_pk_mul_f32 v[122:123], v[122:123], v[190:191] op_sel_hi:[1,0]
	v_pk_mul_f32 v[120:121], v[120:121], v[190:191] op_sel_hi:[1,0]
	v_pk_mul_f32 v[118:119], v[118:119], v[190:191] op_sel_hi:[1,0]
	v_pk_mul_f32 v[116:117], v[116:117], v[190:191] op_sel_hi:[1,0]
	v_pk_mul_f32 v[114:115], v[114:115], v[190:191] op_sel_hi:[1,0]
	v_pk_mul_f32 v[112:113], v[112:113], v[190:191] op_sel_hi:[1,0]
	v_pk_mul_f32 v[110:111], v[110:111], v[190:191] op_sel_hi:[1,0]
	v_pk_mul_f32 v[108:109], v[108:109], v[190:191] op_sel_hi:[1,0]
	v_pk_mul_f32 v[106:107], v[106:107], v[190:191] op_sel_hi:[1,0]
	v_pk_mul_f32 v[104:105], v[104:105], v[190:191] op_sel_hi:[1,0]
	v_pk_mul_f32 v[102:103], v[102:103], v[190:191] op_sel_hi:[1,0]
	v_pk_mul_f32 v[100:101], v[100:101], v[190:191] op_sel_hi:[1,0]
	v_pk_mul_f32 v[98:99], v[98:99], v[190:191] op_sel_hi:[1,0]
	v_pk_mul_f32 v[96:97], v[96:97], v[190:191] op_sel_hi:[1,0]
	v_pk_mul_f32 v[94:95], v[94:95], v[190:191] op_sel_hi:[1,0]
	v_pk_mul_f32 v[92:93], v[92:93], v[190:191] op_sel_hi:[1,0]
	v_pk_mul_f32 v[90:91], v[90:91], v[190:191] op_sel_hi:[1,0]
	v_pk_mul_f32 v[88:89], v[88:89], v[190:191] op_sel_hi:[1,0]
	v_pk_mul_f32 v[86:87], v[86:87], v[190:191] op_sel_hi:[1,0]
	v_pk_mul_f32 v[84:85], v[84:85], v[190:191] op_sel_hi:[1,0]
	v_pk_mul_f32 v[82:83], v[82:83], v[190:191] op_sel_hi:[1,0]
	v_pk_mul_f32 v[80:81], v[80:81], v[190:191] op_sel_hi:[1,0]
	v_pk_mul_f32 v[78:79], v[78:79], v[190:191] op_sel_hi:[1,0]
	v_pk_mul_f32 v[76:77], v[76:77], v[190:191] op_sel_hi:[1,0]
	v_pk_mul_f32 v[74:75], v[74:75], v[190:191] op_sel_hi:[1,0]
	v_pk_mul_f32 v[72:73], v[72:73], v[190:191] op_sel_hi:[1,0]
	v_pk_mul_f32 v[70:71], v[70:71], v[190:191] op_sel_hi:[1,0]
	v_pk_mul_f32 v[68:69], v[68:69], v[190:191] op_sel_hi:[1,0]
	v_pk_mul_f32 v[66:67], v[66:67], v[190:191] op_sel_hi:[1,0]
	v_pk_mul_f32 v[64:65], v[64:65], v[190:191] op_sel_hi:[1,0]
	v_pk_mul_f32 v[62:63], v[62:63], v[190:191] op_sel_hi:[1,0]
	v_pk_mul_f32 v[60:61], v[60:61], v[190:191] op_sel_hi:[1,0]
	v_pk_mul_f32 v[58:59], v[58:59], v[190:191] op_sel_hi:[1,0]
	v_pk_mul_f32 v[56:57], v[56:57], v[190:191] op_sel_hi:[1,0]
	v_pk_mul_f32 v[54:55], v[54:55], v[190:191] op_sel_hi:[1,0]
	v_pk_mul_f32 v[52:53], v[52:53], v[190:191] op_sel_hi:[1,0]
	v_pk_mul_f32 v[50:51], v[50:51], v[190:191] op_sel_hi:[1,0]
	v_pk_mul_f32 v[48:49], v[48:49], v[190:191] op_sel_hi:[1,0]
	v_pk_mul_f32 v[46:47], v[46:47], v[190:191] op_sel_hi:[1,0]
	v_pk_mul_f32 v[44:45], v[44:45], v[190:191] op_sel_hi:[1,0]
	v_pk_mul_f32 v[42:43], v[42:43], v[190:191] op_sel_hi:[1,0]
	v_pk_mul_f32 v[40:41], v[40:41], v[190:191] op_sel_hi:[1,0]
	v_pk_mul_f32 v[38:39], v[38:39], v[190:191] op_sel_hi:[1,0]
	v_pk_mul_f32 v[36:37], v[36:37], v[190:191] op_sel_hi:[1,0]
	v_pk_mul_f32 v[34:35], v[34:35], v[190:191] op_sel_hi:[1,0]
	v_pk_mul_f32 v[32:33], v[32:33], v[190:191] op_sel_hi:[1,0]
	v_pk_mul_f32 v[30:31], v[30:31], v[190:191] op_sel_hi:[1,0]
	v_pk_mul_f32 v[28:29], v[28:29], v[190:191] op_sel_hi:[1,0]
	v_pk_mul_f32 v[26:27], v[26:27], v[190:191] op_sel_hi:[1,0]
	v_pk_mul_f32 v[24:25], v[24:25], v[190:191] op_sel_hi:[1,0]
	v_pk_mul_f32 v[22:23], v[22:23], v[190:191] op_sel_hi:[1,0]
	v_pk_mul_f32 v[20:21], v[20:21], v[190:191] op_sel_hi:[1,0]
	v_pk_mul_f32 v[18:19], v[18:19], v[190:191] op_sel_hi:[1,0]
	v_pk_mul_f32 v[16:17], v[16:17], v[190:191] op_sel_hi:[1,0]
	v_pk_mul_f32 v[14:15], v[14:15], v[190:191] op_sel_hi:[1,0]
	v_pk_mul_f32 v[12:13], v[12:13], v[190:191] op_sel_hi:[1,0]
	v_pk_mul_f32 v[10:11], v[10:11], v[190:191] op_sel_hi:[1,0]
	v_pk_mul_f32 v[8:9], v[8:9], v[190:191] op_sel_hi:[1,0]
	v_pk_mul_f32 v[6:7], v[6:7], v[190:191] op_sel_hi:[1,0]
	v_pk_mul_f32 v[4:5], v[4:5], v[190:191] op_sel_hi:[1,0]
	v_pk_mul_f32 v[2:3], v[2:3], v[190:191] op_sel_hi:[1,0]
	v_pk_mul_f32 v[0:1], v[0:1], v[190:191] op_sel_hi:[1,0]
	v_mul_f32_e32 v202, v202, v190
	v_mov_b32_e32 v190, v246
	v_sub_f32_e32 v222, v222, v190
	v_exp_f32_e32 v222, v222
	v_sub_f32_e32 v223, v223, v190
	v_exp_f32_e32 v223, v223
	v_sub_f32_e32 v224, v224, v190
	v_add_f32_e32 v254, 0, v222
	v_exp_f32_e32 v224, v224
	v_sub_f32_e32 v225, v225, v190
	v_add_f32_e32 v254, v223, v254
	v_exp_f32_e32 v225, v225
	v_sub_f32_e32 v226, v226, v190
	v_add_f32_e32 v254, v224, v254
	v_exp_f32_e32 v226, v226
	v_sub_f32_e32 v227, v227, v190
	v_add_f32_e32 v254, v225, v254
	v_exp_f32_e32 v227, v227
	v_sub_f32_e32 v228, v228, v190
	v_add_f32_e32 v254, v226, v254
	v_exp_f32_e32 v228, v228
	v_sub_f32_e32 v229, v229, v190
	v_add_f32_e32 v254, v227, v254
	v_exp_f32_e32 v229, v229
	v_sub_f32_e32 v230, v230, v190
	v_add_f32_e32 v254, v228, v254
	v_exp_f32_e32 v230, v230
	v_sub_f32_e32 v231, v231, v190
	v_add_f32_e32 v254, v229, v254
	v_exp_f32_e32 v231, v231
	v_sub_f32_e32 v232, v232, v190
	v_add_f32_e32 v254, v230, v254
	v_exp_f32_e32 v232, v232
	v_sub_f32_e32 v233, v233, v190
	v_add_f32_e32 v254, v231, v254
	v_exp_f32_e32 v233, v233
	v_sub_f32_e32 v234, v234, v190
	v_add_f32_e32 v254, v232, v254
	v_exp_f32_e32 v234, v234
	v_sub_f32_e32 v235, v235, v190
	v_add_f32_e32 v254, v233, v254
	v_exp_f32_e32 v235, v235
	v_sub_f32_e32 v236, v236, v190
	v_add_f32_e32 v254, v234, v254
	v_exp_f32_e32 v236, v236
	v_sub_f32_e32 v237, v237, v190
	v_add_f32_e32 v254, v235, v254
	v_exp_f32_e32 v237, v237
	v_add_f32_e32 v254, v236, v254
	v_add_f32_e32 v254, v237, v254
	v_cvt_pk_bf16_f32 v242, v222, v223
	v_cvt_pk_bf16_f32 v243, v224, v225
	v_cvt_pk_bf16_f32 v244, v226, v227
	v_cvt_pk_bf16_f32 v245, v228, v229
	v_cvt_pk_bf16_f32 v250, v230, v231
	v_cvt_pk_bf16_f32 v251, v232, v233
	v_cvt_pk_bf16_f32 v252, v234, v235
	v_cvt_pk_bf16_f32 v253, v236, v237
	v_add_f32_e32 v202, v202, v254
	s_nop 1
	s_waitcnt lgkmcnt(8)
	v_mfma_f32_32x32x16_bf16 v[112:127], v[238:241], v[242:245], v[112:127]
	ds_read_b64_tr_b16 v[238:239], v218 offset:16640
	ds_read_b64_tr_b16 v[240:241], v218 offset:20736
	s_waitcnt lgkmcnt(8)
	v_mfma_f32_32x32x16_bf16 v[96:111], v[128:131], v[242:245], v[96:111]
	ds_read_b64_tr_b16 v[222:223], v219 offset:16640
	ds_read_b64_tr_b16 v[224:225], v219 offset:20736
	s_cmp_lg_u64 s[18:19], 0
	s_cbranch_scc1 .Latt_ndr0_4
	s_sub_i32 s100, s76, 1
	s_cmp_eq_u32 s76, 0
	s_cselect_b32 s100, 2, s100
	s_lshl_b32 s101, s100, 14
	s_add_i32 m0, s73, s101
	s_nop 0
	global_load_lds_dwordx4 v178, s[14:15]

.Latt_nr0_5:
	s_waitcnt lgkmcnt(3)
	v_mfma_f32_32x32x16_bf16 v[222:237], v[214:217], v[152:155], v[222:237]
	v_add_u32_e32 v214, s98, v202
	ds_read_b128 v[214:217], v214 offset:8192
	v_sub_f32_e32 v128, v128, v190
	v_exp_f32_e32 v128, v128
	v_sub_f32_e32 v129, v129, v190
	v_exp_f32_e32 v129, v129
	v_sub_f32_e32 v130, v130, v190
	s_waitcnt lgkmcnt(3)
	v_mfma_f32_32x32x16_bf16 v[222:237], v[238:241], v[156:159], v[222:237]
	v_add_u32_e32 v238, s98, v203
	ds_read_b128 v[238:241], v238 offset:8192
	v_add_f32_e32 v254, 0, v128
	v_exp_f32_e32 v130, v130
	v_sub_f32_e32 v131, v131, v190
	v_add_f32_e32 v254, v129, v254
	v_exp_f32_e32 v131, v131
	s_waitcnt lgkmcnt(3)
	v_mfma_f32_32x32x16_bf16 v[222:237], v[206:209], v[160:163], v[222:237]
	ds_read_b64_tr_b16 v[206:207], v205
	ds_read_b64_tr_b16 v[208:209], v205 offset:4096
	v_sub_f32_e32 v132, v132, v190
	v_add_f32_e32 v254, v130, v254
	v_exp_f32_e32 v132, v132
	v_sub_f32_e32 v133, v133, v190
	v_add_f32_e32 v254, v131, v254
	s_waitcnt lgkmcnt(4)
	v_mfma_f32_32x32x16_bf16 v[222:237], v[210:213], v[164:167], v[222:237]
	ds_read_b64_tr_b16 v[210:211], v218
	ds_read_b64_tr_b16 v[212:213], v218 offset:4096
	v_exp_f32_e32 v133, v133
	v_sub_f32_e32 v134, v134, v190
	v_add_f32_e32 v254, v132, v254
	v_exp_f32_e32 v134, v134
	s_waitcnt lgkmcnt(5)
	v_mfma_f32_32x32x16_bf16 v[222:237], v[214:217], v[168:171], v[222:237]
	ds_read_b64_tr_b16 v[214:215], v219
	ds_read_b64_tr_b16 v[216:217], v219 offset:4096
	v_sub_f32_e32 v135, v135, v190
	v_add_f32_e32 v254, v133, v254
	v_exp_f32_e32 v135, v135
	s_nop 0
	s_waitcnt lgkmcnt(6)
	v_mfma_f32_32x32x16_bf16 v[222:237], v[238:241], v[172:175], v[222:237]
	ds_read_b64_tr_b16 v[238:239], v221
	ds_read_b64_tr_b16 v[240:241], v221 offset:4096
	v_cvt_pk_bf16_f32 v242, v128, v129
	v_cvt_pk_bf16_f32 v243, v130, v131
	v_cvt_pk_bf16_f32 v244, v132, v133
	v_cvt_pk_bf16_f32 v245, v134, v135
	s_nop 1
	s_waitcnt lgkmcnt(6)
	v_mfma_f32_32x32x16_bf16 v[112:127], v[206:209], v[242:245], v[112:127]
	ds_read_b64_tr_b16 v[206:207], v205 offset:256
	ds_read_b64_tr_b16 v[208:209], v205 offset:4352
	v_sub_f32_e32 v136, v136, v190
	v_add_f32_e32 v254, v134, v254
	v_exp_f32_e32 v136, v136
	v_sub_f32_e32 v137, v137, v190
	v_add_f32_e32 v254, v135, v254
	s_waitcnt lgkmcnt(6)
	v_mfma_f32_32x32x16_bf16 v[96:111], v[210:213], v[242:245], v[96:111]
	ds_read_b64_tr_b16 v[210:211], v218 offset:256
	ds_read_b64_tr_b16 v[212:213], v218 offset:4352
	v_exp_f32_e32 v137, v137
	v_sub_f32_e32 v138, v138, v190
	v_add_f32_e32 v254, v136, v254
	v_exp_f32_e32 v138, v138
	v_sub_f32_e32 v139, v139, v190
	s_waitcnt lgkmcnt(6)
	v_mfma_f32_32x32x16_bf16 v[80:95], v[214:217], v[242:245], v[80:95]
	ds_read_b64_tr_b16 v[214:215], v219 offset:256
	ds_read_b64_tr_b16 v[216:217], v219 offset:4352
	v_add_f32_e32 v254, v137, v254
	v_exp_f32_e32 v139, v139
	v_sub_f32_e32 v140, v140, v190
	v_add_f32_e32 v254, v138, v254
	s_waitcnt lgkmcnt(6)
	v_mfma_f32_32x32x16_bf16 v[64:79], v[238:241], v[242:245], v[64:79]
	ds_read_b64_tr_b16 v[238:239], v221 offset:256
	ds_read_b64_tr_b16 v[240:241], v221 offset:4352
	v_exp_f32_e32 v140, v140
	v_sub_f32_e32 v141, v141, v190
	v_add_f32_e32 v254, v139, v254
	v_exp_f32_e32 v141, v141
	s_waitcnt lgkmcnt(6)
	v_mfma_f32_32x32x16_bf16 v[48:63], v[206:209], v[242:245], v[48:63]
	ds_read_b64_tr_b16 v[206:207], v205 offset:8192
	ds_read_b64_tr_b16 v[208:209], v205 offset:12288
	v_sub_f32_e32 v142, v142, v190
	v_add_f32_e32 v254, v140, v254
	v_exp_f32_e32 v142, v142
	v_sub_f32_e32 v143, v143, v190
	s_waitcnt lgkmcnt(6)
	v_mfma_f32_32x32x16_bf16 v[32:47], v[210:213], v[242:245], v[32:47]
	ds_read_b64_tr_b16 v[210:211], v218 offset:8192
	ds_read_b64_tr_b16 v[212:213], v218 offset:12288
	v_add_f32_e32 v254, v141, v254
	v_exp_f32_e32 v143, v143
	v_add_f32_e32 v254, v142, v254
	v_add_f32_e32 v254, v143, v254
	s_waitcnt lgkmcnt(6)
	v_mfma_f32_32x32x16_bf16 v[16:31], v[214:217], v[242:245], v[16:31]
	ds_read_b64_tr_b16 v[214:215], v219 offset:8192
	ds_read_b64_tr_b16 v[216:217], v219 offset:12288
	v_cvt_pk_bf16_f32 v250, v136, v137
	v_cvt_pk_bf16_f32 v251, v138, v139
	v_cvt_pk_bf16_f32 v252, v140, v141
	v_cvt_pk_bf16_f32 v253, v142, v143
	v_add_f32_e32 v195, v195, v254
	s_waitcnt lgkmcnt(6)
	v_mfma_f32_32x32x16_bf16 v[0:15], v[238:241], v[242:245], v[0:15]
	ds_read_b64_tr_b16 v[238:239], v221 offset:8192
	ds_read_b64_tr_b16 v[240:241], v221 offset:12288
	ds_read_b64_tr_b16 v[128:129], v205 offset:8448
	ds_read_b64_tr_b16 v[130:131], v205 offset:12544
	v_max3_f32 v246, v222, v223, v224
	v_max3_f32 v247, v225, v226, v227
	v_max3_f32 v246, v246, v228, v229
	v_max3_f32 v247, v247, v230, v231
	v_max3_f32 v246, v246, v232, v233
	s_waitcnt lgkmcnt(8)
	v_mfma_f32_32x32x16_bf16 v[112:127], v[206:209], v[250:253], v[112:127]
	ds_read_b64_tr_b16 v[206:207], v218 offset:8448
	ds_read_b64_tr_b16 v[208:209], v218 offset:12544
	v_max3_f32 v247, v247, v234, v235
	v_max3_f32 v246, v246, v236, v237
	v_max_f32_e32 v246, v246, v247
	v_mov_b32_e32 v247, v246
	v_add_f32_e32 v249, 0x41000000, v190
	s_waitcnt lgkmcnt(8)
	v_mfma_f32_32x32x16_bf16 v[96:111], v[210:213], v[250:253], v[96:111]
	ds_read_b64_tr_b16 v[210:211], v219 offset:8448
	ds_read_b64_tr_b16 v[212:213], v219 offset:12544
	s_nop 1
	v_permlane32_swap_b32_e32 v246, v247
	v_max_f32_e32 v246, v246, v247
	v_cmp_gt_f32_e32 vcc, v246, v249
	s_cbranch_vccnz .Latt_rs1_5
	s_waitcnt lgkmcnt(8)
	v_mfma_f32_32x32x16_bf16 v[80:95], v[214:217], v[250:253], v[80:95]
	ds_read_b64_tr_b16 v[214:215], v221 offset:8448
	ds_read_b64_tr_b16 v[216:217], v221 offset:12544
	v_sub_f32_e32 v222, v222, v190
	v_exp_f32_e32 v222, v222
	v_sub_f32_e32 v223, v223, v190
	v_exp_f32_e32 v223, v223
	v_sub_f32_e32 v224, v224, v190
	s_waitcnt lgkmcnt(8)
	v_mfma_f32_32x32x16_bf16 v[64:79], v[238:241], v[250:253], v[64:79]
	ds_read_b64_tr_b16 v[238:239], v205 offset:16384
	ds_read_b64_tr_b16 v[240:241], v205 offset:20480
	v_add_f32_e32 v254, 0, v222
	v_exp_f32_e32 v224, v224
	v_sub_f32_e32 v225, v225, v190
	v_add_f32_e32 v254, v223, v254
	v_exp_f32_e32 v225, v225
	s_waitcnt lgkmcnt(8)
	v_mfma_f32_32x32x16_bf16 v[48:63], v[128:131], v[250:253], v[48:63]
	ds_read_b64_tr_b16 v[128:129], v218 offset:16384
	ds_read_b64_tr_b16 v[130:131], v218 offset:20480
	v_sub_f32_e32 v226, v226, v190
	v_add_f32_e32 v254, v224, v254
	v_exp_f32_e32 v226, v226
	v_sub_f32_e32 v227, v227, v190
	v_add_f32_e32 v254, v225, v254
	s_waitcnt lgkmcnt(8)
	v_mfma_f32_32x32x16_bf16 v[32:47], v[206:209], v[250:253], v[32:47]
	ds_read_b64_tr_b16 v[206:207], v219 offset:16384
	ds_read_b64_tr_b16 v[208:209], v219 offset:20480
	v_exp_f32_e32 v227, v227
	v_sub_f32_e32 v228, v228, v190
	v_add_f32_e32 v254, v226, v254
	v_exp_f32_e32 v228, v228
	s_waitcnt lgkmcnt(8)
	v_mfma_f32_32x32x16_bf16 v[16:31], v[210:213], v[250:253], v[16:31]
	ds_read_b64_tr_b16 v[210:211], v221 offset:16384
	ds_read_b64_tr_b16 v[212:213], v221 offset:20480
	v_sub_f32_e32 v229, v229, v190
	v_add_f32_e32 v254, v227, v254
	v_exp_f32_e32 v229, v229
	s_nop 0
	s_waitcnt lgkmcnt(8)
	v_mfma_f32_32x32x16_bf16 v[0:15], v[214:217], v[250:253], v[0:15]
	ds_read_b64_tr_b16 v[214:215], v205 offset:16640
	ds_read_b64_tr_b16 v[216:217], v205 offset:20736
	v_cvt_pk_bf16_f32 v242, v222, v223
	v_cvt_pk_bf16_f32 v243, v224, v225
	v_cvt_pk_bf16_f32 v244, v226, v227
	v_cvt_pk_bf16_f32 v245, v228, v229
	s_nop 1
	s_waitcnt lgkmcnt(8)
	v_mfma_f32_32x32x16_bf16 v[112:127], v[238:241], v[242:245], v[112:127]
	ds_read_b64_tr_b16 v[238:239], v218 offset:16640
	ds_read_b64_tr_b16 v[240:241], v218 offset:20736
	v_sub_f32_e32 v230, v230, v190
	v_add_f32_e32 v254, v228, v254
	v_exp_f32_e32 v230, v230
	v_sub_f32_e32 v231, v231, v190
	v_add_f32_e32 v254, v229, v254
	s_waitcnt lgkmcnt(8)
	v_mfma_f32_32x32x16_bf16 v[96:111], v[128:131], v[242:245], v[96:111]
	ds_read_b64_tr_b16 v[128:129], v219 offset:16640
	ds_read_b64_tr_b16 v[130:131], v219 offset:20736
	v_exp_f32_e32 v231, v231
	v_sub_f32_e32 v232, v232, v190
	v_add_f32_e32 v254, v230, v254
	v_exp_f32_e32 v232, v232
	v_sub_f32_e32 v233, v233, v190
	s_cmp_lg_u64 s[18:19], 0
	s_cbranch_scc1 .Latt_nd0_5
	s_sub_i32 s100, s33, 1
	s_cmp_eq_u32 s33, 0
	s_cselect_b32 s100, 2, s100
	s_lshl_b32 s101, s100, 14
	s_add_i32 m0, s73, s101
	s_nop 0
	global_load_lds_dwordx4 v178, s[12:13]

.Latt_rs1_5:
	s_waitcnt lgkmcnt(8)
	v_mfma_f32_32x32x16_bf16 v[80:95], v[214:217], v[250:253], v[80:95]
	ds_read_b64_tr_b16 v[214:215], v221 offset:8448
	ds_read_b64_tr_b16 v[216:217], v221 offset:12544
	s_waitcnt lgkmcnt(8)
	v_mfma_f32_32x32x16_bf16 v[64:79], v[238:241], v[250:253], v[64:79]
	ds_read_b64_tr_b16 v[238:239], v205 offset:16384
	ds_read_b64_tr_b16 v[240:241], v205 offset:20480
	s_waitcnt lgkmcnt(8)
	v_mfma_f32_32x32x16_bf16 v[48:63], v[128:131], v[250:253], v[48:63]
	ds_read_b64_tr_b16 v[128:129], v218 offset:16384
	ds_read_b64_tr_b16 v[130:131], v218 offset:20480
	s_waitcnt lgkmcnt(8)
	v_mfma_f32_32x32x16_bf16 v[32:47], v[206:209], v[250:253], v[32:47]
	ds_read_b64_tr_b16 v[206:207], v219 offset:16384
	ds_read_b64_tr_b16 v[208:209], v219 offset:20480
	s_waitcnt lgkmcnt(8)
	v_mfma_f32_32x32x16_bf16 v[16:31], v[210:213], v[250:253], v[16:31]
	ds_read_b64_tr_b16 v[210:211], v221 offset:16384
	ds_read_b64_tr_b16 v[212:213], v221 offset:20480
	s_waitcnt lgkmcnt(8)
	v_mfma_f32_32x32x16_bf16 v[0:15], v[214:217], v[250:253], v[0:15]
	ds_read_b64_tr_b16 v[214:215], v205 offset:16640
	ds_read_b64_tr_b16 v[216:217], v205 offset:20736
	s_nop 11
	v_max_f32_e32 v246, v190, v246
	v_sub_f32_e32 v190, v190, v246
	v_exp_f32_e32 v190, v190
	s_nop 0
	v_pk_mul_f32 v[126:127], v[126:127], v[190:191] op_sel_hi:[1,0]
	v_pk_mul_f32 v[124:125], v[124:125], v[190:191] op_sel_hi:[1,0]
	v_pk_mul_f32 v[122:123], v[122:123], v[190:191] op_sel_hi:[1,0]
	v_pk_mul_f32 v[120:121], v[120:121], v[190:191] op_sel_hi:[1,0]
	v_pk_mul_f32 v[118:119], v[118:119], v[190:191] op_sel_hi:[1,0]
	v_pk_mul_f32 v[116:117], v[116:117], v[190:191] op_sel_hi:[1,0]
	v_pk_mul_f32 v[114:115], v[114:115], v[190:191] op_sel_hi:[1,0]
	v_pk_mul_f32 v[112:113], v[112:113], v[190:191] op_sel_hi:[1,0]
	v_pk_mul_f32 v[110:111], v[110:111], v[190:191] op_sel_hi:[1,0]
	v_pk_mul_f32 v[108:109], v[108:109], v[190:191] op_sel_hi:[1,0]
	v_pk_mul_f32 v[106:107], v[106:107], v[190:191] op_sel_hi:[1,0]
	v_pk_mul_f32 v[104:105], v[104:105], v[190:191] op_sel_hi:[1,0]
	v_pk_mul_f32 v[102:103], v[102:103], v[190:191] op_sel_hi:[1,0]
	v_pk_mul_f32 v[100:101], v[100:101], v[190:191] op_sel_hi:[1,0]
	v_pk_mul_f32 v[98:99], v[98:99], v[190:191] op_sel_hi:[1,0]
	v_pk_mul_f32 v[96:97], v[96:97], v[190:191] op_sel_hi:[1,0]
	v_pk_mul_f32 v[94:95], v[94:95], v[190:191] op_sel_hi:[1,0]
	v_pk_mul_f32 v[92:93], v[92:93], v[190:191] op_sel_hi:[1,0]
	v_pk_mul_f32 v[90:91], v[90:91], v[190:191] op_sel_hi:[1,0]
	v_pk_mul_f32 v[88:89], v[88:89], v[190:191] op_sel_hi:[1,0]
	v_pk_mul_f32 v[86:87], v[86:87], v[190:191] op_sel_hi:[1,0]
	v_pk_mul_f32 v[84:85], v[84:85], v[190:191] op_sel_hi:[1,0]
	v_pk_mul_f32 v[82:83], v[82:83], v[190:191] op_sel_hi:[1,0]
	v_pk_mul_f32 v[80:81], v[80:81], v[190:191] op_sel_hi:[1,0]
	v_pk_mul_f32 v[78:79], v[78:79], v[190:191] op_sel_hi:[1,0]
	v_pk_mul_f32 v[76:77], v[76:77], v[190:191] op_sel_hi:[1,0]
	v_pk_mul_f32 v[74:75], v[74:75], v[190:191] op_sel_hi:[1,0]
	v_pk_mul_f32 v[72:73], v[72:73], v[190:191] op_sel_hi:[1,0]
	v_pk_mul_f32 v[70:71], v[70:71], v[190:191] op_sel_hi:[1,0]
	v_pk_mul_f32 v[68:69], v[68:69], v[190:191] op_sel_hi:[1,0]
	v_pk_mul_f32 v[66:67], v[66:67], v[190:191] op_sel_hi:[1,0]
	v_pk_mul_f32 v[64:65], v[64:65], v[190:191] op_sel_hi:[1,0]
	v_pk_mul_f32 v[62:63], v[62:63], v[190:191] op_sel_hi:[1,0]
	v_pk_mul_f32 v[60:61], v[60:61], v[190:191] op_sel_hi:[1,0]
	v_pk_mul_f32 v[58:59], v[58:59], v[190:191] op_sel_hi:[1,0]
	v_pk_mul_f32 v[56:57], v[56:57], v[190:191] op_sel_hi:[1,0]
	v_pk_mul_f32 v[54:55], v[54:55], v[190:191] op_sel_hi:[1,0]
	v_pk_mul_f32 v[52:53], v[52:53], v[190:191] op_sel_hi:[1,0]
	v_pk_mul_f32 v[50:51], v[50:51], v[190:191] op_sel_hi:[1,0]
	v_pk_mul_f32 v[48:49], v[48:49], v[190:191] op_sel_hi:[1,0]
	v_pk_mul_f32 v[46:47], v[46:47], v[190:191] op_sel_hi:[1,0]
	v_pk_mul_f32 v[44:45], v[44:45], v[190:191] op_sel_hi:[1,0]
	v_pk_mul_f32 v[42:43], v[42:43], v[190:191] op_sel_hi:[1,0]
	v_pk_mul_f32 v[40:41], v[40:41], v[190:191] op_sel_hi:[1,0]
	v_pk_mul_f32 v[38:39], v[38:39], v[190:191] op_sel_hi:[1,0]
	v_pk_mul_f32 v[36:37], v[36:37], v[190:191] op_sel_hi:[1,0]
	v_pk_mul_f32 v[34:35], v[34:35], v[190:191] op_sel_hi:[1,0]
	v_pk_mul_f32 v[32:33], v[32:33], v[190:191] op_sel_hi:[1,0]
	v_pk_mul_f32 v[30:31], v[30:31], v[190:191] op_sel_hi:[1,0]
	v_pk_mul_f32 v[28:29], v[28:29], v[190:191] op_sel_hi:[1,0]
	v_pk_mul_f32 v[26:27], v[26:27], v[190:191] op_sel_hi:[1,0]
	v_pk_mul_f32 v[24:25], v[24:25], v[190:191] op_sel_hi:[1,0]
	v_pk_mul_f32 v[22:23], v[22:23], v[190:191] op_sel_hi:[1,0]
	v_pk_mul_f32 v[20:21], v[20:21], v[190:191] op_sel_hi:[1,0]
	v_pk_mul_f32 v[18:19], v[18:19], v[190:191] op_sel_hi:[1,0]
	v_pk_mul_f32 v[16:17], v[16:17], v[190:191] op_sel_hi:[1,0]
	v_pk_mul_f32 v[14:15], v[14:15], v[190:191] op_sel_hi:[1,0]
	v_pk_mul_f32 v[12:13], v[12:13], v[190:191] op_sel_hi:[1,0]
	v_pk_mul_f32 v[10:11], v[10:11], v[190:191] op_sel_hi:[1,0]
	v_pk_mul_f32 v[8:9], v[8:9], v[190:191] op_sel_hi:[1,0]
	v_pk_mul_f32 v[6:7], v[6:7], v[190:191] op_sel_hi:[1,0]
	v_pk_mul_f32 v[4:5], v[4:5], v[190:191] op_sel_hi:[1,0]
	v_pk_mul_f32 v[2:3], v[2:3], v[190:191] op_sel_hi:[1,0]
	v_pk_mul_f32 v[0:1], v[0:1], v[190:191] op_sel_hi:[1,0]
	v_mul_f32_e32 v195, v195, v190
	v_mov_b32_e32 v190, v246
	v_sub_f32_e32 v222, v222, v190
	v_exp_f32_e32 v222, v222
	v_sub_f32_e32 v223, v223, v190
	v_exp_f32_e32 v223, v223
	v_sub_f32_e32 v224, v224, v190
	v_add_f32_e32 v254, 0, v222
	v_exp_f32_e32 v224, v224
	v_sub_f32_e32 v225, v225, v190
	v_add_f32_e32 v254, v223, v254
	v_exp_f32_e32 v225, v225
	v_sub_f32_e32 v226, v226, v190
	v_add_f32_e32 v254, v224, v254
	v_exp_f32_e32 v226, v226
	v_sub_f32_e32 v227, v227, v190
	v_add_f32_e32 v254, v225, v254
	v_exp_f32_e32 v227, v227
	v_sub_f32_e32 v228, v228, v190
	v_add_f32_e32 v254, v226, v254
	v_exp_f32_e32 v228, v228
	v_sub_f32_e32 v229, v229, v190
	v_add_f32_e32 v254, v227, v254
	v_exp_f32_e32 v229, v229
	v_sub_f32_e32 v230, v230, v190
	v_add_f32_e32 v254, v228, v254
	v_exp_f32_e32 v230, v230
	v_sub_f32_e32 v231, v231, v190
	v_add_f32_e32 v254, v229, v254
	v_exp_f32_e32 v231, v231
	v_sub_f32_e32 v232, v232, v190
	v_add_f32_e32 v254, v230, v254
	v_exp_f32_e32 v232, v232
	v_sub_f32_e32 v233, v233, v190
	v_add_f32_e32 v254, v231, v254
	v_exp_f32_e32 v233, v233
	v_sub_f32_e32 v234, v234, v190
	v_add_f32_e32 v254, v232, v254
	v_exp_f32_e32 v234, v234
	v_sub_f32_e32 v235, v235, v190
	v_add_f32_e32 v254, v233, v254
	v_exp_f32_e32 v235, v235
	v_sub_f32_e32 v236, v236, v190
	v_add_f32_e32 v254, v234, v254
	v_exp_f32_e32 v236, v236
	v_sub_f32_e32 v237, v237, v190
	v_add_f32_e32 v254, v235, v254
	v_exp_f32_e32 v237, v237
	v_add_f32_e32 v254, v236, v254
	v_add_f32_e32 v254, v237, v254
	v_cvt_pk_bf16_f32 v242, v222, v223
	v_cvt_pk_bf16_f32 v243, v224, v225
	v_cvt_pk_bf16_f32 v244, v226, v227
	v_cvt_pk_bf16_f32 v245, v228, v229
	v_cvt_pk_bf16_f32 v250, v230, v231
	v_cvt_pk_bf16_f32 v251, v232, v233
	v_cvt_pk_bf16_f32 v252, v234, v235
	v_cvt_pk_bf16_f32 v253, v236, v237
	v_add_f32_e32 v195, v195, v254
	s_nop 1
	s_waitcnt lgkmcnt(8)
	v_mfma_f32_32x32x16_bf16 v[112:127], v[238:241], v[242:245], v[112:127]
	ds_read_b64_tr_b16 v[238:239], v218 offset:16640
	ds_read_b64_tr_b16 v[240:241], v218 offset:20736
	s_waitcnt lgkmcnt(8)
	v_mfma_f32_32x32x16_bf16 v[96:111], v[128:131], v[242:245], v[96:111]
	ds_read_b64_tr_b16 v[222:223], v219 offset:16640
	ds_read_b64_tr_b16 v[224:225], v219 offset:20736
	s_cmp_lg_u64 s[18:19], 0
	s_cbranch_scc1 .Latt_ndr0_5
	s_sub_i32 s100, s33, 1
	s_cmp_eq_u32 s33, 0
	s_cselect_b32 s100, 2, s100
	s_lshl_b32 s101, s100, 14
	s_add_i32 m0, s73, s101
	s_nop 0
	global_load_lds_dwordx4 v178, s[12:13]

.Latt_nr0_6:
	s_waitcnt lgkmcnt(3)
	v_mfma_f32_32x32x16_bf16 v[222:237], v[214:217], v[152:155], v[222:237]
	v_add_u32_e32 v214, s98, v201
	ds_read_b128 v[214:217], v214 offset:8192
	v_sub_f32_e32 v128, v128, v190
	v_exp_f32_e32 v128, v128
	v_sub_f32_e32 v129, v129, v190
	v_exp_f32_e32 v129, v129
	v_sub_f32_e32 v130, v130, v190
	s_waitcnt lgkmcnt(3)
	v_mfma_f32_32x32x16_bf16 v[222:237], v[238:241], v[156:159], v[222:237]
	v_add_u32_e32 v238, s98, v202
	ds_read_b128 v[238:241], v238 offset:8192
	v_add_f32_e32 v254, 0, v128
	v_exp_f32_e32 v130, v130
	v_sub_f32_e32 v131, v131, v190
	v_add_f32_e32 v254, v129, v254
	v_exp_f32_e32 v131, v131
	s_waitcnt lgkmcnt(3)
	v_mfma_f32_32x32x16_bf16 v[222:237], v[206:209], v[160:163], v[222:237]
	ds_read_b64_tr_b16 v[206:207], v205
	ds_read_b64_tr_b16 v[208:209], v205 offset:4096
	v_sub_f32_e32 v132, v132, v190
	v_add_f32_e32 v254, v130, v254
	v_exp_f32_e32 v132, v132
	v_sub_f32_e32 v133, v133, v190
	v_add_f32_e32 v254, v131, v254
	s_waitcnt lgkmcnt(4)
	v_mfma_f32_32x32x16_bf16 v[222:237], v[210:213], v[164:167], v[222:237]
	ds_read_b64_tr_b16 v[210:211], v218
	ds_read_b64_tr_b16 v[212:213], v218 offset:4096
	v_exp_f32_e32 v133, v133
	v_sub_f32_e32 v134, v134, v190
	v_add_f32_e32 v254, v132, v254
	v_exp_f32_e32 v134, v134
	s_waitcnt lgkmcnt(5)
	v_mfma_f32_32x32x16_bf16 v[222:237], v[214:217], v[168:171], v[222:237]
	ds_read_b64_tr_b16 v[214:215], v219
	ds_read_b64_tr_b16 v[216:217], v219 offset:4096
	v_sub_f32_e32 v135, v135, v190
	v_add_f32_e32 v254, v133, v254
	v_exp_f32_e32 v135, v135
	s_nop 0
	s_waitcnt lgkmcnt(6)
	v_mfma_f32_32x32x16_bf16 v[222:237], v[238:241], v[172:175], v[222:237]
	ds_read_b64_tr_b16 v[238:239], v221
	ds_read_b64_tr_b16 v[240:241], v221 offset:4096
	v_cvt_pk_bf16_f32 v242, v128, v129
	v_cvt_pk_bf16_f32 v243, v130, v131
	v_cvt_pk_bf16_f32 v244, v132, v133
	v_cvt_pk_bf16_f32 v245, v134, v135
	s_nop 1
	s_waitcnt lgkmcnt(6)
	v_mfma_f32_32x32x16_bf16 v[112:127], v[206:209], v[242:245], v[112:127]
	ds_read_b64_tr_b16 v[206:207], v205 offset:256
	ds_read_b64_tr_b16 v[208:209], v205 offset:4352
	v_sub_f32_e32 v136, v136, v190
	v_add_f32_e32 v254, v134, v254
	v_exp_f32_e32 v136, v136
	v_sub_f32_e32 v137, v137, v190
	v_add_f32_e32 v254, v135, v254
	s_waitcnt lgkmcnt(6)
	v_mfma_f32_32x32x16_bf16 v[96:111], v[210:213], v[242:245], v[96:111]
	ds_read_b64_tr_b16 v[210:211], v218 offset:256
	ds_read_b64_tr_b16 v[212:213], v218 offset:4352
	v_exp_f32_e32 v137, v137
	v_sub_f32_e32 v138, v138, v190
	v_add_f32_e32 v254, v136, v254
	v_exp_f32_e32 v138, v138
	v_sub_f32_e32 v139, v139, v190
	s_waitcnt lgkmcnt(6)
	v_mfma_f32_32x32x16_bf16 v[80:95], v[214:217], v[242:245], v[80:95]
	ds_read_b64_tr_b16 v[214:215], v219 offset:256
	ds_read_b64_tr_b16 v[216:217], v219 offset:4352
	v_add_f32_e32 v254, v137, v254
	v_exp_f32_e32 v139, v139
	v_sub_f32_e32 v140, v140, v190
	v_add_f32_e32 v254, v138, v254
	s_waitcnt lgkmcnt(6)
	v_mfma_f32_32x32x16_bf16 v[64:79], v[238:241], v[242:245], v[64:79]
	ds_read_b64_tr_b16 v[238:239], v221 offset:256
	ds_read_b64_tr_b16 v[240:241], v221 offset:4352
	v_exp_f32_e32 v140, v140
	v_sub_f32_e32 v141, v141, v190
	v_add_f32_e32 v254, v139, v254
	v_exp_f32_e32 v141, v141
	s_waitcnt lgkmcnt(6)
	v_mfma_f32_32x32x16_bf16 v[48:63], v[206:209], v[242:245], v[48:63]
	ds_read_b64_tr_b16 v[206:207], v205 offset:8192
	ds_read_b64_tr_b16 v[208:209], v205 offset:12288
	v_sub_f32_e32 v142, v142, v190
	v_add_f32_e32 v254, v140, v254
	v_exp_f32_e32 v142, v142
	v_sub_f32_e32 v143, v143, v190
	s_waitcnt lgkmcnt(6)
	v_mfma_f32_32x32x16_bf16 v[32:47], v[210:213], v[242:245], v[32:47]
	ds_read_b64_tr_b16 v[210:211], v218 offset:8192
	ds_read_b64_tr_b16 v[212:213], v218 offset:12288
	v_add_f32_e32 v254, v141, v254
	v_exp_f32_e32 v143, v143
	v_add_f32_e32 v254, v142, v254
	v_add_f32_e32 v254, v143, v254
	s_waitcnt lgkmcnt(6)
	v_mfma_f32_32x32x16_bf16 v[16:31], v[214:217], v[242:245], v[16:31]
	ds_read_b64_tr_b16 v[214:215], v219 offset:8192
	ds_read_b64_tr_b16 v[216:217], v219 offset:12288
	v_cvt_pk_bf16_f32 v250, v136, v137
	v_cvt_pk_bf16_f32 v251, v138, v139
	v_cvt_pk_bf16_f32 v252, v140, v141
	v_cvt_pk_bf16_f32 v253, v142, v143
	v_add_f32_e32 v203, v203, v254
	s_waitcnt lgkmcnt(6)
	v_mfma_f32_32x32x16_bf16 v[0:15], v[238:241], v[242:245], v[0:15]
	ds_read_b64_tr_b16 v[238:239], v221 offset:8192
	ds_read_b64_tr_b16 v[240:241], v221 offset:12288
	ds_read_b64_tr_b16 v[128:129], v205 offset:8448
	ds_read_b64_tr_b16 v[130:131], v205 offset:12544
	v_max3_f32 v246, v222, v223, v224
	v_max3_f32 v247, v225, v226, v227
	v_max3_f32 v246, v246, v228, v229
	v_max3_f32 v247, v247, v230, v231
	v_max3_f32 v246, v246, v232, v233
	s_waitcnt lgkmcnt(8)
	v_mfma_f32_32x32x16_bf16 v[112:127], v[206:209], v[250:253], v[112:127]
	ds_read_b64_tr_b16 v[206:207], v218 offset:8448
	ds_read_b64_tr_b16 v[208:209], v218 offset:12544
	v_max3_f32 v247, v247, v234, v235
	v_max3_f32 v246, v246, v236, v237
	v_max_f32_e32 v246, v246, v247
	v_mov_b32_e32 v247, v246
	v_add_f32_e32 v249, 0x41000000, v190
	s_waitcnt lgkmcnt(8)
	v_mfma_f32_32x32x16_bf16 v[96:111], v[210:213], v[250:253], v[96:111]
	ds_read_b64_tr_b16 v[210:211], v219 offset:8448
	ds_read_b64_tr_b16 v[212:213], v219 offset:12544
	s_nop 1
	v_permlane32_swap_b32_e32 v246, v247
	v_max_f32_e32 v246, v246, v247
	v_cmp_gt_f32_e32 vcc, v246, v249
	s_cbranch_vccnz .Latt_rs1_6
	s_waitcnt lgkmcnt(8)
	v_mfma_f32_32x32x16_bf16 v[80:95], v[214:217], v[250:253], v[80:95]
	ds_read_b64_tr_b16 v[214:215], v221 offset:8448
	ds_read_b64_tr_b16 v[216:217], v221 offset:12544
	v_sub_f32_e32 v222, v222, v190
	v_exp_f32_e32 v222, v222
	v_sub_f32_e32 v223, v223, v190
	v_exp_f32_e32 v223, v223
	v_sub_f32_e32 v224, v224, v190
	s_waitcnt lgkmcnt(8)
	v_mfma_f32_32x32x16_bf16 v[64:79], v[238:241], v[250:253], v[64:79]
	ds_read_b64_tr_b16 v[238:239], v205 offset:16384
	ds_read_b64_tr_b16 v[240:241], v205 offset:20480
	v_add_f32_e32 v254, 0, v222
	v_exp_f32_e32 v224, v224
	v_sub_f32_e32 v225, v225, v190
	v_add_f32_e32 v254, v223, v254
	v_exp_f32_e32 v225, v225
	s_waitcnt lgkmcnt(8)
	v_mfma_f32_32x32x16_bf16 v[48:63], v[128:131], v[250:253], v[48:63]
	ds_read_b64_tr_b16 v[128:129], v218 offset:16384
	ds_read_b64_tr_b16 v[130:131], v218 offset:20480
	v_sub_f32_e32 v226, v226, v190
	v_add_f32_e32 v254, v224, v254
	v_exp_f32_e32 v226, v226
	v_sub_f32_e32 v227, v227, v190
	v_add_f32_e32 v254, v225, v254
	s_waitcnt lgkmcnt(8)
	v_mfma_f32_32x32x16_bf16 v[32:47], v[206:209], v[250:253], v[32:47]
	ds_read_b64_tr_b16 v[206:207], v219 offset:16384
	ds_read_b64_tr_b16 v[208:209], v219 offset:20480
	v_exp_f32_e32 v227, v227
	v_sub_f32_e32 v228, v228, v190
	v_add_f32_e32 v254, v226, v254
	v_exp_f32_e32 v228, v228
	s_waitcnt lgkmcnt(8)
	v_mfma_f32_32x32x16_bf16 v[16:31], v[210:213], v[250:253], v[16:31]
	ds_read_b64_tr_b16 v[210:211], v221 offset:16384
	ds_read_b64_tr_b16 v[212:213], v221 offset:20480
	v_sub_f32_e32 v229, v229, v190
	v_add_f32_e32 v254, v227, v254
	v_exp_f32_e32 v229, v229
	s_nop 0
	s_waitcnt lgkmcnt(8)
	v_mfma_f32_32x32x16_bf16 v[0:15], v[214:217], v[250:253], v[0:15]
	ds_read_b64_tr_b16 v[214:215], v205 offset:16640
	ds_read_b64_tr_b16 v[216:217], v205 offset:20736
	v_cvt_pk_bf16_f32 v242, v222, v223
	v_cvt_pk_bf16_f32 v243, v224, v225
	v_cvt_pk_bf16_f32 v244, v226, v227
	v_cvt_pk_bf16_f32 v245, v228, v229
	s_nop 1
	s_waitcnt lgkmcnt(8)
	v_mfma_f32_32x32x16_bf16 v[112:127], v[238:241], v[242:245], v[112:127]
	ds_read_b64_tr_b16 v[238:239], v218 offset:16640
	ds_read_b64_tr_b16 v[240:241], v218 offset:20736
	v_sub_f32_e32 v230, v230, v190
	v_add_f32_e32 v254, v228, v254
	v_exp_f32_e32 v230, v230
	v_sub_f32_e32 v231, v231, v190
	v_add_f32_e32 v254, v229, v254
	s_waitcnt lgkmcnt(8)
	v_mfma_f32_32x32x16_bf16 v[96:111], v[128:131], v[242:245], v[96:111]
	ds_read_b64_tr_b16 v[128:129], v219 offset:16640
	ds_read_b64_tr_b16 v[130:131], v219 offset:20736
	v_exp_f32_e32 v231, v231
	v_sub_f32_e32 v232, v232, v190
	v_add_f32_e32 v254, v230, v254
	v_exp_f32_e32 v232, v232
	v_sub_f32_e32 v233, v233, v190
	s_cmp_lg_u64 s[12:13], 0
	s_cbranch_scc1 .Latt_nd0_6
	s_sub_i32 s100, s34, 1
	s_cmp_eq_u32 s34, 0
	s_cselect_b32 s100, 2, s100
	s_lshl_b32 s101, s100, 14
	s_add_i32 m0, s36, s101
	s_nop 0
	global_load_lds_dwordx4 v178, s[20:21]

.Latt_rs1_6:
	s_waitcnt lgkmcnt(8)
	v_mfma_f32_32x32x16_bf16 v[80:95], v[214:217], v[250:253], v[80:95]
	ds_read_b64_tr_b16 v[214:215], v221 offset:8448
	ds_read_b64_tr_b16 v[216:217], v221 offset:12544
	s_waitcnt lgkmcnt(8)
	v_mfma_f32_32x32x16_bf16 v[64:79], v[238:241], v[250:253], v[64:79]
	ds_read_b64_tr_b16 v[238:239], v205 offset:16384
	ds_read_b64_tr_b16 v[240:241], v205 offset:20480
	s_waitcnt lgkmcnt(8)
	v_mfma_f32_32x32x16_bf16 v[48:63], v[128:131], v[250:253], v[48:63]
	ds_read_b64_tr_b16 v[128:129], v218 offset:16384
	ds_read_b64_tr_b16 v[130:131], v218 offset:20480
	s_waitcnt lgkmcnt(8)
	v_mfma_f32_32x32x16_bf16 v[32:47], v[206:209], v[250:253], v[32:47]
	ds_read_b64_tr_b16 v[206:207], v219 offset:16384
	ds_read_b64_tr_b16 v[208:209], v219 offset:20480
	s_waitcnt lgkmcnt(8)
	v_mfma_f32_32x32x16_bf16 v[16:31], v[210:213], v[250:253], v[16:31]
	ds_read_b64_tr_b16 v[210:211], v221 offset:16384
	ds_read_b64_tr_b16 v[212:213], v221 offset:20480
	s_waitcnt lgkmcnt(8)
	v_mfma_f32_32x32x16_bf16 v[0:15], v[214:217], v[250:253], v[0:15]
	ds_read_b64_tr_b16 v[214:215], v205 offset:16640
	ds_read_b64_tr_b16 v[216:217], v205 offset:20736
	s_nop 11
	v_max_f32_e32 v246, v190, v246
	v_sub_f32_e32 v190, v190, v246
	v_exp_f32_e32 v190, v190
	s_nop 0
	v_pk_mul_f32 v[126:127], v[126:127], v[190:191] op_sel_hi:[1,0]
	v_pk_mul_f32 v[124:125], v[124:125], v[190:191] op_sel_hi:[1,0]
	v_pk_mul_f32 v[122:123], v[122:123], v[190:191] op_sel_hi:[1,0]
	v_pk_mul_f32 v[120:121], v[120:121], v[190:191] op_sel_hi:[1,0]
	v_pk_mul_f32 v[118:119], v[118:119], v[190:191] op_sel_hi:[1,0]
	v_pk_mul_f32 v[116:117], v[116:117], v[190:191] op_sel_hi:[1,0]
	v_pk_mul_f32 v[114:115], v[114:115], v[190:191] op_sel_hi:[1,0]
	v_pk_mul_f32 v[112:113], v[112:113], v[190:191] op_sel_hi:[1,0]
	v_pk_mul_f32 v[110:111], v[110:111], v[190:191] op_sel_hi:[1,0]
	v_pk_mul_f32 v[108:109], v[108:109], v[190:191] op_sel_hi:[1,0]
	v_pk_mul_f32 v[106:107], v[106:107], v[190:191] op_sel_hi:[1,0]
	v_pk_mul_f32 v[104:105], v[104:105], v[190:191] op_sel_hi:[1,0]
	v_pk_mul_f32 v[102:103], v[102:103], v[190:191] op_sel_hi:[1,0]
	v_pk_mul_f32 v[100:101], v[100:101], v[190:191] op_sel_hi:[1,0]
	v_pk_mul_f32 v[98:99], v[98:99], v[190:191] op_sel_hi:[1,0]
	v_pk_mul_f32 v[96:97], v[96:97], v[190:191] op_sel_hi:[1,0]
	v_pk_mul_f32 v[94:95], v[94:95], v[190:191] op_sel_hi:[1,0]
	v_pk_mul_f32 v[92:93], v[92:93], v[190:191] op_sel_hi:[1,0]
	v_pk_mul_f32 v[90:91], v[90:91], v[190:191] op_sel_hi:[1,0]
	v_pk_mul_f32 v[88:89], v[88:89], v[190:191] op_sel_hi:[1,0]
	v_pk_mul_f32 v[86:87], v[86:87], v[190:191] op_sel_hi:[1,0]
	v_pk_mul_f32 v[84:85], v[84:85], v[190:191] op_sel_hi:[1,0]
	v_pk_mul_f32 v[82:83], v[82:83], v[190:191] op_sel_hi:[1,0]
	v_pk_mul_f32 v[80:81], v[80:81], v[190:191] op_sel_hi:[1,0]
	v_pk_mul_f32 v[78:79], v[78:79], v[190:191] op_sel_hi:[1,0]
	v_pk_mul_f32 v[76:77], v[76:77], v[190:191] op_sel_hi:[1,0]
	v_pk_mul_f32 v[74:75], v[74:75], v[190:191] op_sel_hi:[1,0]
	v_pk_mul_f32 v[72:73], v[72:73], v[190:191] op_sel_hi:[1,0]
	v_pk_mul_f32 v[70:71], v[70:71], v[190:191] op_sel_hi:[1,0]
	v_pk_mul_f32 v[68:69], v[68:69], v[190:191] op_sel_hi:[1,0]
	v_pk_mul_f32 v[66:67], v[66:67], v[190:191] op_sel_hi:[1,0]
	v_pk_mul_f32 v[64:65], v[64:65], v[190:191] op_sel_hi:[1,0]
	v_pk_mul_f32 v[62:63], v[62:63], v[190:191] op_sel_hi:[1,0]
	v_pk_mul_f32 v[60:61], v[60:61], v[190:191] op_sel_hi:[1,0]
	v_pk_mul_f32 v[58:59], v[58:59], v[190:191] op_sel_hi:[1,0]
	v_pk_mul_f32 v[56:57], v[56:57], v[190:191] op_sel_hi:[1,0]
	v_pk_mul_f32 v[54:55], v[54:55], v[190:191] op_sel_hi:[1,0]
	v_pk_mul_f32 v[52:53], v[52:53], v[190:191] op_sel_hi:[1,0]
	v_pk_mul_f32 v[50:51], v[50:51], v[190:191] op_sel_hi:[1,0]
	v_pk_mul_f32 v[48:49], v[48:49], v[190:191] op_sel_hi:[1,0]
	v_pk_mul_f32 v[46:47], v[46:47], v[190:191] op_sel_hi:[1,0]
	v_pk_mul_f32 v[44:45], v[44:45], v[190:191] op_sel_hi:[1,0]
	v_pk_mul_f32 v[42:43], v[42:43], v[190:191] op_sel_hi:[1,0]
	v_pk_mul_f32 v[40:41], v[40:41], v[190:191] op_sel_hi:[1,0]
	v_pk_mul_f32 v[38:39], v[38:39], v[190:191] op_sel_hi:[1,0]
	v_pk_mul_f32 v[36:37], v[36:37], v[190:191] op_sel_hi:[1,0]
	v_pk_mul_f32 v[34:35], v[34:35], v[190:191] op_sel_hi:[1,0]
	v_pk_mul_f32 v[32:33], v[32:33], v[190:191] op_sel_hi:[1,0]
	v_pk_mul_f32 v[30:31], v[30:31], v[190:191] op_sel_hi:[1,0]
	v_pk_mul_f32 v[28:29], v[28:29], v[190:191] op_sel_hi:[1,0]
	v_pk_mul_f32 v[26:27], v[26:27], v[190:191] op_sel_hi:[1,0]
	v_pk_mul_f32 v[24:25], v[24:25], v[190:191] op_sel_hi:[1,0]
	v_pk_mul_f32 v[22:23], v[22:23], v[190:191] op_sel_hi:[1,0]
	v_pk_mul_f32 v[20:21], v[20:21], v[190:191] op_sel_hi:[1,0]
	v_pk_mul_f32 v[18:19], v[18:19], v[190:191] op_sel_hi:[1,0]
	v_pk_mul_f32 v[16:17], v[16:17], v[190:191] op_sel_hi:[1,0]
	v_pk_mul_f32 v[14:15], v[14:15], v[190:191] op_sel_hi:[1,0]
	v_pk_mul_f32 v[12:13], v[12:13], v[190:191] op_sel_hi:[1,0]
	v_pk_mul_f32 v[10:11], v[10:11], v[190:191] op_sel_hi:[1,0]
	v_pk_mul_f32 v[8:9], v[8:9], v[190:191] op_sel_hi:[1,0]
	v_pk_mul_f32 v[6:7], v[6:7], v[190:191] op_sel_hi:[1,0]
	v_pk_mul_f32 v[4:5], v[4:5], v[190:191] op_sel_hi:[1,0]
	v_pk_mul_f32 v[2:3], v[2:3], v[190:191] op_sel_hi:[1,0]
	v_pk_mul_f32 v[0:1], v[0:1], v[190:191] op_sel_hi:[1,0]
	v_mul_f32_e32 v203, v203, v190
	v_mov_b32_e32 v190, v246
	v_sub_f32_e32 v222, v222, v190
	v_exp_f32_e32 v222, v222
	v_sub_f32_e32 v223, v223, v190
	v_exp_f32_e32 v223, v223
	v_sub_f32_e32 v224, v224, v190
	v_add_f32_e32 v254, 0, v222
	v_exp_f32_e32 v224, v224
	v_sub_f32_e32 v225, v225, v190
	v_add_f32_e32 v254, v223, v254
	v_exp_f32_e32 v225, v225
	v_sub_f32_e32 v226, v226, v190
	v_add_f32_e32 v254, v224, v254
	v_exp_f32_e32 v226, v226
	v_sub_f32_e32 v227, v227, v190
	v_add_f32_e32 v254, v225, v254
	v_exp_f32_e32 v227, v227
	v_sub_f32_e32 v228, v228, v190
	v_add_f32_e32 v254, v226, v254
	v_exp_f32_e32 v228, v228
	v_sub_f32_e32 v229, v229, v190
	v_add_f32_e32 v254, v227, v254
	v_exp_f32_e32 v229, v229
	v_sub_f32_e32 v230, v230, v190
	v_add_f32_e32 v254, v228, v254
	v_exp_f32_e32 v230, v230
	v_sub_f32_e32 v231, v231, v190
	v_add_f32_e32 v254, v229, v254
	v_exp_f32_e32 v231, v231
	v_sub_f32_e32 v232, v232, v190
	v_add_f32_e32 v254, v230, v254
	v_exp_f32_e32 v232, v232
	v_sub_f32_e32 v233, v233, v190
	v_add_f32_e32 v254, v231, v254
	v_exp_f32_e32 v233, v233
	v_sub_f32_e32 v234, v234, v190
	v_add_f32_e32 v254, v232, v254
	v_exp_f32_e32 v234, v234
	v_sub_f32_e32 v235, v235, v190
	v_add_f32_e32 v254, v233, v254
	v_exp_f32_e32 v235, v235
	v_sub_f32_e32 v236, v236, v190
	v_add_f32_e32 v254, v234, v254
	v_exp_f32_e32 v236, v236
	v_sub_f32_e32 v237, v237, v190
	v_add_f32_e32 v254, v235, v254
	v_exp_f32_e32 v237, v237
	v_add_f32_e32 v254, v236, v254
	v_add_f32_e32 v254, v237, v254
	v_cvt_pk_bf16_f32 v242, v222, v223
	v_cvt_pk_bf16_f32 v243, v224, v225
	v_cvt_pk_bf16_f32 v244, v226, v227
	v_cvt_pk_bf16_f32 v245, v228, v229
	v_cvt_pk_bf16_f32 v250, v230, v231
	v_cvt_pk_bf16_f32 v251, v232, v233
	v_cvt_pk_bf16_f32 v252, v234, v235
	v_cvt_pk_bf16_f32 v253, v236, v237
	v_add_f32_e32 v203, v203, v254
	s_nop 1
	s_waitcnt lgkmcnt(8)
	v_mfma_f32_32x32x16_bf16 v[112:127], v[238:241], v[242:245], v[112:127]
	ds_read_b64_tr_b16 v[238:239], v218 offset:16640
	ds_read_b64_tr_b16 v[240:241], v218 offset:20736
	s_waitcnt lgkmcnt(8)
	v_mfma_f32_32x32x16_bf16 v[96:111], v[128:131], v[242:245], v[96:111]
	ds_read_b64_tr_b16 v[222:223], v219 offset:16640
	ds_read_b64_tr_b16 v[224:225], v219 offset:20736
	s_cmp_lg_u64 s[12:13], 0
	s_cbranch_scc1 .Latt_ndr0_6
	s_sub_i32 s100, s34, 1
	s_cmp_eq_u32 s34, 0
	s_cselect_b32 s100, 2, s100
	s_lshl_b32 s101, s100, 14
	s_add_i32 m0, s36, s101
	s_nop 0
	global_load_lds_dwordx4 v178, s[20:21]

.Latt_nr0_7:
	s_waitcnt lgkmcnt(3)
	v_mfma_f32_32x32x16_bf16 v[222:237], v[214:217], v[152:155], v[222:237]
	v_add_u32_e32 v214, s98, v202
	ds_read_b128 v[214:217], v214 offset:8192
	v_sub_f32_e32 v128, v128, v190
	v_exp_f32_e32 v128, v128
	v_sub_f32_e32 v129, v129, v190
	v_exp_f32_e32 v129, v129
	v_sub_f32_e32 v130, v130, v190
	s_waitcnt lgkmcnt(3)
	v_mfma_f32_32x32x16_bf16 v[222:237], v[238:241], v[156:159], v[222:237]
	v_add_u32_e32 v238, s98, v203
	ds_read_b128 v[238:241], v238 offset:8192
	v_add_f32_e32 v254, 0, v128
	v_exp_f32_e32 v130, v130
	v_sub_f32_e32 v131, v131, v190
	v_add_f32_e32 v254, v129, v254
	v_exp_f32_e32 v131, v131
	s_waitcnt lgkmcnt(3)
	v_mfma_f32_32x32x16_bf16 v[222:237], v[206:209], v[160:163], v[222:237]
	ds_read_b64_tr_b16 v[206:207], v205
	ds_read_b64_tr_b16 v[208:209], v205 offset:4096
	v_sub_f32_e32 v132, v132, v190
	v_add_f32_e32 v254, v130, v254
	v_exp_f32_e32 v132, v132
	v_sub_f32_e32 v133, v133, v190
	v_add_f32_e32 v254, v131, v254
	s_waitcnt lgkmcnt(4)
	v_mfma_f32_32x32x16_bf16 v[222:237], v[210:213], v[164:167], v[222:237]
	ds_read_b64_tr_b16 v[210:211], v218
	ds_read_b64_tr_b16 v[212:213], v218 offset:4096
	v_exp_f32_e32 v133, v133
	v_sub_f32_e32 v134, v134, v190
	v_add_f32_e32 v254, v132, v254
	v_exp_f32_e32 v134, v134
	s_waitcnt lgkmcnt(5)
	v_mfma_f32_32x32x16_bf16 v[222:237], v[214:217], v[168:171], v[222:237]
	ds_read_b64_tr_b16 v[214:215], v219
	ds_read_b64_tr_b16 v[216:217], v219 offset:4096
	v_sub_f32_e32 v135, v135, v190
	v_add_f32_e32 v254, v133, v254
	v_exp_f32_e32 v135, v135
	s_nop 0
	s_waitcnt lgkmcnt(6)
	v_mfma_f32_32x32x16_bf16 v[222:237], v[238:241], v[172:175], v[222:237]
	ds_read_b64_tr_b16 v[238:239], v221
	ds_read_b64_tr_b16 v[240:241], v221 offset:4096
	v_cvt_pk_bf16_f32 v242, v128, v129
	v_cvt_pk_bf16_f32 v243, v130, v131
	v_cvt_pk_bf16_f32 v244, v132, v133
	v_cvt_pk_bf16_f32 v245, v134, v135
	s_nop 1
	s_waitcnt lgkmcnt(6)
	v_mfma_f32_32x32x16_bf16 v[112:127], v[206:209], v[242:245], v[112:127]
	ds_read_b64_tr_b16 v[206:207], v205 offset:256
	ds_read_b64_tr_b16 v[208:209], v205 offset:4352
	v_sub_f32_e32 v136, v136, v190
	v_add_f32_e32 v254, v134, v254
	v_exp_f32_e32 v136, v136
	v_sub_f32_e32 v137, v137, v190
	v_add_f32_e32 v254, v135, v254
	s_waitcnt lgkmcnt(6)
	v_mfma_f32_32x32x16_bf16 v[96:111], v[210:213], v[242:245], v[96:111]
	ds_read_b64_tr_b16 v[210:211], v218 offset:256
	ds_read_b64_tr_b16 v[212:213], v218 offset:4352
	v_exp_f32_e32 v137, v137
	v_sub_f32_e32 v138, v138, v190
	v_add_f32_e32 v254, v136, v254
	v_exp_f32_e32 v138, v138
	v_sub_f32_e32 v139, v139, v190
	s_waitcnt lgkmcnt(6)
	v_mfma_f32_32x32x16_bf16 v[80:95], v[214:217], v[242:245], v[80:95]
	ds_read_b64_tr_b16 v[214:215], v219 offset:256
	ds_read_b64_tr_b16 v[216:217], v219 offset:4352
	v_add_f32_e32 v254, v137, v254
	v_exp_f32_e32 v139, v139
	v_sub_f32_e32 v140, v140, v190
	v_add_f32_e32 v254, v138, v254
	s_waitcnt lgkmcnt(6)
	v_mfma_f32_32x32x16_bf16 v[64:79], v[238:241], v[242:245], v[64:79]
	ds_read_b64_tr_b16 v[238:239], v221 offset:256
	ds_read_b64_tr_b16 v[240:241], v221 offset:4352
	v_exp_f32_e32 v140, v140
	v_sub_f32_e32 v141, v141, v190
	v_add_f32_e32 v254, v139, v254
	v_exp_f32_e32 v141, v141
	s_waitcnt lgkmcnt(6)
	v_mfma_f32_32x32x16_bf16 v[48:63], v[206:209], v[242:245], v[48:63]
	ds_read_b64_tr_b16 v[206:207], v205 offset:8192
	ds_read_b64_tr_b16 v[208:209], v205 offset:12288
	v_sub_f32_e32 v142, v142, v190
	v_add_f32_e32 v254, v140, v254
	v_exp_f32_e32 v142, v142
	v_sub_f32_e32 v143, v143, v190
	s_waitcnt lgkmcnt(6)
	v_mfma_f32_32x32x16_bf16 v[32:47], v[210:213], v[242:245], v[32:47]
	ds_read_b64_tr_b16 v[210:211], v218 offset:8192
	ds_read_b64_tr_b16 v[212:213], v218 offset:12288
	v_add_f32_e32 v254, v141, v254
	v_exp_f32_e32 v143, v143
	v_add_f32_e32 v254, v142, v254
	v_add_f32_e32 v254, v143, v254
	s_waitcnt lgkmcnt(6)
	v_mfma_f32_32x32x16_bf16 v[16:31], v[214:217], v[242:245], v[16:31]
	ds_read_b64_tr_b16 v[214:215], v219 offset:8192
	ds_read_b64_tr_b16 v[216:217], v219 offset:12288
	v_cvt_pk_bf16_f32 v250, v136, v137
	v_cvt_pk_bf16_f32 v251, v138, v139
	v_cvt_pk_bf16_f32 v252, v140, v141
	v_cvt_pk_bf16_f32 v253, v142, v143
	v_add_f32_e32 v195, v195, v254
	s_waitcnt lgkmcnt(6)
	v_mfma_f32_32x32x16_bf16 v[0:15], v[238:241], v[242:245], v[0:15]
	ds_read_b64_tr_b16 v[238:239], v221 offset:8192
	ds_read_b64_tr_b16 v[240:241], v221 offset:12288
	ds_read_b64_tr_b16 v[128:129], v205 offset:8448
	ds_read_b64_tr_b16 v[130:131], v205 offset:12544
	v_max3_f32 v246, v222, v223, v224
	v_max3_f32 v247, v225, v226, v227
	v_max3_f32 v246, v246, v228, v229
	v_max3_f32 v247, v247, v230, v231
	v_max3_f32 v246, v246, v232, v233
	s_waitcnt lgkmcnt(8)
	v_mfma_f32_32x32x16_bf16 v[112:127], v[206:209], v[250:253], v[112:127]
	ds_read_b64_tr_b16 v[206:207], v218 offset:8448
	ds_read_b64_tr_b16 v[208:209], v218 offset:12544
	v_max3_f32 v247, v247, v234, v235
	v_max3_f32 v246, v246, v236, v237
	v_max_f32_e32 v246, v246, v247
	v_mov_b32_e32 v247, v246
	v_add_f32_e32 v249, 0x41000000, v190
	s_waitcnt lgkmcnt(8)
	v_mfma_f32_32x32x16_bf16 v[96:111], v[210:213], v[250:253], v[96:111]
	ds_read_b64_tr_b16 v[210:211], v219 offset:8448
	ds_read_b64_tr_b16 v[212:213], v219 offset:12544
	s_nop 1
	v_permlane32_swap_b32_e32 v246, v247
	v_max_f32_e32 v246, v246, v247
	v_cmp_gt_f32_e32 vcc, v246, v249
	s_cbranch_vccnz .Latt_rs1_7
	s_waitcnt lgkmcnt(8)
	v_mfma_f32_32x32x16_bf16 v[80:95], v[214:217], v[250:253], v[80:95]
	ds_read_b64_tr_b16 v[214:215], v221 offset:8448
	ds_read_b64_tr_b16 v[216:217], v221 offset:12544
	v_sub_f32_e32 v222, v222, v190
	v_exp_f32_e32 v222, v222
	v_sub_f32_e32 v223, v223, v190
	v_exp_f32_e32 v223, v223
	v_sub_f32_e32 v224, v224, v190
	s_waitcnt lgkmcnt(8)
	v_mfma_f32_32x32x16_bf16 v[64:79], v[238:241], v[250:253], v[64:79]
	ds_read_b64_tr_b16 v[238:239], v205 offset:16384
	ds_read_b64_tr_b16 v[240:241], v205 offset:20480
	v_add_f32_e32 v254, 0, v222
	v_exp_f32_e32 v224, v224
	v_sub_f32_e32 v225, v225, v190
	v_add_f32_e32 v254, v223, v254
	v_exp_f32_e32 v225, v225
	s_waitcnt lgkmcnt(8)
	v_mfma_f32_32x32x16_bf16 v[48:63], v[128:131], v[250:253], v[48:63]
	ds_read_b64_tr_b16 v[128:129], v218 offset:16384
	ds_read_b64_tr_b16 v[130:131], v218 offset:20480
	v_sub_f32_e32 v226, v226, v190
	v_add_f32_e32 v254, v224, v254
	v_exp_f32_e32 v226, v226
	v_sub_f32_e32 v227, v227, v190
	v_add_f32_e32 v254, v225, v254
	s_waitcnt lgkmcnt(8)
	v_mfma_f32_32x32x16_bf16 v[32:47], v[206:209], v[250:253], v[32:47]
	ds_read_b64_tr_b16 v[206:207], v219 offset:16384
	ds_read_b64_tr_b16 v[208:209], v219 offset:20480
	v_exp_f32_e32 v227, v227
	v_sub_f32_e32 v228, v228, v190
	v_add_f32_e32 v254, v226, v254
	v_exp_f32_e32 v228, v228
	s_waitcnt lgkmcnt(8)
	v_mfma_f32_32x32x16_bf16 v[16:31], v[210:213], v[250:253], v[16:31]
	ds_read_b64_tr_b16 v[210:211], v221 offset:16384
	ds_read_b64_tr_b16 v[212:213], v221 offset:20480
	v_sub_f32_e32 v229, v229, v190
	v_add_f32_e32 v254, v227, v254
	v_exp_f32_e32 v229, v229
	s_nop 0
	s_waitcnt lgkmcnt(8)
	v_mfma_f32_32x32x16_bf16 v[0:15], v[214:217], v[250:253], v[0:15]
	ds_read_b64_tr_b16 v[214:215], v205 offset:16640
	ds_read_b64_tr_b16 v[216:217], v205 offset:20736
	v_cvt_pk_bf16_f32 v242, v222, v223
	v_cvt_pk_bf16_f32 v243, v224, v225
	v_cvt_pk_bf16_f32 v244, v226, v227
	v_cvt_pk_bf16_f32 v245, v228, v229
	s_nop 1
	s_waitcnt lgkmcnt(8)
	v_mfma_f32_32x32x16_bf16 v[112:127], v[238:241], v[242:245], v[112:127]
	ds_read_b64_tr_b16 v[238:239], v218 offset:16640
	ds_read_b64_tr_b16 v[240:241], v218 offset:20736
	v_sub_f32_e32 v230, v230, v190
	v_add_f32_e32 v254, v228, v254
	v_exp_f32_e32 v230, v230
	v_sub_f32_e32 v231, v231, v190
	v_add_f32_e32 v254, v229, v254
	s_waitcnt lgkmcnt(8)
	v_mfma_f32_32x32x16_bf16 v[96:111], v[128:131], v[242:245], v[96:111]
	ds_read_b64_tr_b16 v[128:129], v219 offset:16640
	ds_read_b64_tr_b16 v[130:131], v219 offset:20736
	v_exp_f32_e32 v231, v231
	v_sub_f32_e32 v232, v232, v190
	v_add_f32_e32 v254, v230, v254
	v_exp_f32_e32 v232, v232
	v_sub_f32_e32 v233, v233, v190
	s_cmp_lg_u64 s[8:9], 0
	s_cbranch_scc1 .Latt_nd0_7
	s_sub_i32 s100, s11, 1
	s_cmp_eq_u32 s11, 0
	s_cselect_b32 s100, 2, s100
	s_lshl_b32 s101, s100, 14
	s_add_i32 m0, s36, s101
	s_nop 0
	global_load_lds_dwordx4 v178, s[22:23]

.Latt_rs1_7:
	s_waitcnt lgkmcnt(8)
	v_mfma_f32_32x32x16_bf16 v[80:95], v[214:217], v[250:253], v[80:95]
	ds_read_b64_tr_b16 v[214:215], v221 offset:8448
	ds_read_b64_tr_b16 v[216:217], v221 offset:12544
	s_waitcnt lgkmcnt(8)
	v_mfma_f32_32x32x16_bf16 v[64:79], v[238:241], v[250:253], v[64:79]
	ds_read_b64_tr_b16 v[238:239], v205 offset:16384
	ds_read_b64_tr_b16 v[240:241], v205 offset:20480
	s_waitcnt lgkmcnt(8)
	v_mfma_f32_32x32x16_bf16 v[48:63], v[128:131], v[250:253], v[48:63]
	ds_read_b64_tr_b16 v[128:129], v218 offset:16384
	ds_read_b64_tr_b16 v[130:131], v218 offset:20480
	s_waitcnt lgkmcnt(8)
	v_mfma_f32_32x32x16_bf16 v[32:47], v[206:209], v[250:253], v[32:47]
	ds_read_b64_tr_b16 v[206:207], v219 offset:16384
	ds_read_b64_tr_b16 v[208:209], v219 offset:20480
	s_waitcnt lgkmcnt(8)
	v_mfma_f32_32x32x16_bf16 v[16:31], v[210:213], v[250:253], v[16:31]
	ds_read_b64_tr_b16 v[210:211], v221 offset:16384
	ds_read_b64_tr_b16 v[212:213], v221 offset:20480
	s_waitcnt lgkmcnt(8)
	v_mfma_f32_32x32x16_bf16 v[0:15], v[214:217], v[250:253], v[0:15]
	ds_read_b64_tr_b16 v[214:215], v205 offset:16640
	ds_read_b64_tr_b16 v[216:217], v205 offset:20736
	s_nop 11
	v_max_f32_e32 v246, v190, v246
	v_sub_f32_e32 v190, v190, v246
	v_exp_f32_e32 v190, v190
	s_nop 0
	v_pk_mul_f32 v[126:127], v[126:127], v[190:191] op_sel_hi:[1,0]
	v_pk_mul_f32 v[124:125], v[124:125], v[190:191] op_sel_hi:[1,0]
	v_pk_mul_f32 v[122:123], v[122:123], v[190:191] op_sel_hi:[1,0]
	v_pk_mul_f32 v[120:121], v[120:121], v[190:191] op_sel_hi:[1,0]
	v_pk_mul_f32 v[118:119], v[118:119], v[190:191] op_sel_hi:[1,0]
	v_pk_mul_f32 v[116:117], v[116:117], v[190:191] op_sel_hi:[1,0]
	v_pk_mul_f32 v[114:115], v[114:115], v[190:191] op_sel_hi:[1,0]
	v_pk_mul_f32 v[112:113], v[112:113], v[190:191] op_sel_hi:[1,0]
	v_pk_mul_f32 v[110:111], v[110:111], v[190:191] op_sel_hi:[1,0]
	v_pk_mul_f32 v[108:109], v[108:109], v[190:191] op_sel_hi:[1,0]
	v_pk_mul_f32 v[106:107], v[106:107], v[190:191] op_sel_hi:[1,0]
	v_pk_mul_f32 v[104:105], v[104:105], v[190:191] op_sel_hi:[1,0]
	v_pk_mul_f32 v[102:103], v[102:103], v[190:191] op_sel_hi:[1,0]
	v_pk_mul_f32 v[100:101], v[100:101], v[190:191] op_sel_hi:[1,0]
	v_pk_mul_f32 v[98:99], v[98:99], v[190:191] op_sel_hi:[1,0]
	v_pk_mul_f32 v[96:97], v[96:97], v[190:191] op_sel_hi:[1,0]
	v_pk_mul_f32 v[94:95], v[94:95], v[190:191] op_sel_hi:[1,0]
	v_pk_mul_f32 v[92:93], v[92:93], v[190:191] op_sel_hi:[1,0]
	v_pk_mul_f32 v[90:91], v[90:91], v[190:191] op_sel_hi:[1,0]
	v_pk_mul_f32 v[88:89], v[88:89], v[190:191] op_sel_hi:[1,0]
	v_pk_mul_f32 v[86:87], v[86:87], v[190:191] op_sel_hi:[1,0]
	v_pk_mul_f32 v[84:85], v[84:85], v[190:191] op_sel_hi:[1,0]
	v_pk_mul_f32 v[82:83], v[82:83], v[190:191] op_sel_hi:[1,0]
	v_pk_mul_f32 v[80:81], v[80:81], v[190:191] op_sel_hi:[1,0]
	v_pk_mul_f32 v[78:79], v[78:79], v[190:191] op_sel_hi:[1,0]
	v_pk_mul_f32 v[76:77], v[76:77], v[190:191] op_sel_hi:[1,0]
	v_pk_mul_f32 v[74:75], v[74:75], v[190:191] op_sel_hi:[1,0]
	v_pk_mul_f32 v[72:73], v[72:73], v[190:191] op_sel_hi:[1,0]
	v_pk_mul_f32 v[70:71], v[70:71], v[190:191] op_sel_hi:[1,0]
	v_pk_mul_f32 v[68:69], v[68:69], v[190:191] op_sel_hi:[1,0]
	v_pk_mul_f32 v[66:67], v[66:67], v[190:191] op_sel_hi:[1,0]
	v_pk_mul_f32 v[64:65], v[64:65], v[190:191] op_sel_hi:[1,0]
	v_pk_mul_f32 v[62:63], v[62:63], v[190:191] op_sel_hi:[1,0]
	v_pk_mul_f32 v[60:61], v[60:61], v[190:191] op_sel_hi:[1,0]
	v_pk_mul_f32 v[58:59], v[58:59], v[190:191] op_sel_hi:[1,0]
	v_pk_mul_f32 v[56:57], v[56:57], v[190:191] op_sel_hi:[1,0]
	v_pk_mul_f32 v[54:55], v[54:55], v[190:191] op_sel_hi:[1,0]
	v_pk_mul_f32 v[52:53], v[52:53], v[190:191] op_sel_hi:[1,0]
	v_pk_mul_f32 v[50:51], v[50:51], v[190:191] op_sel_hi:[1,0]
	v_pk_mul_f32 v[48:49], v[48:49], v[190:191] op_sel_hi:[1,0]
	v_pk_mul_f32 v[46:47], v[46:47], v[190:191] op_sel_hi:[1,0]
	v_pk_mul_f32 v[44:45], v[44:45], v[190:191] op_sel_hi:[1,0]
	v_pk_mul_f32 v[42:43], v[42:43], v[190:191] op_sel_hi:[1,0]
	v_pk_mul_f32 v[40:41], v[40:41], v[190:191] op_sel_hi:[1,0]
	v_pk_mul_f32 v[38:39], v[38:39], v[190:191] op_sel_hi:[1,0]
	v_pk_mul_f32 v[36:37], v[36:37], v[190:191] op_sel_hi:[1,0]
	v_pk_mul_f32 v[34:35], v[34:35], v[190:191] op_sel_hi:[1,0]
	v_pk_mul_f32 v[32:33], v[32:33], v[190:191] op_sel_hi:[1,0]
	v_pk_mul_f32 v[30:31], v[30:31], v[190:191] op_sel_hi:[1,0]
	v_pk_mul_f32 v[28:29], v[28:29], v[190:191] op_sel_hi:[1,0]
	v_pk_mul_f32 v[26:27], v[26:27], v[190:191] op_sel_hi:[1,0]
	v_pk_mul_f32 v[24:25], v[24:25], v[190:191] op_sel_hi:[1,0]
	v_pk_mul_f32 v[22:23], v[22:23], v[190:191] op_sel_hi:[1,0]
	v_pk_mul_f32 v[20:21], v[20:21], v[190:191] op_sel_hi:[1,0]
	v_pk_mul_f32 v[18:19], v[18:19], v[190:191] op_sel_hi:[1,0]
	v_pk_mul_f32 v[16:17], v[16:17], v[190:191] op_sel_hi:[1,0]
	v_pk_mul_f32 v[14:15], v[14:15], v[190:191] op_sel_hi:[1,0]
	v_pk_mul_f32 v[12:13], v[12:13], v[190:191] op_sel_hi:[1,0]
	v_pk_mul_f32 v[10:11], v[10:11], v[190:191] op_sel_hi:[1,0]
	v_pk_mul_f32 v[8:9], v[8:9], v[190:191] op_sel_hi:[1,0]
	v_pk_mul_f32 v[6:7], v[6:7], v[190:191] op_sel_hi:[1,0]
	v_pk_mul_f32 v[4:5], v[4:5], v[190:191] op_sel_hi:[1,0]
	v_pk_mul_f32 v[2:3], v[2:3], v[190:191] op_sel_hi:[1,0]
	v_pk_mul_f32 v[0:1], v[0:1], v[190:191] op_sel_hi:[1,0]
	v_mul_f32_e32 v195, v195, v190
	v_mov_b32_e32 v190, v246
	v_sub_f32_e32 v222, v222, v190
	v_exp_f32_e32 v222, v222
	v_sub_f32_e32 v223, v223, v190
	v_exp_f32_e32 v223, v223
	v_sub_f32_e32 v224, v224, v190
	v_add_f32_e32 v254, 0, v222
	v_exp_f32_e32 v224, v224
	v_sub_f32_e32 v225, v225, v190
	v_add_f32_e32 v254, v223, v254
	v_exp_f32_e32 v225, v225
	v_sub_f32_e32 v226, v226, v190
	v_add_f32_e32 v254, v224, v254
	v_exp_f32_e32 v226, v226
	v_sub_f32_e32 v227, v227, v190
	v_add_f32_e32 v254, v225, v254
	v_exp_f32_e32 v227, v227
	v_sub_f32_e32 v228, v228, v190
	v_add_f32_e32 v254, v226, v254
	v_exp_f32_e32 v228, v228
	v_sub_f32_e32 v229, v229, v190
	v_add_f32_e32 v254, v227, v254
	v_exp_f32_e32 v229, v229
	v_sub_f32_e32 v230, v230, v190
	v_add_f32_e32 v254, v228, v254
	v_exp_f32_e32 v230, v230
	v_sub_f32_e32 v231, v231, v190
	v_add_f32_e32 v254, v229, v254
	v_exp_f32_e32 v231, v231
	v_sub_f32_e32 v232, v232, v190
	v_add_f32_e32 v254, v230, v254
	v_exp_f32_e32 v232, v232
	v_sub_f32_e32 v233, v233, v190
	v_add_f32_e32 v254, v231, v254
	v_exp_f32_e32 v233, v233
	v_sub_f32_e32 v234, v234, v190
	v_add_f32_e32 v254, v232, v254
	v_exp_f32_e32 v234, v234
	v_sub_f32_e32 v235, v235, v190
	v_add_f32_e32 v254, v233, v254
	v_exp_f32_e32 v235, v235
	v_sub_f32_e32 v236, v236, v190
	v_add_f32_e32 v254, v234, v254
	v_exp_f32_e32 v236, v236
	v_sub_f32_e32 v237, v237, v190
	v_add_f32_e32 v254, v235, v254
	v_exp_f32_e32 v237, v237
	v_add_f32_e32 v254, v236, v254
	v_add_f32_e32 v254, v237, v254
	v_cvt_pk_bf16_f32 v242, v222, v223
	v_cvt_pk_bf16_f32 v243, v224, v225
	v_cvt_pk_bf16_f32 v244, v226, v227
	v_cvt_pk_bf16_f32 v245, v228, v229
	v_cvt_pk_bf16_f32 v250, v230, v231
	v_cvt_pk_bf16_f32 v251, v232, v233
	v_cvt_pk_bf16_f32 v252, v234, v235
	v_cvt_pk_bf16_f32 v253, v236, v237
	v_add_f32_e32 v195, v195, v254
	s_nop 1
	s_waitcnt lgkmcnt(8)
	v_mfma_f32_32x32x16_bf16 v[112:127], v[238:241], v[242:245], v[112:127]
	ds_read_b64_tr_b16 v[238:239], v218 offset:16640
	ds_read_b64_tr_b16 v[240:241], v218 offset:20736
	s_waitcnt lgkmcnt(8)
	v_mfma_f32_32x32x16_bf16 v[96:111], v[128:131], v[242:245], v[96:111]
	ds_read_b64_tr_b16 v[222:223], v219 offset:16640
	ds_read_b64_tr_b16 v[224:225], v219 offset:20736
	s_cmp_lg_u64 s[8:9], 0
	s_cbranch_scc1 .Latt_ndr0_7
	s_sub_i32 s100, s11, 1
	s_cmp_eq_u32 s11, 0
	s_cselect_b32 s100, 2, s100
	s_lshl_b32 s101, s100, 14
	s_add_i32 m0, s36, s101
	s_nop 0
	global_load_lds_dwordx4 v178, s[22:23]
